# hyena x task spectral multiply: the thread's 16 filter-spectrum values fetched together up front instead of ~8 dependent load/wait groups (twice per task)
# speedup vs baseline: 1.0017x; 1.0017x over previous
.LBB0_795:
	s_lshl_b32 s90, s89, 8
	s_lshl_b32 s48, s73, 8
	v_add_u32_e32 v27, s90, v0
	v_add_u32_e32 v26, s48, v1
	v_max_i32_e32 v23, 1, v27
	v_max_i32_e32 v22, 1, v26
	v_lshl_add_u32 v38, v23, 1, s33
	v_lshl_add_u32 v40, v27, 1, s33
	v_cmp_lt_i32_e32 vcc, 0, v27
	v_lshl_add_u32 v39, v22, 1, s33
	ds_read_u16 v22, v38 offset:34814
	ds_read_u16 v23, v39 offset:34814
	v_lshl_add_u32 v41, v26, 1, s33
	ds_read_u16 v24, v40 offset:34816
	ds_read_u16 v25, v41 offset:34816
	v_cmp_gt_i32_e64 s[12:13], s66, v27
	v_min_i32_e32 v27, 0xffe, v27
	v_cmp_lt_i32_e64 s[10:11], 0, v26
	v_cmp_gt_i32_e64 s[14:15], s66, v26
	v_min_i32_e32 v26, 0xffe, v26
	v_lshl_add_u32 v42, v27, 1, s33
	v_lshl_add_u32 v43, v26, 1, s33
	ds_read_u16 v26, v42 offset:34818
	ds_read_u16 v27, v43 offset:34818
	s_waitcnt lgkmcnt(2)
	v_lshlrev_b32_e32 v25, 16, v25
	v_lshlrev_b32_e32 v24, 16, v24
	v_lshlrev_b32_e32 v23, 16, v23
	v_lshlrev_b32_e32 v22, 16, v22
	v_pk_fma_f32 v[24:25], v[2:3], v[24:25], v[10:11]
	v_cndmask_b32_e64 v29, 0, v92, s[10:11]
	v_cndmask_b32_e32 v28, 0, v92, vcc
	s_waitcnt lgkmcnt(0)
	v_lshlrev_b32_e32 v27, 16, v27
	v_lshlrev_b32_e32 v26, 16, v26
	v_pk_fma_f32 v[22:23], v[28:29], v[22:23], v[24:25]
	v_cndmask_b32_e64 v25, 0, v93, s[14:15]
	v_cndmask_b32_e64 v24, 0, v93, s[12:13]
	v_pk_fma_f32 v[22:23], v[24:25], v[26:27], v[22:23]
	ds_read_u16 v26, v38 offset:43006
	ds_read_u16 v27, v39 offset:43006
	ds_read_u16 v30, v40 offset:43008
	ds_read_u16 v31, v41 offset:43008
	ds_read_u16 v32, v42 offset:43010
	ds_read_u16 v33, v43 offset:43010
	v_cndmask_b32_e64 v35, 0, v94, s[10:11]
	s_waitcnt lgkmcnt(5)
	v_lshlrev_b32_e32 v26, 16, v26
	s_waitcnt lgkmcnt(3)
	v_lshlrev_b32_e32 v30, 16, v30
	s_waitcnt lgkmcnt(2)
	v_lshlrev_b32_e32 v31, 16, v31
	v_lshlrev_b32_e32 v27, 16, v27
	v_pk_fma_f32 v[30:31], v[4:5], v[30:31], v[12:13]
	v_cndmask_b32_e32 v34, 0, v94, vcc
	s_waitcnt lgkmcnt(0)
	v_lshlrev_b32_e32 v33, 16, v33
	v_lshlrev_b32_e32 v32, 16, v32
	v_pk_fma_f32 v[26:27], v[34:35], v[26:27], v[30:31]
	v_cndmask_b32_e64 v31, 0, v95, s[14:15]
	v_cndmask_b32_e64 v30, 0, v95, s[12:13]
	v_pk_fma_f32 v[26:27], v[30:31], v[32:33], v[26:27]
	s_mul_i32 s10, s73, 0x880
	v_pk_mul_f32 v[22:23], v[22:23], v[26:27]
	ds_read_u16 v26, v38 offset:51198
	ds_read_u16 v27, v39 offset:51198
	ds_read_u16 v32, v40 offset:51200
	ds_read_u16 v33, v41 offset:51200
	ds_read_u16 v36, v42 offset:51202
	ds_read_u16 v37, v43 offset:51202
	s_mul_i32 s11, s89, 0x880
	s_waitcnt lgkmcnt(5)
	v_lshlrev_b32_e32 v26, 16, v26
	s_waitcnt lgkmcnt(3)
	v_lshlrev_b32_e32 v32, 16, v32
	s_waitcnt lgkmcnt(2)
	v_lshlrev_b32_e32 v33, 16, v33
	v_lshlrev_b32_e32 v27, 16, v27
	v_pk_fma_f32 v[32:33], v[2:3], v[32:33], v[10:11]
	s_waitcnt lgkmcnt(0)
	v_lshlrev_b32_e32 v37, 16, v37
	v_lshlrev_b32_e32 v36, 16, v36
	v_pk_fma_f32 v[26:27], v[28:29], v[26:27], v[32:33]
	s_add_i32 s89, s89, 8
	v_pk_fma_f32 v[24:25], v[24:25], v[36:37], v[26:27]
	ds_read_u16 v26, v38 offset:59390
	ds_read_u16 v27, v39 offset:59390
	ds_read_u16 v28, v40 offset:59392
	ds_read_u16 v29, v41 offset:59392
	ds_read_u16 v32, v42 offset:59394
	ds_read_u16 v33, v43 offset:59394
	v_add_u32_e32 v39, s10, v89
	s_waitcnt lgkmcnt(5)
	v_lshlrev_b32_e32 v26, 16, v26
	s_waitcnt lgkmcnt(3)
	v_lshlrev_b32_e32 v28, 16, v28
	s_waitcnt lgkmcnt(2)
	v_lshlrev_b32_e32 v29, 16, v29
	v_lshlrev_b32_e32 v27, 16, v27
	v_pk_fma_f32 v[28:29], v[4:5], v[28:29], v[12:13]
	s_waitcnt lgkmcnt(0)
	v_lshlrev_b32_e32 v33, 16, v33
	v_lshlrev_b32_e32 v32, 16, v32
	v_pk_fma_f32 v[26:27], v[34:35], v[26:27], v[28:29]
	s_add_i32 s10, s90, 0x200
	v_pk_fma_f32 v[26:27], v[30:31], v[32:33], v[26:27]
	v_add_u32_e32 v38, s11, v89
	v_pk_mul_f32 v[24:25], v[24:25], v[26:27]
	s_add_i32 s11, s48, 0x200
	v_add_u32_e32 v27, s10, v0
	ds_write_b32 v38, v22
	ds_write_b32 v39, v23
	ds_write_b32 v38, v24 offset:4
	ds_write_b32 v39, v25 offset:4
	v_add_u32_e32 v26, s11, v1
	v_max_i32_e32 v23, 1, v27
	v_max_i32_e32 v22, 1, v26
	v_lshl_add_u32 v40, v23, 1, s33
	v_lshl_add_u32 v42, v27, 1, s33
	v_cmp_lt_i32_e32 vcc, 0, v27
	v_lshl_add_u32 v41, v22, 1, s33
	ds_read_u16 v22, v40 offset:34814
	ds_read_u16 v23, v41 offset:34814
	v_lshl_add_u32 v43, v26, 1, s33
	ds_read_u16 v24, v42 offset:34816
	ds_read_u16 v25, v43 offset:34816
	v_cmp_gt_i32_e64 s[12:13], s66, v27
	v_min_i32_e32 v27, 0xffe, v27
	v_cmp_lt_i32_e64 s[10:11], 0, v26
	v_cmp_gt_i32_e64 s[14:15], s66, v26
	v_min_i32_e32 v26, 0xffe, v26
	v_lshl_add_u32 v44, v27, 1, s33
	v_lshl_add_u32 v45, v26, 1, s33
	ds_read_u16 v26, v44 offset:34818
	ds_read_u16 v27, v45 offset:34818
	s_waitcnt lgkmcnt(2)
	v_lshlrev_b32_e32 v25, 16, v25
	v_lshlrev_b32_e32 v24, 16, v24
	v_lshlrev_b32_e32 v23, 16, v23
	v_lshlrev_b32_e32 v22, 16, v22
	v_pk_fma_f32 v[24:25], v[2:3], v[24:25], v[10:11]
	v_cndmask_b32_e64 v29, 0, v92, s[10:11]
	v_cndmask_b32_e32 v28, 0, v92, vcc
	s_waitcnt lgkmcnt(0)
	v_lshlrev_b32_e32 v27, 16, v27
	v_lshlrev_b32_e32 v26, 16, v26
	v_pk_fma_f32 v[22:23], v[28:29], v[22:23], v[24:25]
	v_cndmask_b32_e64 v25, 0, v93, s[14:15]
	v_cndmask_b32_e64 v24, 0, v93, s[12:13]
	v_pk_fma_f32 v[22:23], v[24:25], v[26:27], v[22:23]
	ds_read_u16 v26, v40 offset:43006
	ds_read_u16 v27, v41 offset:43006
	ds_read_u16 v30, v42 offset:43008
	ds_read_u16 v31, v43 offset:43008
	ds_read_u16 v32, v44 offset:43010
	ds_read_u16 v33, v45 offset:43010
	v_cndmask_b32_e64 v35, 0, v94, s[10:11]
	s_waitcnt lgkmcnt(5)
	v_lshlrev_b32_e32 v26, 16, v26
	s_waitcnt lgkmcnt(3)
	v_lshlrev_b32_e32 v30, 16, v30
	s_waitcnt lgkmcnt(2)
	v_lshlrev_b32_e32 v31, 16, v31
	v_lshlrev_b32_e32 v27, 16, v27
	v_pk_fma_f32 v[30:31], v[4:5], v[30:31], v[12:13]
	v_cndmask_b32_e32 v34, 0, v94, vcc
	s_waitcnt lgkmcnt(0)
	v_lshlrev_b32_e32 v33, 16, v33
	v_lshlrev_b32_e32 v32, 16, v32
	v_pk_fma_f32 v[26:27], v[34:35], v[26:27], v[30:31]
	v_cndmask_b32_e64 v31, 0, v95, s[14:15]
	v_cndmask_b32_e64 v30, 0, v95, s[12:13]
	v_pk_fma_f32 v[26:27], v[30:31], v[32:33], v[26:27]
	s_add_i32 s10, s90, 0x400
	v_pk_mul_f32 v[22:23], v[22:23], v[26:27]
	ds_read_u16 v26, v40 offset:51198
	ds_read_u16 v27, v41 offset:51198
	ds_read_u16 v32, v42 offset:51200
	ds_read_u16 v33, v43 offset:51200
	ds_read_u16 v36, v44 offset:51202
	ds_read_u16 v37, v45 offset:51202
	s_add_i32 s11, s48, 0x400
	s_waitcnt lgkmcnt(5)
	v_lshlrev_b32_e32 v26, 16, v26
	s_waitcnt lgkmcnt(3)
	v_lshlrev_b32_e32 v32, 16, v32
	s_waitcnt lgkmcnt(2)
	v_lshlrev_b32_e32 v33, 16, v33
	v_lshlrev_b32_e32 v27, 16, v27
	v_pk_fma_f32 v[32:33], v[2:3], v[32:33], v[10:11]
	s_waitcnt lgkmcnt(0)
	v_lshlrev_b32_e32 v37, 16, v37
	v_lshlrev_b32_e32 v36, 16, v36
	v_pk_fma_f32 v[26:27], v[28:29], v[26:27], v[32:33]
	s_addk_i32 s90, 0x600
	v_pk_fma_f32 v[24:25], v[24:25], v[36:37], v[26:27]
	ds_read_u16 v26, v40 offset:59390
	ds_read_u16 v27, v41 offset:59390
	ds_read_u16 v28, v42 offset:59392
	ds_read_u16 v29, v43 offset:59392
	ds_read_u16 v32, v44 offset:59394
	ds_read_u16 v33, v45 offset:59394
	s_addk_i32 s48, 0x600
	s_waitcnt lgkmcnt(5)
	v_lshlrev_b32_e32 v26, 16, v26
	s_waitcnt lgkmcnt(3)
	v_lshlrev_b32_e32 v28, 16, v28
	s_waitcnt lgkmcnt(2)
	v_lshlrev_b32_e32 v29, 16, v29
	v_lshlrev_b32_e32 v27, 16, v27
	v_pk_fma_f32 v[28:29], v[4:5], v[28:29], v[12:13]
	s_waitcnt lgkmcnt(0)
	v_lshlrev_b32_e32 v33, 16, v33
	v_lshlrev_b32_e32 v32, 16, v32
	v_pk_fma_f32 v[26:27], v[34:35], v[26:27], v[28:29]
	s_add_i32 s73, s73, 8
	v_pk_fma_f32 v[26:27], v[30:31], v[32:33], v[26:27]
	s_add_i32 s75, s75, -8
	v_pk_mul_f32 v[24:25], v[24:25], v[26:27]
	v_add_u32_e32 v27, s10, v0
	ds_write_b32 v38, v22 offset:4352
	ds_write_b32 v39, v23 offset:4352
	ds_write_b32 v38, v24 offset:4356
	ds_write_b32 v39, v25 offset:4356
	v_add_u32_e32 v26, s11, v1
	v_max_i32_e32 v23, 1, v27
	v_max_i32_e32 v22, 1, v26
	v_lshl_add_u32 v40, v23, 1, s33
	v_lshl_add_u32 v42, v27, 1, s33
	v_cmp_lt_i32_e32 vcc, 0, v27
	v_lshl_add_u32 v41, v22, 1, s33
	ds_read_u16 v22, v40 offset:34814
	ds_read_u16 v23, v41 offset:34814
	v_lshl_add_u32 v43, v26, 1, s33
	ds_read_u16 v24, v42 offset:34816
	ds_read_u16 v25, v43 offset:34816
	v_cmp_gt_i32_e64 s[12:13], s66, v27
	v_min_i32_e32 v27, 0xffe, v27
	v_cmp_lt_i32_e64 s[10:11], 0, v26
	v_cmp_gt_i32_e64 s[14:15], s66, v26
	v_min_i32_e32 v26, 0xffe, v26
	v_lshl_add_u32 v44, v27, 1, s33
	v_lshl_add_u32 v45, v26, 1, s33
	ds_read_u16 v26, v44 offset:34818
	ds_read_u16 v27, v45 offset:34818
	s_waitcnt lgkmcnt(2)
	v_lshlrev_b32_e32 v25, 16, v25
	v_lshlrev_b32_e32 v24, 16, v24
	v_lshlrev_b32_e32 v23, 16, v23
	v_lshlrev_b32_e32 v22, 16, v22
	v_pk_fma_f32 v[24:25], v[2:3], v[24:25], v[10:11]
	v_cndmask_b32_e64 v29, 0, v92, s[10:11]
	v_cndmask_b32_e32 v28, 0, v92, vcc
	s_waitcnt lgkmcnt(0)
	v_lshlrev_b32_e32 v27, 16, v27
	v_lshlrev_b32_e32 v26, 16, v26
	v_pk_fma_f32 v[22:23], v[28:29], v[22:23], v[24:25]
	v_cndmask_b32_e64 v25, 0, v93, s[14:15]
	v_cndmask_b32_e64 v24, 0, v93, s[12:13]
	v_pk_fma_f32 v[22:23], v[24:25], v[26:27], v[22:23]
	ds_read_u16 v26, v40 offset:43006
	ds_read_u16 v27, v41 offset:43006
	ds_read_u16 v30, v42 offset:43008
	ds_read_u16 v31, v43 offset:43008
	ds_read_u16 v32, v44 offset:43010
	ds_read_u16 v33, v45 offset:43010
	v_cndmask_b32_e64 v35, 0, v94, s[10:11]
	s_waitcnt lgkmcnt(5)
	v_lshlrev_b32_e32 v26, 16, v26
	s_waitcnt lgkmcnt(3)
	v_lshlrev_b32_e32 v30, 16, v30
	s_waitcnt lgkmcnt(2)
	v_lshlrev_b32_e32 v31, 16, v31
	v_lshlrev_b32_e32 v27, 16, v27
	v_pk_fma_f32 v[30:31], v[4:5], v[30:31], v[12:13]
	v_cndmask_b32_e32 v34, 0, v94, vcc
	s_waitcnt lgkmcnt(0)
	v_lshlrev_b32_e32 v33, 16, v33
	v_lshlrev_b32_e32 v32, 16, v32
	v_pk_fma_f32 v[26:27], v[34:35], v[26:27], v[30:31]
	v_cndmask_b32_e64 v31, 0, v95, s[14:15]
	v_cndmask_b32_e64 v30, 0, v95, s[12:13]
	v_pk_fma_f32 v[26:27], v[30:31], v[32:33], v[26:27]
	s_cmp_lg_u32 s75, 0
	v_pk_mul_f32 v[22:23], v[22:23], v[26:27]
	ds_read_u16 v26, v40 offset:51198
	ds_read_u16 v27, v41 offset:51198
	ds_read_u16 v32, v42 offset:51200
	ds_read_u16 v33, v43 offset:51200
	ds_read_u16 v36, v44 offset:51202
	ds_read_u16 v37, v45 offset:51202
	s_waitcnt lgkmcnt(5)
	v_lshlrev_b32_e32 v26, 16, v26
	s_waitcnt lgkmcnt(3)
	v_lshlrev_b32_e32 v32, 16, v32
	s_waitcnt lgkmcnt(2)
	v_lshlrev_b32_e32 v33, 16, v33
	v_lshlrev_b32_e32 v27, 16, v27
	v_pk_fma_f32 v[32:33], v[2:3], v[32:33], v[10:11]
	s_waitcnt lgkmcnt(0)
	v_lshlrev_b32_e32 v37, 16, v37
	v_lshlrev_b32_e32 v36, 16, v36
	v_pk_fma_f32 v[26:27], v[28:29], v[26:27], v[32:33]
	s_nop 0
	v_pk_fma_f32 v[24:25], v[24:25], v[36:37], v[26:27]
	ds_read_u16 v26, v40 offset:59390
	ds_read_u16 v27, v41 offset:59390
	ds_read_u16 v28, v42 offset:59392
	ds_read_u16 v29, v43 offset:59392
	ds_read_u16 v32, v44 offset:59394
	ds_read_u16 v33, v45 offset:59394
	s_waitcnt lgkmcnt(5)
	v_lshlrev_b32_e32 v26, 16, v26
	s_waitcnt lgkmcnt(3)
	v_lshlrev_b32_e32 v28, 16, v28
	s_waitcnt lgkmcnt(2)
	v_lshlrev_b32_e32 v29, 16, v29
	v_lshlrev_b32_e32 v27, 16, v27
	v_pk_fma_f32 v[28:29], v[4:5], v[28:29], v[12:13]
	s_waitcnt lgkmcnt(0)
	v_lshlrev_b32_e32 v33, 16, v33
	v_lshlrev_b32_e32 v32, 16, v32
	v_pk_fma_f32 v[26:27], v[34:35], v[26:27], v[28:29]
	s_nop 0
	v_pk_fma_f32 v[26:27], v[30:31], v[32:33], v[26:27]
	s_nop 0
	v_pk_mul_f32 v[24:25], v[24:25], v[26:27]
	v_add_u32_e32 v27, s90, v0
	ds_write_b32 v38, v22 offset:8704
	ds_write_b32 v39, v23 offset:8704
	ds_write_b32 v38, v24 offset:8708
	ds_write_b32 v39, v25 offset:8708
	v_add_u32_e32 v26, s48, v1
	v_max_i32_e32 v23, 1, v27
	v_max_i32_e32 v22, 1, v26
	v_lshl_add_u32 v40, v23, 1, s33
	v_lshl_add_u32 v42, v27, 1, s33
	v_cmp_lt_i32_e32 vcc, 0, v27
	v_lshl_add_u32 v41, v22, 1, s33
	ds_read_u16 v22, v40 offset:34814
	ds_read_u16 v23, v41 offset:34814
	v_lshl_add_u32 v43, v26, 1, s33
	ds_read_u16 v24, v42 offset:34816
	ds_read_u16 v25, v43 offset:34816
	v_cmp_gt_i32_e64 s[12:13], s66, v27
	v_min_i32_e32 v27, 0xffe, v27
	v_cmp_lt_i32_e64 s[10:11], 0, v26
	v_cmp_gt_i32_e64 s[14:15], s66, v26
	v_min_i32_e32 v26, 0xffe, v26
	v_lshl_add_u32 v44, v27, 1, s33
	v_lshl_add_u32 v45, v26, 1, s33
	ds_read_u16 v26, v44 offset:34818
	ds_read_u16 v27, v45 offset:34818
	s_waitcnt lgkmcnt(2)
	v_lshlrev_b32_e32 v25, 16, v25
	v_lshlrev_b32_e32 v24, 16, v24
	v_lshlrev_b32_e32 v23, 16, v23
	v_lshlrev_b32_e32 v22, 16, v22
	v_pk_fma_f32 v[24:25], v[2:3], v[24:25], v[10:11]
	v_cndmask_b32_e64 v29, 0, v92, s[10:11]
	v_cndmask_b32_e32 v28, 0, v92, vcc
	s_waitcnt lgkmcnt(0)
	v_lshlrev_b32_e32 v27, 16, v27
	v_lshlrev_b32_e32 v26, 16, v26
	v_pk_fma_f32 v[22:23], v[28:29], v[22:23], v[24:25]
	v_cndmask_b32_e64 v25, 0, v93, s[14:15]
	v_cndmask_b32_e64 v24, 0, v93, s[12:13]
	v_pk_fma_f32 v[22:23], v[24:25], v[26:27], v[22:23]
	ds_read_u16 v26, v40 offset:43006
	ds_read_u16 v27, v41 offset:43006
	ds_read_u16 v30, v42 offset:43008
	ds_read_u16 v31, v43 offset:43008
	ds_read_u16 v32, v44 offset:43010
	ds_read_u16 v33, v45 offset:43010
	v_cndmask_b32_e64 v35, 0, v94, s[10:11]
	s_waitcnt lgkmcnt(5)
	v_lshlrev_b32_e32 v26, 16, v26
	s_waitcnt lgkmcnt(3)
	v_lshlrev_b32_e32 v30, 16, v30
	s_waitcnt lgkmcnt(2)
	v_lshlrev_b32_e32 v31, 16, v31
	v_lshlrev_b32_e32 v27, 16, v27
	v_pk_fma_f32 v[30:31], v[4:5], v[30:31], v[12:13]
	v_cndmask_b32_e32 v34, 0, v94, vcc
	s_waitcnt lgkmcnt(0)
	v_lshlrev_b32_e32 v33, 16, v33
	v_lshlrev_b32_e32 v32, 16, v32
	v_pk_fma_f32 v[26:27], v[34:35], v[26:27], v[30:31]
	v_cndmask_b32_e64 v31, 0, v95, s[14:15]
	v_cndmask_b32_e64 v30, 0, v95, s[12:13]
	v_pk_fma_f32 v[26:27], v[30:31], v[32:33], v[26:27]
	s_nop 0
	v_pk_mul_f32 v[22:23], v[22:23], v[26:27]
	ds_read_u16 v26, v40 offset:51198
	ds_read_u16 v27, v41 offset:51198
	ds_read_u16 v32, v42 offset:51200
	ds_read_u16 v33, v43 offset:51200
	ds_read_u16 v36, v44 offset:51202
	ds_read_u16 v37, v45 offset:51202
	s_waitcnt lgkmcnt(5)
	v_lshlrev_b32_e32 v26, 16, v26
	s_waitcnt lgkmcnt(3)
	v_lshlrev_b32_e32 v32, 16, v32
	s_waitcnt lgkmcnt(2)
	v_lshlrev_b32_e32 v33, 16, v33
	v_lshlrev_b32_e32 v27, 16, v27
	v_pk_fma_f32 v[32:33], v[2:3], v[32:33], v[10:11]
	s_waitcnt lgkmcnt(0)
	v_lshlrev_b32_e32 v37, 16, v37
	v_lshlrev_b32_e32 v36, 16, v36
	v_pk_fma_f32 v[26:27], v[28:29], v[26:27], v[32:33]
	s_nop 0
	v_pk_fma_f32 v[24:25], v[24:25], v[36:37], v[26:27]
	ds_read_u16 v26, v40 offset:59390
	ds_read_u16 v27, v41 offset:59390
	ds_read_u16 v28, v42 offset:59392
	ds_read_u16 v29, v43 offset:59392
	ds_read_u16 v32, v44 offset:59394
	ds_read_u16 v33, v45 offset:59394
	s_waitcnt lgkmcnt(5)
	v_lshlrev_b32_e32 v26, 16, v26
	s_waitcnt lgkmcnt(3)
	v_lshlrev_b32_e32 v28, 16, v28
	s_waitcnt lgkmcnt(2)
	v_lshlrev_b32_e32 v29, 16, v29
	v_lshlrev_b32_e32 v27, 16, v27
	v_pk_fma_f32 v[28:29], v[4:5], v[28:29], v[12:13]
	s_waitcnt lgkmcnt(0)
	v_lshlrev_b32_e32 v33, 16, v33
	v_lshlrev_b32_e32 v32, 16, v32
	v_pk_fma_f32 v[26:27], v[34:35], v[26:27], v[28:29]
	s_nop 0
	v_pk_fma_f32 v[26:27], v[30:31], v[32:33], v[26:27]
	s_nop 0
	v_pk_mul_f32 v[24:25], v[24:25], v[26:27]
	ds_write_b32 v38, v22 offset:13056
	ds_write_b32 v39, v23 offset:13056
	ds_write_b32 v38, v24 offset:13060
	ds_write_b32 v39, v25 offset:13060
	s_cbranch_scc1 .LBB0_795
	ds_read_b64 v[50:51], v89
	ds_read_b64 v[48:49], v89 offset:2176
	ds_read_b64 v[46:47], v89 offset:4352
	ds_read_b64 v[44:45], v89 offset:6528
	ds_read_b64 v[40:41], v89 offset:8704
	ds_read_b64 v[38:39], v89 offset:10880
	ds_read_b64 v[36:37], v89 offset:13056
	ds_read_b64 v[30:31], v89 offset:15232
	ds_read_b64 v[28:29], v89 offset:17408
	ds_read_b64 v[32:33], v89 offset:19584
	ds_read_b64 v[26:27], v89 offset:21760
	ds_read_b64 v[22:23], v89 offset:23936
	ds_read_b64 v[24:25], v89 offset:26112
	s_waitcnt lgkmcnt(4)
	v_pk_add_f32 v[34:35], v[50:51], v[28:29]
	v_pk_add_f32 v[42:43], v[50:51], v[28:29] neg_lo:[0,1] neg_hi:[0,1]
	s_waitcnt lgkmcnt(3)
	v_pk_add_f32 v[52:53], v[48:49], v[32:33]
	v_pk_add_f32 v[60:61], v[48:49], v[32:33] neg_lo:[0,1] neg_hi:[0,1]
	s_waitcnt lgkmcnt(0)
	v_pk_add_f32 v[58:59], v[40:41], v[24:25]
	v_pk_add_f32 v[66:67], v[40:41], v[24:25] neg_lo:[0,1] neg_hi:[0,1]
	v_pk_add_f32 v[68:69], v[34:35], v[58:59]
	v_pk_add_f32 v[70:71], v[34:35], v[58:59] neg_lo:[0,1] neg_hi:[0,1]
	ds_read_b64 v[34:35], v89 offset:28288
	v_add_f32_e32 v72, v42, v67
	v_sub_f32_e32 v73, v43, v66
	v_sub_f32_e32 v74, v42, v67
	v_add_f32_e32 v75, v43, v66
	s_waitcnt lgkmcnt(0)
	v_pk_add_f32 v[42:43], v[38:39], v[34:35]
	v_pk_add_f32 v[66:67], v[38:39], v[34:35] neg_lo:[0,1] neg_hi:[0,1]
	v_pk_add_f32 v[58:59], v[52:53], v[42:43]
	v_pk_add_f32 v[42:43], v[52:53], v[42:43] neg_lo:[0,1] neg_hi:[0,1]
	v_add_f32_e32 v52, v60, v67
	v_mul_f32_e32 v42, 0x3f3504f3, v42
	v_fmamk_f32 v99, v43, 0x3f3504f3, v42
	v_fma_f32 v100, v43, s72, -v42
	ds_read_b64 v[42:43], v89 offset:30464
	v_sub_f32_e32 v60, v60, v67
	v_sub_f32_e32 v53, v61, v66
	v_add_f32_e32 v61, v61, v66
	v_mul_f32_e32 v76, 0x3f6c835e, v52
	v_mul_f32_e32 v77, 0xbec3ef15, v52
	v_mul_f32_e32 v101, 0x3ec3ef15, v60
	v_mul_f32_e32 v102, 0xbf6c835e, v60
	v_pk_add_f32 v[62:63], v[46:47], v[26:27]
	v_pk_add_f32 v[64:65], v[46:47], v[26:27] neg_lo:[0,1] neg_hi:[0,1]
	v_fmac_f32_e32 v76, 0x3ec3ef15, v53
	v_fmac_f32_e32 v77, 0x3f6c835e, v53
	v_fmac_f32_e32 v101, 0x3f6c835e, v61
	v_fmac_f32_e32 v102, 0x3ec3ef15, v61
	s_waitcnt lgkmcnt(0)
	v_pk_add_f32 v[52:53], v[36:37], v[42:43]
	v_pk_add_f32 v[60:61], v[36:37], v[42:43] neg_lo:[0,1] neg_hi:[0,1]
	v_pk_add_f32 v[66:67], v[62:63], v[52:53]
	v_pk_add_f32 v[52:53], v[62:63], v[52:53] neg_lo:[0,1] neg_hi:[0,1]
	v_add_f32_e32 v62, v64, v61
	v_sub_f32_e32 v61, v64, v61
	v_sub_f32_e32 v63, v65, v60
	v_add_f32_e32 v60, v65, v60
	v_fma_f32 v103, v53, 0, -v52
	v_fmac_f32_e32 v53, 0, v52
	v_mul_f32_e32 v52, 0xbf3504f3, v61
	v_fmamk_f32 v104, v60, 0x3f3504f3, v52
	v_fmac_f32_e32 v52, 0xbf3504f3, v60
	v_add_f32_e32 v107, v70, v53
	v_sub_f32_e32 v70, v70, v53
	v_add_f32_e32 v109, v75, v52
	v_sub_f32_e32 v75, v75, v52
	ds_read_b64 v[52:53], v89 offset:32640
	v_mul_f32_e32 v62, 0x3f3504f3, v62
	v_fmamk_f32 v64, v63, 0x3f3504f3, v62
	v_fma_f32 v65, v63, s72, -v62
	v_pk_add_f32 v[56:57], v[44:45], v[22:23]
	v_pk_add_f32 v[54:55], v[44:45], v[22:23] neg_lo:[0,1] neg_hi:[0,1]
	v_pk_add_f32 v[62:63], v[68:69], v[66:67]
	v_pk_add_f32 v[60:61], v[68:69], v[66:67] neg_lo:[0,1] neg_hi:[0,1]
	v_add_f32_e32 v105, v72, v64
	v_add_f32_e32 v106, v73, v65
	v_sub_f32_e32 v72, v72, v64
	v_sub_f32_e32 v73, v73, v65
	s_waitcnt lgkmcnt(0)
	v_pk_add_f32 v[64:65], v[30:31], v[52:53]
	v_pk_add_f32 v[66:67], v[30:31], v[52:53] neg_lo:[0,1] neg_hi:[0,1]
	v_pk_add_f32 v[68:69], v[56:57], v[64:65]
	v_pk_add_f32 v[56:57], v[56:57], v[64:65] neg_lo:[0,1] neg_hi:[0,1]
	v_add_f32_e32 v64, v54, v67
	v_sub_f32_e32 v54, v54, v67
	v_add_f32_e32 v108, v71, v103
	v_sub_f32_e32 v71, v71, v103
	v_add_f32_e32 v103, v74, v104
	v_sub_f32_e32 v74, v74, v104
	v_sub_f32_e32 v65, v55, v66
	v_add_f32_e32 v55, v55, v66
	v_mul_f32_e32 v66, 0x3ec3ef15, v64
	v_mul_f32_e32 v64, 0xbf6c835e, v64
	v_mul_f32_e32 v104, 0xbf6c835e, v54
	v_fmac_f32_e32 v66, 0x3f6c835e, v65
	v_fmac_f32_e32 v64, 0x3ec3ef15, v65
	v_mul_f32_e32 v65, 0xbf3504f3, v56
	v_fmac_f32_e32 v104, 0xbec3ef15, v55
	v_mul_f32_e32 v55, 0xbf6c835e, v55
	v_fmamk_f32 v67, v57, 0x3f3504f3, v65
	v_fmac_f32_e32 v65, 0xbf3504f3, v57
	v_fmac_f32_e32 v55, 0x3ec3ef15, v54
	v_pk_add_f32 v[56:57], v[58:59], v[68:69]
	v_pk_add_f32 v[58:59], v[58:59], v[68:69] neg_lo:[0,1] neg_hi:[0,1]
	v_add_f32_e32 v68, v76, v66
	v_add_f32_e32 v69, v77, v64
	v_sub_f32_e32 v66, v76, v66
	v_sub_f32_e32 v76, v77, v64
	v_add_f32_e32 v77, v99, v67
	v_add_f32_e32 v110, v100, v65
	v_sub_f32_e32 v67, v99, v67
	v_sub_f32_e32 v99, v100, v65
	v_add_f32_e32 v100, v101, v104
	v_add_f32_e32 v111, v102, v55
	v_sub_f32_e32 v101, v101, v104
	v_sub_f32_e32 v102, v102, v55
	v_mov_b32_e32 v104, v82
	v_mov_b32_e32 v112, v83
	v_mov_b32_e32 v54, v78
	v_mov_b32_e32 v55, v79
	s_barrier
	v_pk_add_f32 v[64:65], v[62:63], v[56:57]
	v_pk_add_f32 v[56:57], v[62:63], v[56:57] neg_lo:[0,1] neg_hi:[0,1]
	v_add_f32_e32 v62, v60, v59
	v_sub_f32_e32 v63, v61, v58
	v_sub_f32_e32 v60, v60, v59
	v_add_f32_e32 v61, v61, v58
	v_add_f32_e32 v113, v105, v68
	v_add_f32_e32 v114, v106, v69
	v_sub_f32_e32 v68, v105, v68
	v_sub_f32_e32 v69, v106, v69
	v_add_f32_e32 v105, v72, v76
	v_sub_f32_e32 v106, v73, v66
	v_sub_f32_e32 v72, v72, v76
	v_add_f32_e32 v66, v73, v66
	v_add_f32_e32 v73, v107, v77
	v_add_f32_e32 v76, v108, v110
	v_sub_f32_e32 v77, v107, v77
	v_sub_f32_e32 v107, v108, v110
	v_add_f32_e32 v108, v70, v99
	v_sub_f32_e32 v110, v71, v67
	v_sub_f32_e32 v70, v70, v99
	v_add_f32_e32 v67, v71, v67
	v_add_f32_e32 v71, v103, v100
	v_add_f32_e32 v99, v109, v111
	v_sub_f32_e32 v100, v103, v100
	v_sub_f32_e32 v103, v109, v111
	v_add_f32_e32 v109, v74, v102
	v_sub_f32_e32 v111, v75, v101
	v_sub_f32_e32 v74, v74, v102
	v_add_f32_e32 v75, v75, v101
	v_fmamk_f32 v58, v65, 0x80000000, v64
	v_fmac_f32_e32 v65, 0, v64
	v_mov_b32_e32 v59, v65
	v_fmamk_f32 v64, v112, 0x80000000, v104
	v_fma_f32 v65, 0, v104, v112
	ds_write_b64 v89, v[58:59]
	v_mul_f32_e32 v58, v65, v114
	v_mul_f32_e32 v59, v114, v64
	v_fma_f32 v58, v113, v64, -v58
	v_fmac_f32_e32 v59, v65, v113
	ds_write_b64 v89, v[58:59] offset:2176
	v_mul_f32_e32 v58, v112, v65
	v_fma_f32 v101, v104, v64, -v58
	v_mul_f32_e32 v64, v112, v64
	v_fmac_f32_e32 v64, v104, v65
	v_mul_f32_e32 v58, v76, v64
	v_mul_f32_e32 v59, v73, v64
	v_fma_f32 v58, v73, v101, -v58
	v_fmac_f32_e32 v59, v76, v101
	v_mul_f32_e32 v73, v112, v101
	ds_write_b64 v89, v[58:59] offset:4352
	v_mul_f32_e32 v58, v112, v64
	v_fmac_f32_e32 v73, v104, v64
	v_fma_f32 v65, v104, v101, -v58
	v_mul_f32_e32 v58, v99, v73
	v_mul_f32_e32 v59, v71, v73
	v_fma_f32 v58, v71, v65, -v58
	v_fmac_f32_e32 v59, v99, v65
	ds_write_b64 v89, v[58:59] offset:6528
	v_mul_f32_e32 v58, v112, v73
	v_fma_f32 v64, v104, v65, -v58
	v_mul_f32_e32 v65, v112, v65
	v_fmac_f32_e32 v65, v104, v73
	v_mul_f32_e32 v58, v63, v65
	v_mul_f32_e32 v59, v63, v64
	v_fma_f32 v58, v62, v64, -v58
	v_fmac_f32_e32 v59, v62, v65
	v_mul_f32_e32 v63, v112, v64
	ds_write_b64 v89, v[58:59] offset:8704
	v_mul_f32_e32 v58, v112, v65
	v_fmac_f32_e32 v63, v104, v65
	v_fma_f32 v62, v104, v64, -v58
	v_mul_f32_e32 v58, v106, v63
	v_mul_f32_e32 v59, v105, v63
	v_fma_f32 v58, v105, v62, -v58
	v_fmac_f32_e32 v59, v106, v62
	ds_write_b64 v89, v[58:59] offset:10880
	v_mul_f32_e32 v58, v112, v63
	v_fma_f32 v64, v104, v62, -v58
	v_mul_f32_e32 v62, v112, v62
	v_fmac_f32_e32 v62, v104, v63
	v_mul_f32_e32 v58, v110, v62
	v_mul_f32_e32 v59, v108, v62
	v_fma_f32 v58, v108, v64, -v58
	v_fmac_f32_e32 v59, v110, v64
	ds_write_b64 v89, v[58:59] offset:13056
	v_mul_f32_e32 v58, v112, v62
	v_fma_f32 v63, v104, v64, -v58
	v_mul_f32_e32 v64, v112, v64
	v_fmac_f32_e32 v64, v104, v62
	v_mul_f32_e32 v58, v111, v64
	v_mul_f32_e32 v59, v109, v64
	v_fma_f32 v58, v109, v63, -v58
	v_fmac_f32_e32 v59, v111, v63
	ds_write_b64 v89, v[58:59] offset:15232
	v_mul_f32_e32 v58, v112, v64
	v_fma_f32 v62, v104, v63, -v58
	v_mul_f32_e32 v63, v112, v63
	v_fmac_f32_e32 v63, v104, v64
	v_mul_f32_e32 v58, v57, v63
	v_mul_f32_e32 v59, v57, v62
	v_fma_f32 v58, v56, v62, -v58
	v_fmac_f32_e32 v59, v56, v63
	ds_write_b64 v89, v[58:59] offset:17408
	v_mul_f32_e32 v59, v112, v62
	v_mul_f32_e32 v56, v112, v63
	v_fmac_f32_e32 v59, v104, v63
	v_fma_f32 v58, v104, v62, -v56
	v_mul_f32_e32 v56, v69, v59
	v_mul_f32_e32 v57, v68, v59
	v_fma_f32 v56, v68, v58, -v56
	v_fmac_f32_e32 v57, v69, v58
	ds_write_b64 v89, v[56:57] offset:19584
	v_mul_f32_e32 v56, v112, v59
	v_fma_f32 v62, v104, v58, -v56
	v_mul_f32_e32 v58, v112, v58
	v_fmac_f32_e32 v58, v104, v59
	v_mul_f32_e32 v56, v107, v58
	v_mul_f32_e32 v57, v77, v58
	v_fma_f32 v56, v77, v62, -v56
	v_fmac_f32_e32 v57, v107, v62
	ds_write_b64 v89, v[56:57] offset:21760
	v_mul_f32_e32 v56, v112, v58
	v_fma_f32 v59, v104, v62, -v56
	v_mul_f32_e32 v62, v112, v62
	v_fmac_f32_e32 v62, v104, v58
	v_mul_f32_e32 v56, v103, v62
	v_mul_f32_e32 v57, v100, v62
	v_fma_f32 v56, v100, v59, -v56
	v_fmac_f32_e32 v57, v103, v59
	ds_write_b64 v89, v[56:57] offset:23936
	v_mul_f32_e32 v56, v112, v62
	v_fma_f32 v58, v104, v59, -v56
	v_mul_f32_e32 v59, v112, v59
	v_fmac_f32_e32 v59, v104, v62
	v_mul_f32_e32 v56, v61, v59
	v_mul_f32_e32 v57, v61, v58
	v_fma_f32 v56, v60, v58, -v56
	v_fmac_f32_e32 v57, v60, v59
	ds_write_b64 v89, v[56:57] offset:26112
	v_mul_f32_e32 v56, v112, v59
	v_fma_f32 v60, v104, v58, -v56
	v_mul_f32_e32 v58, v112, v58
	v_fmac_f32_e32 v58, v104, v59
	v_mul_f32_e32 v56, v66, v58
	v_mul_f32_e32 v57, v72, v58
	v_fma_f32 v56, v72, v60, -v56
	v_fmac_f32_e32 v57, v66, v60
	ds_write_b64 v89, v[56:57] offset:28288
	v_mul_f32_e32 v56, v112, v58
	v_fma_f32 v59, v104, v60, -v56
	v_mul_f32_e32 v60, v112, v60
	v_fmac_f32_e32 v60, v104, v58
	v_mul_f32_e32 v56, v67, v60
	v_mul_f32_e32 v57, v70, v60
	v_fma_f32 v56, v70, v59, -v56
	v_fmac_f32_e32 v57, v67, v59
	ds_write_b64 v89, v[56:57] offset:30464
	v_mul_f32_e32 v57, v112, v59
	v_mul_f32_e32 v56, v112, v60
	v_fmac_f32_e32 v57, v104, v60
	v_fma_f32 v58, v104, v59, -v56
	v_mul_f32_e32 v56, v75, v57
	v_mul_f32_e32 v57, v74, v57
	v_fma_f32 v56, v74, v58, -v56
	v_fmac_f32_e32 v57, v75, v58
	ds_write_b64 v89, v[56:57] offset:32640
	s_waitcnt lgkmcnt(0)
	s_barrier
	ds_read2_b64 v[56:59], v90 offset1:17
	ds_read2_b64 v[60:63], v90 offset0:34 offset1:51
	ds_read2_b64 v[64:67], v90 offset0:68 offset1:85
	ds_read2_b64 v[68:71], v90 offset0:102 offset1:119
	ds_read2_b64 v[72:75], v90 offset0:136 offset1:153
	ds_read2_b64 v[100:103], v90 offset0:170 offset1:187
	ds_read2_b64 v[104:107], v90 offset0:204 offset1:221
	ds_read2_b64 v[108:111], v90 offset0:238 offset1:255
	s_waitcnt lgkmcnt(3)
	v_add_f32_e32 v76, v56, v72
	v_add_f32_e32 v77, v57, v73
	v_sub_f32_e32 v56, v56, v72
	v_sub_f32_e32 v57, v57, v73
	s_waitcnt lgkmcnt(1)
	v_add_f32_e32 v72, v64, v104
	v_add_f32_e32 v73, v65, v105
	v_sub_f32_e32 v64, v64, v104
	v_sub_f32_e32 v65, v65, v105
	v_add_f32_e32 v99, v76, v72
	v_add_f32_e32 v104, v77, v73
	v_sub_f32_e32 v72, v76, v72
	v_sub_f32_e32 v73, v77, v73
	v_add_f32_e32 v76, v56, v65
	v_sub_f32_e32 v77, v57, v64
	v_sub_f32_e32 v56, v56, v65
	v_add_f32_e32 v64, v57, v64
	v_add_f32_e32 v57, v58, v74
	v_add_f32_e32 v65, v59, v75
	v_sub_f32_e32 v58, v58, v74
	v_sub_f32_e32 v59, v59, v75
	v_add_f32_e32 v74, v66, v106
	v_add_f32_e32 v75, v67, v107
	v_sub_f32_e32 v66, v66, v106
	v_sub_f32_e32 v67, v67, v107
	v_add_f32_e32 v105, v57, v74
	v_add_f32_e32 v106, v65, v75
	v_sub_f32_e32 v57, v57, v74
	v_sub_f32_e32 v65, v65, v75
	v_add_f32_e32 v74, v58, v67
	v_sub_f32_e32 v75, v59, v66
	v_sub_f32_e32 v58, v58, v67
	v_add_f32_e32 v59, v59, v66
	v_add_f32_e32 v66, v60, v100
	v_add_f32_e32 v67, v61, v101
	v_sub_f32_e32 v60, v60, v100
	v_sub_f32_e32 v61, v61, v101
	s_waitcnt lgkmcnt(0)
	v_add_f32_e32 v100, v68, v108
	v_add_f32_e32 v101, v69, v109
	v_sub_f32_e32 v68, v68, v108
	v_sub_f32_e32 v69, v69, v109
	v_add_f32_e32 v107, v66, v100
	v_add_f32_e32 v108, v67, v101
	v_sub_f32_e32 v66, v66, v100
	v_sub_f32_e32 v67, v67, v101
	v_add_f32_e32 v100, v60, v69
	v_sub_f32_e32 v101, v61, v68
	v_sub_f32_e32 v60, v60, v69
	v_add_f32_e32 v61, v61, v68
	v_add_f32_e32 v68, v62, v102
	v_add_f32_e32 v69, v63, v103
	v_sub_f32_e32 v62, v62, v102
	v_sub_f32_e32 v63, v63, v103
	v_add_f32_e32 v102, v70, v110
	v_add_f32_e32 v103, v71, v111
	v_sub_f32_e32 v70, v70, v110
	v_sub_f32_e32 v71, v71, v111
	v_add_f32_e32 v109, v68, v102
	v_add_f32_e32 v110, v69, v103
	v_sub_f32_e32 v68, v68, v102
	v_sub_f32_e32 v69, v69, v103
	v_add_f32_e32 v102, v62, v71
	v_sub_f32_e32 v103, v63, v70
	v_sub_f32_e32 v62, v62, v71
	v_add_f32_e32 v63, v63, v70
	v_mul_f32_e32 v70, 0x3f6c835e, v74
	v_mul_f32_e32 v71, 0xbec3ef15, v74
	v_mul_f32_e32 v74, 0x3f3504f3, v100
	v_fmac_f32_e32 v70, 0x3ec3ef15, v75
	v_fmac_f32_e32 v71, 0x3f6c835e, v75
	v_fmamk_f32 v75, v101, 0x3f3504f3, v74
	v_fma_f32 v74, v101, s72, -v74
	v_mul_f32_e32 v100, 0x3ec3ef15, v102
	v_mul_f32_e32 v101, 0xbf6c835e, v102
	v_fmac_f32_e32 v100, 0x3f6c835e, v103
	v_fmac_f32_e32 v101, 0x3ec3ef15, v103
	v_fma_f32 v103, 0, v66, v67
	v_fma_f32 v66, v67, 0, -v66
	v_mul_f32_e32 v67, 0xbf3504f3, v68
	v_fmamk_f32 v68, v69, 0x3f3504f3, v67
	v_fmac_f32_e32 v67, 0xbf3504f3, v69
	v_mul_f32_e32 v69, 0x3ec3ef15, v58
	v_mul_f32_e32 v58, 0xbf6c835e, v58
	v_fmac_f32_e32 v69, 0x3f6c835e, v59
	v_fmac_f32_e32 v58, 0x3ec3ef15, v59
	v_mul_f32_e32 v59, 0xbf3504f3, v60
	v_fmamk_f32 v60, v61, 0x3f3504f3, v59
	v_fmac_f32_e32 v59, 0xbf3504f3, v61
	v_mul_f32_e32 v61, 0xbf6c835e, v62
	v_fmac_f32_e32 v61, 0xbec3ef15, v63
	v_mul_f32_e32 v63, 0xbf6c835e, v63
	v_mul_f32_e32 v57, 0x3f3504f3, v57
	v_fmac_f32_e32 v63, 0x3ec3ef15, v62
	v_add_f32_e32 v62, v99, v107
	v_add_f32_e32 v111, v104, v108
	v_sub_f32_e32 v99, v99, v107
	v_sub_f32_e32 v104, v104, v108
	v_add_f32_e32 v107, v105, v109
	v_add_f32_e32 v108, v106, v110
	v_sub_f32_e32 v105, v105, v109
	v_sub_f32_e32 v106, v106, v110
	v_fmamk_f32 v102, v65, 0x3f3504f3, v57
	v_fma_f32 v65, v65, s72, -v57
	v_add_f32_e32 v109, v62, v107
	v_add_f32_e32 v57, v111, v108
	v_sub_f32_e32 v62, v62, v107
	v_sub_f32_e32 v107, v111, v108
	v_add_f32_e32 v108, v99, v106
	v_sub_f32_e32 v110, v104, v105
	v_sub_f32_e32 v99, v99, v106
	v_add_f32_e32 v104, v104, v105
	v_add_f32_e32 v105, v76, v75
	v_add_f32_e32 v106, v77, v74
	v_sub_f32_e32 v75, v76, v75
	v_sub_f32_e32 v74, v77, v74
	v_add_f32_e32 v76, v70, v100
	v_add_f32_e32 v77, v71, v101
	v_sub_f32_e32 v70, v70, v100
	v_sub_f32_e32 v71, v71, v101
	v_add_f32_e32 v100, v105, v76
	v_add_f32_e32 v101, v106, v77
	v_sub_f32_e32 v76, v105, v76
	v_sub_f32_e32 v77, v106, v77
	v_add_f32_e32 v105, v75, v71
	v_sub_f32_e32 v106, v74, v70
	v_sub_f32_e32 v71, v75, v71
	v_add_f32_e32 v70, v74, v70
	v_add_f32_e32 v74, v72, v103
	v_add_f32_e32 v75, v73, v66
	v_sub_f32_e32 v72, v72, v103
	v_sub_f32_e32 v66, v73, v66
	v_add_f32_e32 v73, v102, v68
	v_add_f32_e32 v103, v65, v67
	v_sub_f32_e32 v68, v102, v68
	v_sub_f32_e32 v65, v65, v67
	v_add_f32_e32 v67, v74, v73
	v_add_f32_e32 v102, v75, v103
	v_sub_f32_e32 v73, v74, v73
	v_sub_f32_e32 v74, v75, v103
	v_add_f32_e32 v75, v72, v65
	v_sub_f32_e32 v103, v66, v68
	v_sub_f32_e32 v65, v72, v65
	v_add_f32_e32 v66, v66, v68
	v_add_f32_e32 v68, v56, v60
	v_add_f32_e32 v72, v64, v59
	v_sub_f32_e32 v56, v56, v60
	v_sub_f32_e32 v59, v64, v59
	v_add_f32_e32 v60, v69, v61
	v_add_f32_e32 v64, v58, v63
	v_sub_f32_e32 v61, v69, v61
	v_sub_f32_e32 v58, v58, v63
	v_add_f32_e32 v63, v68, v60
	v_add_f32_e32 v69, v72, v64
	v_sub_f32_e32 v60, v68, v60
	v_sub_f32_e32 v64, v72, v64
	v_add_f32_e32 v68, v56, v58
	v_sub_f32_e32 v72, v59, v61
	v_sub_f32_e32 v58, v56, v58
	v_add_f32_e32 v59, v59, v61
	v_fmamk_f32 v56, v57, 0x80000000, v109
	v_fmac_f32_e32 v57, 0, v109
	ds_write_b64 v90, v[56:57]
	v_fmamk_f32 v61, v55, 0x80000000, v54
	v_fma_f32 v109, 0, v54, v55
	v_mul_f32_e32 v56, v109, v101
	v_mul_f32_e32 v57, v61, v101
	v_fma_f32 v56, v61, v100, -v56
	v_fmac_f32_e32 v57, v109, v100
	ds_write_b64 v90, v[56:57] offset:136
	v_mul_f32_e32 v56, v55, v109
	v_fma_f32 v100, v54, v61, -v56
	v_mul_f32_e32 v61, v55, v61
	v_fmac_f32_e32 v61, v54, v109
	v_mul_f32_e32 v56, v61, v102
	v_mul_f32_e32 v57, v100, v102
	v_fma_f32 v56, v100, v67, -v56
	v_fmac_f32_e32 v57, v61, v67
	ds_write_b64 v90, v[56:57] offset:272
	v_mul_f32_e32 v56, v55, v61
	v_mul_f32_e32 v61, v54, v61
	v_fma_f32 v67, v54, v100, -v56
	v_fmac_f32_e32 v61, v55, v100
	v_mul_f32_e32 v56, v61, v69
	v_mul_f32_e32 v57, v67, v69
	v_fma_f32 v56, v67, v63, -v56
	v_fmac_f32_e32 v57, v61, v63
	ds_write_b64 v90, v[56:57] offset:408
	v_mul_f32_e32 v56, v55, v61
	v_mul_f32_e32 v61, v54, v61
	v_fma_f32 v63, v54, v67, -v56
	v_fmac_f32_e32 v61, v55, v67
	v_mul_f32_e32 v56, v61, v110
	v_mul_f32_e32 v57, v61, v108
	v_fma_f32 v56, v63, v108, -v56
	v_fmac_f32_e32 v57, v63, v110
	ds_write_b64 v90, v[56:57] offset:544
	v_mul_f32_e32 v56, v55, v61
	v_mul_f32_e32 v61, v54, v61
	v_fma_f32 v67, v54, v63, -v56
	v_fmac_f32_e32 v61, v55, v63
	v_mul_f32_e32 v56, v61, v106
	v_mul_f32_e32 v57, v67, v106
	v_fma_f32 v56, v67, v105, -v56
	v_fmac_f32_e32 v57, v61, v105
	ds_write_b64 v90, v[56:57] offset:680
	v_mul_f32_e32 v56, v55, v61
	v_mul_f32_e32 v61, v54, v61
	v_fma_f32 v63, v54, v67, -v56
	v_fmac_f32_e32 v61, v55, v67
	v_mul_f32_e32 v56, v61, v103
	v_mul_f32_e32 v57, v63, v103
	v_fma_f32 v56, v63, v75, -v56
	v_fmac_f32_e32 v57, v61, v75
	ds_write_b64 v90, v[56:57] offset:816
	v_mul_f32_e32 v56, v55, v61
	v_mul_f32_e32 v61, v54, v61
	v_fma_f32 v67, v54, v63, -v56
	v_fmac_f32_e32 v61, v55, v63
	v_mul_f32_e32 v56, v61, v72
	v_mul_f32_e32 v57, v67, v72
	v_fma_f32 v56, v67, v68, -v56
	v_fmac_f32_e32 v57, v61, v68
	ds_write_b64 v90, v[56:57] offset:952
	v_mul_f32_e32 v56, v55, v61
	v_mul_f32_e32 v61, v54, v61
	v_fma_f32 v63, v54, v67, -v56
	v_fmac_f32_e32 v61, v55, v67
	v_mul_f32_e32 v56, v61, v107
	v_mul_f32_e32 v57, v63, v107
	v_fma_f32 v56, v63, v62, -v56
	v_fmac_f32_e32 v57, v61, v62
	ds_write_b64 v90, v[56:57] offset:1088
	v_mul_f32_e32 v56, v55, v61
	v_mul_f32_e32 v61, v54, v61
	v_fma_f32 v62, v54, v63, -v56
	v_fmac_f32_e32 v61, v55, v63
	v_mul_f32_e32 v56, v61, v77
	v_mul_f32_e32 v57, v62, v77
	v_fma_f32 v56, v62, v76, -v56
	v_fmac_f32_e32 v57, v61, v76
	ds_write_b64 v90, v[56:57] offset:1224
	v_mul_f32_e32 v56, v55, v61
	v_mul_f32_e32 v61, v54, v61
	v_fma_f32 v63, v54, v62, -v56
	v_fmac_f32_e32 v61, v55, v62
	v_mul_f32_e32 v56, v61, v74
	v_mul_f32_e32 v57, v63, v74
	v_fma_f32 v56, v63, v73, -v56
	v_fmac_f32_e32 v57, v61, v73
	ds_write_b64 v90, v[56:57] offset:1360
	v_mul_f32_e32 v56, v55, v61
	v_mul_f32_e32 v61, v54, v61
	v_fma_f32 v62, v54, v63, -v56
	v_fmac_f32_e32 v61, v55, v63
	v_mul_f32_e32 v56, v61, v64
	v_mul_f32_e32 v57, v62, v64
	v_fma_f32 v56, v62, v60, -v56
	v_fmac_f32_e32 v57, v61, v60
	ds_write_b64 v90, v[56:57] offset:1496
	v_mul_f32_e32 v56, v55, v61
	v_mul_f32_e32 v61, v54, v61
	v_fma_f32 v60, v54, v62, -v56
	v_fmac_f32_e32 v61, v55, v62
	v_mul_f32_e32 v56, v61, v104
	v_mul_f32_e32 v57, v61, v99
	v_fma_f32 v56, v60, v99, -v56
	v_fmac_f32_e32 v57, v60, v104
	ds_write_b64 v90, v[56:57] offset:1632
	v_mul_f32_e32 v56, v55, v61
	v_mul_f32_e32 v61, v54, v61
	v_fma_f32 v62, v54, v60, -v56
	v_fmac_f32_e32 v61, v55, v60
	v_mul_f32_e32 v56, v61, v70
	v_mul_f32_e32 v57, v62, v70
	v_fma_f32 v56, v62, v71, -v56
	v_fmac_f32_e32 v57, v61, v71
	ds_write_b64 v90, v[56:57] offset:1768
	v_mul_f32_e32 v56, v55, v61
	v_mul_f32_e32 v61, v54, v61
	v_fma_f32 v60, v54, v62, -v56
	v_fmac_f32_e32 v61, v55, v62
	v_mul_f32_e32 v56, v61, v66
	v_mul_f32_e32 v57, v60, v66
	v_fma_f32 v56, v60, v65, -v56
	v_fmac_f32_e32 v57, v61, v65
	ds_write_b64 v90, v[56:57] offset:1904
	v_mul_f32_e32 v56, v55, v61
	v_mul_f32_e32 v57, v54, v61
	v_fma_f32 v56, v54, v60, -v56
	v_fmac_f32_e32 v57, v55, v60
	v_mul_f32_e32 v54, v57, v59
	v_mul_f32_e32 v55, v56, v59
	v_fma_f32 v54, v56, v58, -v54
	v_fmac_f32_e32 v55, v57, v58
	ds_write_b64 v90, v[54:55] offset:2040
	s_waitcnt lgkmcnt(0)
	s_barrier
	ds_read2_b64 v[54:57], v91 offset1:1
	ds_read2_b64 v[58:61], v91 offset0:2 offset1:3
	ds_read2_b64 v[62:65], v91 offset0:8 offset1:9
	ds_read2_b64 v[66:69], v91 offset0:4 offset1:5
	ds_read2_b64 v[70:73], v91 offset0:6 offset1:7
	ds_read2_b64 v[74:77], v91 offset0:10 offset1:11
	ds_read2_b64 v[100:103], v91 offset0:14 offset1:15
	ds_read2_b64 v[104:107], v91 offset0:12 offset1:13
	s_waitcnt lgkmcnt(5)
	v_add_f32_e32 v99, v54, v62
	v_add_f32_e32 v108, v55, v63
	v_sub_f32_e32 v54, v54, v62
	v_sub_f32_e32 v55, v55, v63
	s_waitcnt lgkmcnt(0)
	v_add_f32_e32 v62, v66, v104
	v_add_f32_e32 v63, v67, v105
	v_sub_f32_e32 v66, v66, v104
	v_sub_f32_e32 v67, v67, v105
	v_add_f32_e32 v104, v99, v62
	v_add_f32_e32 v105, v108, v63
	v_sub_f32_e32 v99, v99, v62
	v_sub_f32_e32 v108, v108, v63
	v_add_f32_e32 v62, v54, v67
	v_sub_f32_e32 v63, v55, v66
	v_sub_f32_e32 v109, v54, v67
	v_add_f32_e32 v110, v55, v66
	v_add_f32_e32 v54, v56, v64
	v_add_f32_e32 v55, v57, v65
	v_sub_f32_e32 v56, v56, v64
	v_sub_f32_e32 v57, v57, v65
	v_add_f32_e32 v64, v68, v106
	v_add_f32_e32 v65, v69, v107
	v_sub_f32_e32 v66, v68, v106
	v_sub_f32_e32 v67, v69, v107
	v_add_f32_e32 v68, v54, v64
	v_add_f32_e32 v69, v55, v65
	v_sub_f32_e32 v54, v54, v64
	v_sub_f32_e32 v55, v55, v65
	v_add_f32_e32 v64, v56, v67
	v_sub_f32_e32 v65, v57, v66
	v_sub_f32_e32 v56, v56, v67
	v_add_f32_e32 v57, v57, v66
	v_add_f32_e32 v66, v58, v74
	v_add_f32_e32 v67, v59, v75
	v_sub_f32_e32 v58, v58, v74
	v_sub_f32_e32 v59, v59, v75
	v_add_f32_e32 v74, v70, v100
	v_add_f32_e32 v75, v71, v101
	v_sub_f32_e32 v70, v70, v100
	v_sub_f32_e32 v71, v71, v101
	v_add_f32_e32 v100, v66, v74
	v_add_f32_e32 v101, v67, v75
	v_sub_f32_e32 v66, v66, v74
	v_sub_f32_e32 v67, v67, v75
	v_add_f32_e32 v74, v58, v71
	v_sub_f32_e32 v75, v59, v70
	v_sub_f32_e32 v58, v58, v71
	v_add_f32_e32 v59, v59, v70
	v_add_f32_e32 v70, v60, v76
	v_add_f32_e32 v71, v61, v77
	v_sub_f32_e32 v60, v60, v76
	v_sub_f32_e32 v61, v61, v77
	v_add_f32_e32 v76, v72, v102
	v_add_f32_e32 v77, v73, v103
	v_sub_f32_e32 v72, v72, v102
	v_sub_f32_e32 v73, v73, v103
	v_add_f32_e32 v102, v70, v76
	v_add_f32_e32 v103, v71, v77
	v_sub_f32_e32 v70, v70, v76
	v_sub_f32_e32 v71, v71, v77
	v_add_f32_e32 v76, v60, v73
	v_sub_f32_e32 v77, v61, v72
	v_sub_f32_e32 v60, v60, v73
	v_add_f32_e32 v61, v61, v72
	v_mul_f32_e32 v72, 0x3f6c835e, v64
	v_mul_f32_e32 v64, 0xbec3ef15, v64
	v_fmac_f32_e32 v72, 0x3ec3ef15, v65
	v_fmac_f32_e32 v64, 0x3f6c835e, v65
	v_mul_f32_e32 v65, 0x3f3504f3, v74
	v_mul_f32_e32 v74, 0x3ec3ef15, v76
	v_mul_f32_e32 v54, 0x3f3504f3, v54
	v_mul_f32_e32 v117, 0xbf6c835e, v60
	v_fmamk_f32 v73, v75, 0x3f3504f3, v65
	v_fma_f32 v65, v75, s72, -v65
	v_fmac_f32_e32 v74, 0x3f6c835e, v77
	v_mul_f32_e32 v75, 0xbf6c835e, v76
	v_fmamk_f32 v106, v55, 0x3f3504f3, v54
	v_fma_f32 v107, v55, s72, -v54
	v_mul_f32_e32 v113, 0x3ec3ef15, v56
	v_mul_f32_e32 v114, 0xbf6c835e, v56
	v_mul_f32_e32 v115, 0xbf3504f3, v58
	v_fmac_f32_e32 v117, 0xbec3ef15, v61
	v_mul_f32_e32 v118, 0xbf6c835e, v61
	v_add_f32_e32 v54, v104, v100
	v_sub_f32_e32 v56, v104, v100
	v_add_f32_e32 v58, v68, v102
	v_sub_f32_e32 v61, v69, v103
	v_fmac_f32_e32 v75, 0x3ec3ef15, v77
	v_fmac_f32_e32 v113, 0x3f6c835e, v57
	v_fmac_f32_e32 v114, 0x3ec3ef15, v57
	v_fmamk_f32 v116, v59, 0x3f3504f3, v115
	v_fmac_f32_e32 v115, 0xbf3504f3, v59
	v_fmac_f32_e32 v118, 0x3ec3ef15, v60
	v_add_f32_e32 v55, v105, v101
	v_sub_f32_e32 v57, v105, v101
	v_add_f32_e32 v59, v69, v103
	v_sub_f32_e32 v60, v68, v102
	v_add_f32_e32 v119, v58, v54
	v_sub_f32_e32 v121, v54, v58
	v_add_f32_e32 v123, v56, v61
	v_sub_f32_e32 v125, v56, v61
	v_add_f32_e32 v54, v62, v73
	v_add_f32_e32 v56, v72, v74
	v_add_f32_e32 v120, v59, v55
	v_sub_f32_e32 v122, v55, v59
	v_sub_f32_e32 v124, v57, v60
	v_add_f32_e32 v126, v60, v57
	v_add_f32_e32 v55, v63, v65
	v_add_f32_e32 v57, v64, v75
	v_add_f32_e32 v127, v56, v54
	v_sub_f32_e32 v129, v54, v56
	v_mov_b32_e32 v54, v0
	v_add_f32_e32 v128, v57, v55
	v_sub_f32_e32 v130, v55, v57
	s_barrier
	v_sub_f32_e32 v69, v64, v75
	v_ashrrev_i32_e32 v55, 31, v54
	v_lshl_add_u64 v[54:55], v[54:55], 3, s[34:35]
	v_add_co_u32_e32 v60, vcc, s19, v54
	v_fma_f32 v76, 0, v66, v67
	s_nop 0
	v_addc_co_u32_e32 v61, vcc, 0, v55, vcc
	v_add_co_u32_e32 v64, vcc, s18, v54
	v_fma_f32 v77, v67, 0, -v66
	v_sub_f32_e32 v67, v63, v65
	v_sub_f32_e32 v68, v72, v74
	v_addc_co_u32_e32 v65, vcc, 0, v55, vcc
	v_sub_f32_e32 v66, v62, v73
	v_sub_f32_e32 v132, v67, v68
	v_add_f32_e32 v134, v68, v67
	v_add_co_u32_e32 v68, vcc, s50, v54
	v_add_f32_e32 v131, v69, v66
	v_sub_f32_e32 v133, v66, v69
	v_addc_co_u32_e32 v69, vcc, 0, v55, vcc
	v_add_co_u32_e32 v72, vcc, s67, v54
	v_add_f32_e32 v135, v99, v76
	s_nop 0
	v_addc_co_u32_e32 v73, vcc, 0, v55, vcc
	v_sub_f32_e32 v99, v99, v76
	v_add_co_u32_e32 v76, vcc, s51, v54
	global_load_dwordx2 v[56:57], v[54:55], off
	global_load_dwordx2 v[58:59], v[54:55], off offset:2048
	global_load_dwordx2 v[66:67], v[60:61], off
	v_add_f32_e32 v136, v108, v77
	v_sub_f32_e32 v108, v108, v77
	v_addc_co_u32_e32 v77, vcc, 0, v55, vcc
	v_add_co_u32_e32 v102, vcc, s5, v54
	v_mul_f32_e32 v111, 0xbf3504f3, v70
	global_load_dwordx2 v[62:63], v[60:61], off offset:-4096
	v_addc_co_u32_e32 v103, vcc, 0, v55, vcc
	v_fmamk_f32 v112, v71, 0x3f3504f3, v111
	v_fmac_f32_e32 v111, 0xbf3504f3, v71
	global_load_dwordx2 v[64:65], v[64:65], off offset:2048
	v_add_f32_e32 v137, v106, v112
	global_load_dwordx2 v[70:71], v[68:69], off offset:-4096
	v_add_co_u32_e32 v54, vcc, s56, v54
	global_load_dwordx2 v[72:73], v[72:73], off offset:2048
	s_nop 0
	v_addc_co_u32_e32 v55, vcc, 0, v55, vcc
	v_add_f32_e32 v138, v107, v111
	v_sub_f32_e32 v112, v106, v112
	v_sub_f32_e32 v111, v107, v111
	global_load_dwordx2 v[106:107], v[54:55], off
	global_load_dwordx2 v[74:75], v[68:69], off
	global_load_dwordx2 v[100:101], v[76:77], off offset:-4096
	global_load_dwordx2 v[104:105], v[76:77], off
	v_add_f32_e32 v139, v135, v137
	global_load_dwordx2 v[60:61], v[60:61], off offset:2048
	v_add_f32_e32 v140, v138, v136
	global_load_dwordx2 v[68:69], v[68:69], off offset:2048
	v_sub_f32_e32 v135, v135, v137
	global_load_dwordx2 v[102:103], v[102:103], off offset:2048
	v_sub_f32_e32 v136, v136, v138
	global_load_dwordx2 v[76:77], v[76:77], off offset:2048
	v_add_f32_e32 v137, v99, v111
	global_load_dwordx2 v[54:55], v[54:55], off offset:2048
	v_sub_f32_e32 v138, v108, v112
	v_sub_f32_e32 v99, v99, v111
	v_add_f32_e32 v108, v112, v108
	v_add_f32_e32 v111, v109, v116
	v_add_f32_e32 v112, v110, v115
	v_sub_f32_e32 v109, v109, v116
	v_sub_f32_e32 v110, v110, v115
	v_add_f32_e32 v115, v113, v117
	v_add_f32_e32 v116, v114, v118
	v_sub_f32_e32 v113, v113, v117
	v_sub_f32_e32 v114, v114, v118
	v_add_f32_e32 v117, v115, v111
	v_add_f32_e32 v118, v116, v112
	v_sub_f32_e32 v111, v111, v115
	v_sub_f32_e32 v112, v112, v116
	v_add_f32_e32 v115, v114, v109
	v_sub_f32_e32 v116, v110, v113
	v_sub_f32_e32 v109, v109, v114
	v_add_f32_e32 v110, v113, v110
	s_mov_b32 s89, 0
	s_waitcnt vmcnt(15)
	v_mul_f32_e32 v113, v120, v57
	v_mul_f32_e32 v114, v119, v57
	v_fma_f32 v113, v119, v56, -v113
	v_fmac_f32_e32 v114, v120, v56
	s_waitcnt vmcnt(14)
	v_mul_f32_e32 v56, v124, v59
	v_fma_f32 v119, v123, v58, -v56
	v_mul_f32_e32 v59, v123, v59
	v_fmac_f32_e32 v59, v124, v58
	v_mov_b32_e32 v57, v81
	s_waitcnt vmcnt(12)
	v_mul_f32_e32 v56, v122, v63
	v_fma_f32 v58, v121, v62, -v56
	v_mul_f32_e32 v63, v121, v63
	v_fmac_f32_e32 v63, v122, v62
	s_waitcnt vmcnt(11)
	v_mul_f32_e32 v56, v126, v65
	v_fma_f32 v62, v125, v64, -v56
	v_mul_f32_e32 v65, v125, v65
	v_mul_f32_e32 v56, v128, v67
	v_fmac_f32_e32 v65, v126, v64
	v_fma_f32 v64, v127, v66, -v56
	v_mul_f32_e32 v67, v127, v67
	v_fmac_f32_e32 v67, v128, v66
	s_waitcnt vmcnt(4)
	v_mul_f32_e32 v56, v132, v61
	v_fma_f32 v66, v131, v60, -v56
	v_mul_f32_e32 v61, v131, v61
	v_mul_f32_e32 v56, v130, v71
	v_fmac_f32_e32 v61, v132, v60
	v_fma_f32 v60, v129, v70, -v56
	v_mul_f32_e32 v71, v129, v71
	v_mul_f32_e32 v56, v134, v73
	v_fmac_f32_e32 v71, v130, v70
	v_fma_f32 v70, v133, v72, -v56
	v_mul_f32_e32 v73, v133, v73
	v_mul_f32_e32 v56, v140, v75
	v_fmac_f32_e32 v73, v134, v72
	v_fma_f32 v72, v139, v74, -v56
	v_mul_f32_e32 v75, v139, v75
	s_waitcnt vmcnt(3)
	v_mul_f32_e32 v56, v138, v69
	v_fmac_f32_e32 v75, v140, v74
	v_fma_f32 v74, v137, v68, -v56
	v_mul_f32_e32 v69, v137, v69
	v_mul_f32_e32 v56, v136, v101
	v_fmac_f32_e32 v69, v138, v68
	v_fma_f32 v68, v135, v100, -v56
	v_mul_f32_e32 v101, v135, v101
	s_waitcnt vmcnt(2)
	v_mul_f32_e32 v56, v108, v103
	v_fmac_f32_e32 v101, v136, v100
	v_fma_f32 v100, v99, v102, -v56
	v_mul_f32_e32 v99, v99, v103
	v_mul_f32_e32 v56, v118, v105
	v_fmac_f32_e32 v99, v108, v102
	v_fma_f32 v102, v117, v104, -v56
	v_mul_f32_e32 v103, v117, v105
	s_waitcnt vmcnt(1)
	v_mul_f32_e32 v56, v116, v77
	v_fmac_f32_e32 v103, v118, v104
	v_fma_f32 v104, v115, v76, -v56
	v_mul_f32_e32 v77, v115, v77
	v_mul_f32_e32 v56, v112, v107
	v_mul_f32_e32 v105, v111, v107
	s_waitcnt vmcnt(0)
	v_mul_f32_e32 v107, v109, v55
	v_fmac_f32_e32 v77, v116, v76
	v_fma_f32 v76, v111, v106, -v56
	v_fmac_f32_e32 v105, v112, v106
	v_mul_f32_e32 v56, v110, v55
	v_fmac_f32_e32 v107, v110, v54
	v_add_f32_e32 v110, v113, v58
	v_add_f32_e32 v111, v114, v63
	v_sub_f32_e32 v58, v113, v58
	v_sub_f32_e32 v63, v114, v63
	v_add_f32_e32 v112, v119, v62
	v_add_f32_e32 v113, v59, v65
	v_sub_f32_e32 v62, v119, v62
	v_sub_f32_e32 v59, v59, v65
	v_add_f32_e32 v65, v110, v112
	v_add_f32_e32 v114, v111, v113
	v_sub_f32_e32 v110, v110, v112
	v_sub_f32_e32 v111, v111, v113
	v_sub_f32_e32 v112, v58, v59
	v_add_f32_e32 v113, v63, v62
	v_add_f32_e32 v58, v58, v59
	v_sub_f32_e32 v62, v63, v62
	v_add_f32_e32 v59, v64, v60
	v_add_f32_e32 v63, v67, v71
	v_sub_f32_e32 v60, v64, v60
	v_sub_f32_e32 v64, v67, v71
	v_add_f32_e32 v67, v66, v70
	v_add_f32_e32 v71, v61, v73
	v_sub_f32_e32 v66, v66, v70
	v_sub_f32_e32 v61, v61, v73
	v_fma_f32 v106, v109, v54, -v56
	v_add_f32_e32 v70, v59, v67
	v_add_f32_e32 v73, v63, v71
	v_sub_f32_e32 v59, v59, v67
	v_sub_f32_e32 v63, v63, v71
	v_sub_f32_e32 v67, v60, v61
	v_add_f32_e32 v71, v64, v66
	v_add_f32_e32 v60, v60, v61
	v_sub_f32_e32 v61, v64, v66
	v_add_f32_e32 v64, v72, v68
	v_add_f32_e32 v66, v75, v101
	v_sub_f32_e32 v68, v72, v68
	v_sub_f32_e32 v72, v75, v101
	v_add_f32_e32 v75, v74, v100
	v_add_f32_e32 v101, v69, v99
	v_sub_f32_e32 v74, v74, v100
	v_sub_f32_e32 v69, v69, v99
	v_add_f32_e32 v99, v64, v75
	v_add_f32_e32 v100, v66, v101
	v_sub_f32_e32 v64, v64, v75
	v_sub_f32_e32 v66, v66, v101
	v_sub_f32_e32 v75, v68, v69
	v_add_f32_e32 v101, v72, v74
	v_add_f32_e32 v68, v68, v69
	v_sub_f32_e32 v69, v72, v74
	v_add_f32_e32 v72, v102, v76
	v_add_f32_e32 v74, v103, v105
	v_sub_f32_e32 v76, v102, v76
	v_sub_f32_e32 v102, v103, v105
	v_add_f32_e32 v103, v104, v106
	v_add_f32_e32 v105, v77, v107
	v_sub_f32_e32 v104, v104, v106
	v_sub_f32_e32 v77, v77, v107
	v_add_f32_e32 v106, v72, v103
	v_add_f32_e32 v107, v74, v105
	v_sub_f32_e32 v72, v72, v103
	v_sub_f32_e32 v74, v74, v105
	v_sub_f32_e32 v103, v76, v77
	v_add_f32_e32 v105, v102, v104
	v_add_f32_e32 v76, v76, v77
	v_sub_f32_e32 v77, v102, v104
	v_mul_f32_e32 v104, 0xbf6c835e, v61
	v_fmac_f32_e32 v104, 0x3ec3ef15, v60
	v_mul_f32_e32 v60, 0x3f6c835e, v60
	v_fmac_f32_e32 v60, 0x3ec3ef15, v61
	v_mul_f32_e32 v61, 0x3f3504f3, v75
	v_fmamk_f32 v75, v101, 0xbf3504f3, v61
	v_fmac_f32_e32 v61, 0x3f3504f3, v101
	v_fma_f32 v101, v64, 0, -v66
	v_fmac_f32_e32 v64, 0, v66
	v_mul_f32_e32 v66, 0xbf3504f3, v69
	v_fmamk_f32 v69, v68, 0xbf3504f3, v66
	v_fmac_f32_e32 v66, 0x3f3504f3, v68
	v_mul_f32_e32 v68, 0xbf6c835e, v105
	v_mul_f32_e32 v102, 0xbec3ef15, v71
	v_fmac_f32_e32 v68, 0x3ec3ef15, v103
	v_mul_f32_e32 v103, 0x3f6c835e, v103
	v_mul_f32_e32 v74, 0xbf3504f3, v74
	v_fmac_f32_e32 v102, 0x3f6c835e, v67
	v_mul_f32_e32 v67, 0x3ec3ef15, v67
	v_fmac_f32_e32 v103, 0x3ec3ef15, v105
	v_fmamk_f32 v105, v72, 0xbf3504f3, v74
	v_fmac_f32_e32 v74, 0x3f3504f3, v72
	v_mul_f32_e32 v72, 0xbf6c835e, v76
	v_mul_f32_e32 v76, 0xbec3ef15, v76
	v_fmac_f32_e32 v67, 0x3f6c835e, v71
	v_mul_f32_e32 v63, 0x3f3504f3, v63
	v_fmac_f32_e32 v72, 0x3ec3ef15, v77
	v_fmac_f32_e32 v76, 0xbf6c835e, v77
	v_add_f32_e32 v77, v65, v99
	v_add_f32_e32 v115, v114, v100
	v_sub_f32_e32 v65, v65, v99
	v_sub_f32_e32 v99, v114, v100
	v_add_f32_e32 v100, v70, v106
	v_add_f32_e32 v114, v73, v107
	v_sub_f32_e32 v70, v70, v106
	v_sub_f32_e32 v73, v73, v107
	v_fma_f32 v71, v59, s72, -v63
	v_fmac_f32_e32 v63, 0x3f3504f3, v59
	v_add_f32_e32 v106, v77, v100
	v_add_f32_e32 v59, v115, v114
	v_sub_f32_e32 v77, v77, v100
	v_sub_f32_e32 v100, v115, v114
	v_sub_f32_e32 v107, v65, v73
	v_add_f32_e32 v114, v99, v70
	v_add_f32_e32 v65, v65, v73
	v_sub_f32_e32 v70, v99, v70
	v_add_f32_e32 v73, v112, v75
	v_add_f32_e32 v99, v113, v61
	v_sub_f32_e32 v75, v112, v75
	v_sub_f32_e32 v61, v113, v61
	v_add_f32_e32 v112, v102, v68
	v_add_f32_e32 v113, v67, v103
	v_sub_f32_e32 v68, v102, v68
	v_sub_f32_e32 v67, v67, v103
	v_add_f32_e32 v102, v73, v112
	v_add_f32_e32 v103, v99, v113
	v_sub_f32_e32 v73, v73, v112
	v_sub_f32_e32 v99, v99, v113
	v_sub_f32_e32 v112, v75, v67
	v_add_f32_e32 v113, v61, v68
	v_add_f32_e32 v67, v75, v67
	v_sub_f32_e32 v61, v61, v68
	v_add_f32_e32 v68, v110, v101
	v_add_f32_e32 v75, v111, v64
	v_sub_f32_e32 v101, v110, v101
	v_sub_f32_e32 v64, v111, v64
	v_add_f32_e32 v110, v71, v105
	v_add_f32_e32 v111, v63, v74
	v_sub_f32_e32 v71, v71, v105
	v_sub_f32_e32 v63, v63, v74
	v_mov_b32_e32 v108, v78
	v_mov_b32_e32 v109, v79
	v_mov_b32_e32 v56, v80
	v_mov_b32_e32 v54, v84
	v_mov_b32_e32 v55, v85
	v_add_f32_e32 v74, v68, v110
	v_add_f32_e32 v105, v75, v111
	v_sub_f32_e32 v68, v68, v110
	v_sub_f32_e32 v75, v75, v111
	v_sub_f32_e32 v110, v101, v63
	v_add_f32_e32 v111, v64, v71
	v_add_f32_e32 v63, v101, v63
	v_sub_f32_e32 v64, v64, v71
	v_add_f32_e32 v71, v58, v69
	v_add_f32_e32 v101, v62, v66
	v_sub_f32_e32 v58, v58, v69
	v_sub_f32_e32 v62, v62, v66
	v_add_f32_e32 v66, v104, v72
	v_add_f32_e32 v69, v60, v76
	v_sub_f32_e32 v72, v104, v72
	v_sub_f32_e32 v60, v60, v76
	v_add_f32_e32 v76, v71, v66
	v_add_f32_e32 v104, v101, v69
	v_sub_f32_e32 v66, v71, v66
	v_sub_f32_e32 v69, v101, v69
	v_sub_f32_e32 v71, v58, v60
	v_add_f32_e32 v101, v62, v72
	v_add_f32_e32 v60, v58, v60
	v_sub_f32_e32 v62, v62, v72
	v_fma_f32 v58, 0, v59, v106
	v_fmac_f32_e32 v59, 0x80000000, v106
	ds_write_b64 v91, v[58:59]
	v_fmamk_f32 v72, v109, 0x80000000, v108
	v_fma_f32 v106, 0, v108, v109
	v_mul_f32_e32 v58, v106, v103
	v_mul_f32_e32 v59, v106, v102
	v_fmac_f32_e32 v58, v72, v102
	v_fma_f32 v59, v72, v103, -v59
	ds_write_b64 v91, v[58:59] offset:8
	v_mul_f32_e32 v58, v109, v106
	v_fma_f32 v102, v108, v72, -v58
	v_mul_f32_e32 v72, v109, v72
	v_fmac_f32_e32 v72, v108, v106
	v_mul_f32_e32 v58, v72, v105
	v_mul_f32_e32 v59, v72, v74
	v_fmac_f32_e32 v58, v102, v74
	v_fma_f32 v59, v102, v105, -v59
	ds_write_b64 v91, v[58:59] offset:16
	v_mul_f32_e32 v58, v109, v72
	v_fma_f32 v74, v108, v102, -v58
	v_mul_f32_e32 v102, v109, v102
	v_fmac_f32_e32 v102, v108, v72
	v_mul_f32_e32 v58, v102, v104
	v_mul_f32_e32 v59, v102, v76
	v_fmac_f32_e32 v58, v74, v76
	v_fma_f32 v59, v74, v104, -v59
	ds_write_b64 v91, v[58:59] offset:24
	v_mul_f32_e32 v58, v109, v102
	v_fma_f32 v72, v108, v74, -v58
	v_mul_f32_e32 v74, v109, v74
	v_fmac_f32_e32 v74, v108, v102
	v_mul_f32_e32 v58, v114, v74
	v_mul_f32_e32 v59, v107, v74
	v_fmac_f32_e32 v58, v107, v72
	v_fma_f32 v59, v114, v72, -v59
	ds_write_b64 v91, v[58:59] offset:32
	v_mul_f32_e32 v58, v109, v74
	v_fma_f32 v76, v108, v72, -v58
	v_mul_f32_e32 v72, v109, v72
	v_fmac_f32_e32 v72, v108, v74
	v_mul_f32_e32 v58, v113, v72
	v_mul_f32_e32 v59, v112, v72
	v_fmac_f32_e32 v58, v112, v76
	v_fma_f32 v59, v113, v76, -v59
	ds_write_b64 v91, v[58:59] offset:40
	v_mul_f32_e32 v58, v109, v72
	v_fma_f32 v74, v108, v76, -v58
	v_mul_f32_e32 v76, v109, v76
	v_fmac_f32_e32 v76, v108, v72
	v_mul_f32_e32 v58, v111, v76
	v_mul_f32_e32 v59, v110, v76
	v_fmac_f32_e32 v58, v110, v74
	v_fma_f32 v59, v111, v74, -v59
	ds_write_b64 v91, v[58:59] offset:48
	v_mul_f32_e32 v58, v109, v76
	v_fma_f32 v72, v108, v74, -v58
	v_mul_f32_e32 v74, v109, v74
	v_fmac_f32_e32 v74, v108, v76
	v_mul_f32_e32 v58, v101, v74
	v_mul_f32_e32 v59, v71, v74
	v_fmac_f32_e32 v58, v71, v72
	v_fma_f32 v59, v101, v72, -v59
	ds_write_b64 v91, v[58:59] offset:56
	v_mul_f32_e32 v58, v109, v74
	v_fma_f32 v71, v108, v72, -v58
	v_mul_f32_e32 v72, v109, v72
	v_fmac_f32_e32 v72, v108, v74
	v_mul_f32_e32 v58, v100, v72
	v_mul_f32_e32 v59, v77, v72
	v_fmac_f32_e32 v58, v77, v71
	v_fma_f32 v59, v100, v71, -v59
	ds_write_b64 v91, v[58:59] offset:64
	v_mul_f32_e32 v58, v109, v72
	v_fma_f32 v74, v108, v71, -v58
	v_mul_f32_e32 v71, v109, v71
	v_fmac_f32_e32 v71, v108, v72
	v_mul_f32_e32 v58, v99, v71
	v_mul_f32_e32 v59, v73, v71
	v_fmac_f32_e32 v58, v73, v74
	v_fma_f32 v59, v99, v74, -v59
	ds_write_b64 v91, v[58:59] offset:72
	v_mul_f32_e32 v58, v109, v71
	v_mul_f32_e32 v73, v109, v74
	v_fma_f32 v72, v108, v74, -v58
	v_fmac_f32_e32 v73, v108, v71
	v_mul_f32_e32 v58, v75, v73
	v_mul_f32_e32 v59, v68, v73
	v_fmac_f32_e32 v58, v68, v72
	v_fma_f32 v59, v75, v72, -v59
	ds_write_b64 v91, v[58:59] offset:80
	v_mul_f32_e32 v58, v109, v73
	v_mul_f32_e32 v71, v109, v72
	v_fma_f32 v68, v108, v72, -v58
	v_fmac_f32_e32 v71, v108, v73
	v_mul_f32_e32 v58, v69, v71
	v_mul_f32_e32 v59, v66, v71
	v_fmac_f32_e32 v58, v66, v68
	v_fma_f32 v59, v69, v68, -v59
	ds_write_b64 v91, v[58:59] offset:88
	v_mul_f32_e32 v58, v109, v71
	v_fma_f32 v66, v108, v68, -v58
	v_mul_f32_e32 v68, v109, v68
	v_fmac_f32_e32 v68, v108, v71
	v_mul_f32_e32 v58, v70, v68
	v_mul_f32_e32 v59, v65, v68
	v_fmac_f32_e32 v58, v65, v66
	v_fma_f32 v59, v70, v66, -v59
	ds_write_b64 v91, v[58:59] offset:96
	v_mul_f32_e32 v58, v109, v68
	v_fma_f32 v65, v108, v66, -v58
	v_mul_f32_e32 v66, v109, v66
	v_fmac_f32_e32 v66, v108, v68
	v_mul_f32_e32 v58, v61, v66
	v_mul_f32_e32 v59, v67, v66
	v_fmac_f32_e32 v58, v67, v65
	v_fma_f32 v59, v61, v65, -v59
	ds_write_b64 v91, v[58:59] offset:104
	v_mul_f32_e32 v58, v109, v66
	v_fma_f32 v61, v108, v65, -v58
	v_mul_f32_e32 v65, v109, v65
	v_fmac_f32_e32 v65, v108, v66
	v_mul_f32_e32 v58, v64, v65
	v_mul_f32_e32 v59, v63, v65
	v_fmac_f32_e32 v58, v63, v61
	v_fma_f32 v59, v64, v61, -v59
	ds_write_b64 v91, v[58:59] offset:112
	v_mul_f32_e32 v58, v109, v65
	v_fma_f32 v59, v108, v61, -v58
	v_mul_f32_e32 v61, v109, v61
	v_fmac_f32_e32 v61, v108, v65
	v_mul_f32_e32 v58, v62, v61
	v_fmac_f32_e32 v58, v60, v59
	v_mul_f32_e32 v60, v60, v61
	v_fma_f32 v59, v62, v59, -v60
	ds_write_b64 v91, v[58:59] offset:120
	s_waitcnt lgkmcnt(0)
	s_barrier
	ds_read2_b64 v[58:61], v90 offset1:17
	ds_read2_b64 v[62:65], v90 offset0:34 offset1:51
	ds_read2_b64 v[66:69], v90 offset0:68 offset1:85
	ds_read2_b64 v[70:73], v90 offset0:136 offset1:153
	ds_read2_b64 v[74:77], v90 offset0:102 offset1:119
	ds_read2_b64 v[100:103], v90 offset0:170 offset1:187
	ds_read2_b64 v[104:107], v90 offset0:204 offset1:221
	ds_read2_b64 v[108:111], v90 offset0:238 offset1:255
	s_waitcnt lgkmcnt(4)
	v_add_f32_e32 v99, v58, v70
	v_add_f32_e32 v112, v59, v71
	v_sub_f32_e32 v58, v58, v70
	v_sub_f32_e32 v59, v59, v71
	s_waitcnt lgkmcnt(1)
	v_add_f32_e32 v70, v66, v104
	v_add_f32_e32 v71, v67, v105
	v_sub_f32_e32 v66, v66, v104
	v_sub_f32_e32 v67, v67, v105
	v_add_f32_e32 v104, v99, v70
	v_add_f32_e32 v105, v112, v71
	v_sub_f32_e32 v70, v99, v70
	v_sub_f32_e32 v71, v112, v71
	v_sub_f32_e32 v99, v58, v67
	v_add_f32_e32 v112, v59, v66
	v_add_f32_e32 v58, v58, v67
	v_sub_f32_e32 v59, v59, v66
	v_add_f32_e32 v66, v60, v72
	v_add_f32_e32 v67, v61, v73
	v_sub_f32_e32 v60, v60, v72
	v_sub_f32_e32 v61, v61, v73
	v_add_f32_e32 v72, v68, v106
	v_add_f32_e32 v73, v69, v107
	v_sub_f32_e32 v68, v68, v106
	v_sub_f32_e32 v69, v69, v107
	v_add_f32_e32 v106, v66, v72
	v_add_f32_e32 v107, v67, v73
	v_sub_f32_e32 v66, v66, v72
	v_sub_f32_e32 v67, v67, v73
	v_sub_f32_e32 v72, v60, v69
	v_add_f32_e32 v73, v61, v68
	v_add_f32_e32 v60, v60, v69
	v_sub_f32_e32 v61, v61, v68
	v_add_f32_e32 v68, v62, v100
	v_add_f32_e32 v69, v63, v101
	v_sub_f32_e32 v62, v62, v100
	v_sub_f32_e32 v63, v63, v101
	s_waitcnt lgkmcnt(0)
	v_add_f32_e32 v100, v74, v108
	v_add_f32_e32 v101, v75, v109
	v_sub_f32_e32 v74, v74, v108
	v_sub_f32_e32 v75, v75, v109
	v_add_f32_e32 v108, v68, v100
	v_add_f32_e32 v109, v69, v101
	v_sub_f32_e32 v68, v68, v100
	v_sub_f32_e32 v69, v69, v101
	v_sub_f32_e32 v100, v62, v75
	v_add_f32_e32 v101, v63, v74
	v_add_f32_e32 v62, v62, v75
	v_sub_f32_e32 v63, v63, v74
	v_add_f32_e32 v74, v64, v102
	v_add_f32_e32 v75, v65, v103
	v_sub_f32_e32 v64, v64, v102
	v_sub_f32_e32 v65, v65, v103
	v_add_f32_e32 v102, v76, v110
	v_add_f32_e32 v103, v77, v111
	v_sub_f32_e32 v76, v76, v110
	v_sub_f32_e32 v77, v77, v111
	v_add_f32_e32 v111, v75, v103
	v_sub_f32_e32 v75, v75, v103
	v_add_f32_e32 v103, v65, v76
	v_sub_f32_e32 v65, v65, v76
	v_mul_f32_e32 v76, 0xbec3ef15, v73
	v_fmac_f32_e32 v76, 0x3f6c835e, v72
	v_mul_f32_e32 v72, 0x3ec3ef15, v72
	v_add_f32_e32 v110, v74, v102
	v_sub_f32_e32 v74, v74, v102
	v_sub_f32_e32 v102, v64, v77
	v_fmac_f32_e32 v72, 0x3f6c835e, v73
	v_mul_f32_e32 v73, 0x3f3504f3, v100
	v_mul_f32_e32 v100, 0xbf6c835e, v103
	v_mul_f32_e32 v67, 0x3f3504f3, v67
	v_add_f32_e32 v64, v64, v77
	v_fmamk_f32 v77, v101, 0xbf3504f3, v73
	v_fmac_f32_e32 v73, 0x3f3504f3, v101
	v_fmac_f32_e32 v100, 0x3ec3ef15, v102
	v_mul_f32_e32 v101, 0x3f6c835e, v102
	v_fma_f32 v102, v66, s72, -v67
	v_fmac_f32_e32 v67, 0x3f3504f3, v66
	v_fma_f32 v66, v68, 0, -v69
	v_fmac_f32_e32 v68, 0, v69
	v_mul_f32_e32 v69, 0xbf3504f3, v75
	v_fmamk_f32 v75, v74, 0xbf3504f3, v69
	v_fmac_f32_e32 v69, 0x3f3504f3, v74
	v_mul_f32_e32 v74, 0xbf6c835e, v61
	v_fmac_f32_e32 v74, 0x3ec3ef15, v60
	v_mul_f32_e32 v60, 0x3f6c835e, v60
	v_fmac_f32_e32 v60, 0x3ec3ef15, v61
	v_mul_f32_e32 v61, 0xbf3504f3, v63
	v_fmamk_f32 v63, v62, 0xbf3504f3, v61
	v_fmac_f32_e32 v61, 0x3f3504f3, v62
	v_mul_f32_e32 v62, 0xbf6c835e, v64
	v_mul_f32_e32 v64, 0xbec3ef15, v64
	v_fmac_f32_e32 v101, 0x3ec3ef15, v103
	v_fmac_f32_e32 v62, 0x3ec3ef15, v65
	v_fmac_f32_e32 v64, 0xbf6c835e, v65
	v_add_f32_e32 v65, v104, v108
	v_add_f32_e32 v103, v105, v109
	v_sub_f32_e32 v104, v104, v108
	v_sub_f32_e32 v105, v105, v109
	v_add_f32_e32 v108, v106, v110
	v_add_f32_e32 v109, v107, v111
	v_sub_f32_e32 v106, v106, v110
	v_sub_f32_e32 v107, v107, v111
	v_add_f32_e32 v110, v108, v65
	v_add_f32_e32 v111, v109, v103
	v_sub_f32_e32 v65, v65, v108
	v_sub_f32_e32 v103, v103, v109
	v_sub_f32_e32 v108, v104, v107
	v_add_f32_e32 v109, v106, v105
	v_add_f32_e32 v104, v104, v107
	v_sub_f32_e32 v105, v105, v106
	v_add_f32_e32 v106, v99, v77
	v_add_f32_e32 v107, v112, v73
	v_sub_f32_e32 v77, v99, v77
	v_sub_f32_e32 v73, v112, v73
	v_add_f32_e32 v99, v76, v100
	v_add_f32_e32 v112, v72, v101
	v_sub_f32_e32 v76, v76, v100
	v_sub_f32_e32 v72, v72, v101
	v_add_f32_e32 v100, v99, v106
	v_add_f32_e32 v101, v112, v107
	v_sub_f32_e32 v99, v106, v99
	v_sub_f32_e32 v106, v107, v112
	v_sub_f32_e32 v107, v77, v72
	v_add_f32_e32 v112, v76, v73
	v_add_f32_e32 v72, v72, v77
	v_sub_f32_e32 v73, v73, v76
	v_add_f32_e32 v76, v70, v66
	v_add_f32_e32 v77, v71, v68
	v_sub_f32_e32 v66, v70, v66
	v_sub_f32_e32 v68, v71, v68
	v_add_f32_e32 v70, v102, v75
	v_add_f32_e32 v71, v67, v69
	v_sub_f32_e32 v75, v102, v75
	v_sub_f32_e32 v67, v67, v69
	v_add_f32_e32 v69, v76, v70
	v_add_f32_e32 v102, v71, v77
	v_sub_f32_e32 v70, v76, v70
	v_sub_f32_e32 v71, v77, v71
	v_sub_f32_e32 v76, v66, v67
	v_add_f32_e32 v77, v75, v68
	v_add_f32_e32 v66, v66, v67
	v_sub_f32_e32 v67, v68, v75
	v_add_f32_e32 v68, v58, v63
	v_add_f32_e32 v75, v59, v61
	v_sub_f32_e32 v58, v58, v63
	v_sub_f32_e32 v59, v59, v61
	v_add_f32_e32 v61, v74, v62
	v_add_f32_e32 v63, v60, v64
	v_sub_f32_e32 v62, v74, v62
	v_sub_f32_e32 v60, v60, v64
	v_add_f32_e32 v64, v61, v68
	v_add_f32_e32 v74, v63, v75
	v_sub_f32_e32 v61, v68, v61
	v_sub_f32_e32 v63, v75, v63
	v_sub_f32_e32 v68, v58, v60
	v_add_f32_e32 v75, v62, v59
	v_add_f32_e32 v60, v60, v58
	v_sub_f32_e32 v62, v59, v62
	v_mul_f32_e32 v58, v57, v111
	v_mul_f32_e32 v59, v57, v110
	v_fmac_f32_e32 v58, v56, v110
	v_fma_f32 v59, v56, v111, -v59
	v_mul_f32_e32 v110, v57, v55
	v_mul_f32_e32 v111, v56, v55
	v_fma_f32 v110, v56, v54, -v110
	v_fmac_f32_e32 v111, v57, v54
	v_mul_f32_e32 v56, v110, v100
	v_mul_f32_e32 v57, v111, v100
	v_fmac_f32_e32 v56, v111, v101
	v_fma_f32 v57, v110, v101, -v57
	ds_write2_b64 v90, v[58:59], v[56:57] offset1:17
	v_mul_f32_e32 v59, v55, v110
	v_mul_f32_e32 v56, v55, v111
	v_fmac_f32_e32 v59, v54, v111
	v_fma_f32 v58, v54, v110, -v56
	v_mul_f32_e32 v56, v59, v102
	v_fmac_f32_e32 v56, v58, v69
	v_mul_f32_e32 v57, v59, v69
	v_mul_f32_e32 v69, v55, v59
	v_mul_f32_e32 v100, v55, v58
	v_fma_f32 v69, v54, v58, -v69
	v_fmac_f32_e32 v100, v54, v59
	v_fma_f32 v57, v58, v102, -v57
	v_mul_f32_e32 v58, v69, v64
	v_mul_f32_e32 v59, v100, v64
	v_fmac_f32_e32 v58, v100, v74
	v_fma_f32 v59, v69, v74, -v59
	ds_write2_b64 v90, v[56:57], v[58:59] offset0:34 offset1:51
	v_mul_f32_e32 v56, v55, v100
	v_mul_f32_e32 v59, v55, v69
	v_fma_f32 v58, v54, v69, -v56
	v_fmac_f32_e32 v59, v54, v100
	v_mul_f32_e32 v64, v55, v59
	v_mul_f32_e32 v69, v55, v58
	v_mul_f32_e32 v56, v59, v109
	v_mul_f32_e32 v57, v59, v108
	v_fma_f32 v64, v54, v58, -v64
	v_fmac_f32_e32 v69, v54, v59
	v_fmac_f32_e32 v56, v58, v108
	v_fma_f32 v57, v58, v109, -v57
	v_mul_f32_e32 v58, v64, v107
	v_mul_f32_e32 v59, v69, v107
	v_fmac_f32_e32 v58, v69, v112
	v_fma_f32 v59, v64, v112, -v59
	ds_write2_b64 v90, v[56:57], v[58:59] offset0:68 offset1:85
	v_mul_f32_e32 v56, v55, v69
	v_mul_f32_e32 v59, v55, v64
	v_fma_f32 v58, v54, v64, -v56
	v_fmac_f32_e32 v59, v54, v69
	v_mul_f32_e32 v64, v55, v59
	v_mul_f32_e32 v69, v55, v58
	v_mul_f32_e32 v56, v59, v77
	v_mul_f32_e32 v57, v59, v76
	v_fma_f32 v64, v54, v58, -v64
	v_fmac_f32_e32 v69, v54, v59
	v_fmac_f32_e32 v56, v58, v76
	v_fma_f32 v57, v58, v77, -v57
	v_mul_f32_e32 v58, v64, v68
	v_mul_f32_e32 v59, v69, v68
	v_fmac_f32_e32 v58, v69, v75
	v_fma_f32 v59, v64, v75, -v59
	ds_write2_b64 v90, v[56:57], v[58:59] offset0:102 offset1:119
	v_mul_f32_e32 v56, v55, v69
	v_mul_f32_e32 v59, v55, v64
	v_fma_f32 v58, v54, v64, -v56
	v_fmac_f32_e32 v59, v54, v69
	v_mul_f32_e32 v56, v59, v103
	v_fmac_f32_e32 v56, v58, v65
	v_mul_f32_e32 v57, v59, v65
	v_mul_f32_e32 v64, v55, v59
	v_mul_f32_e32 v65, v55, v58
	v_fma_f32 v64, v54, v58, -v64
	v_fmac_f32_e32 v65, v54, v59
	v_fma_f32 v57, v58, v103, -v57
	v_mul_f32_e32 v58, v64, v99
	v_mul_f32_e32 v59, v65, v99
	v_fmac_f32_e32 v58, v65, v106
	v_fma_f32 v59, v64, v106, -v59
	ds_write2_b64 v90, v[56:57], v[58:59] offset0:136 offset1:153
	v_mul_f32_e32 v56, v55, v65
	v_mul_f32_e32 v59, v55, v64
	v_fma_f32 v58, v54, v64, -v56
	v_fmac_f32_e32 v59, v54, v65
	v_mul_f32_e32 v64, v55, v59
	v_mul_f32_e32 v65, v55, v58
	v_mul_f32_e32 v56, v59, v71
	v_mul_f32_e32 v57, v59, v70
	v_fma_f32 v64, v54, v58, -v64
	v_fmac_f32_e32 v65, v54, v59
	v_fmac_f32_e32 v56, v58, v70
	v_fma_f32 v57, v58, v71, -v57
	v_mul_f32_e32 v58, v64, v61
	v_mul_f32_e32 v59, v65, v61
	v_fmac_f32_e32 v58, v65, v63
	v_fma_f32 v59, v64, v63, -v59
	ds_write2_b64 v90, v[56:57], v[58:59] offset0:170 offset1:187
	v_mul_f32_e32 v56, v55, v65
	v_mul_f32_e32 v59, v55, v64
	v_fma_f32 v58, v54, v64, -v56
	v_fmac_f32_e32 v59, v54, v65
	v_mul_f32_e32 v61, v55, v59
	v_mul_f32_e32 v63, v55, v58
	v_mul_f32_e32 v56, v59, v105
	v_mul_f32_e32 v57, v59, v104
	v_fma_f32 v61, v54, v58, -v61
	v_fmac_f32_e32 v63, v54, v59
	v_fmac_f32_e32 v56, v58, v104
	v_fma_f32 v57, v58, v105, -v57
	v_mul_f32_e32 v58, v61, v72
	v_mul_f32_e32 v59, v63, v72
	v_fmac_f32_e32 v58, v63, v73
	v_fma_f32 v59, v61, v73, -v59
	ds_write2_b64 v90, v[56:57], v[58:59] offset0:204 offset1:221
	v_mul_f32_e32 v59, v55, v61
	v_mul_f32_e32 v56, v55, v63
	v_fmac_f32_e32 v59, v54, v63
	v_fma_f32 v58, v54, v61, -v56
	v_mul_f32_e32 v61, v55, v59
	v_fma_f32 v61, v54, v58, -v61
	v_mul_f32_e32 v55, v55, v58
	v_fmac_f32_e32 v55, v54, v59
	v_mul_f32_e32 v54, v61, v60
	v_mul_f32_e32 v56, v59, v67
	v_mul_f32_e32 v57, v59, v66
	v_fmac_f32_e32 v54, v55, v62
	v_mul_f32_e32 v55, v55, v60
	v_fmac_f32_e32 v56, v58, v66
	v_fma_f32 v57, v58, v67, -v57
	v_fma_f32 v55, v61, v62, -v55
	ds_write2_b64 v90, v[56:57], v[54:55] offset0:238 offset1:255
	s_waitcnt lgkmcnt(0)
	s_barrier
	ds_read_b64 v[54:55], v89
	ds_read_b64 v[56:57], v89 offset:2176
	ds_read_b64 v[58:59], v89 offset:4352
	ds_read_b64 v[60:61], v89 offset:6528
	ds_read_b64 v[62:63], v89 offset:8704
	ds_read_b64 v[64:65], v89 offset:10880
	ds_read_b64 v[66:67], v89 offset:13056
	ds_read_b64 v[68:69], v89 offset:15232
	ds_read_b64 v[70:71], v89 offset:17408
	ds_read_b64 v[72:73], v89 offset:19584
	ds_read_b64 v[74:75], v89 offset:21760
	ds_read_b64 v[76:77], v89 offset:23936
	ds_read_b64 v[100:101], v89 offset:26112
	ds_read_b64 v[102:103], v89 offset:28288
	ds_read_b64 v[104:105], v89 offset:30464
	ds_read_b64 v[106:107], v89 offset:32640
	s_waitcnt lgkmcnt(7)
	v_add_f32_e32 v99, v54, v70
	v_add_f32_e32 v108, v55, v71
	v_sub_f32_e32 v54, v54, v70
	v_sub_f32_e32 v55, v55, v71
	s_waitcnt lgkmcnt(3)
	v_add_f32_e32 v70, v62, v100
	v_add_f32_e32 v71, v63, v101
	v_sub_f32_e32 v62, v62, v100
	v_sub_f32_e32 v63, v63, v101
	v_add_f32_e32 v100, v99, v70
	v_add_f32_e32 v101, v108, v71
	v_sub_f32_e32 v70, v99, v70
	v_sub_f32_e32 v71, v108, v71
	v_sub_f32_e32 v99, v54, v63
	v_add_f32_e32 v108, v55, v62
	v_add_f32_e32 v109, v54, v63
	v_sub_f32_e32 v110, v55, v62
	v_add_f32_e32 v54, v56, v72
	v_add_f32_e32 v55, v57, v73
	v_sub_f32_e32 v56, v56, v72
	v_sub_f32_e32 v57, v57, v73
	s_waitcnt lgkmcnt(2)
	v_add_f32_e32 v62, v64, v102
	v_add_f32_e32 v63, v65, v103
	v_sub_f32_e32 v64, v64, v102
	v_sub_f32_e32 v65, v65, v103
	v_add_f32_e32 v72, v54, v62
	v_add_f32_e32 v73, v55, v63
	v_sub_f32_e32 v62, v54, v62
	v_sub_f32_e32 v63, v55, v63
	v_sub_f32_e32 v102, v56, v65
	v_add_f32_e32 v103, v57, v64
	v_add_f32_e32 v65, v56, v65
	v_sub_f32_e32 v64, v57, v64
	v_add_f32_e32 v54, v58, v74
	v_add_f32_e32 v55, v59, v75
	v_sub_f32_e32 v56, v58, v74
	v_sub_f32_e32 v57, v59, v75
	s_waitcnt lgkmcnt(1)
	v_add_f32_e32 v58, v66, v104
	v_add_f32_e32 v59, v67, v105
	v_sub_f32_e32 v66, v66, v104
	v_sub_f32_e32 v67, v67, v105
	v_add_f32_e32 v74, v58, v54
	v_add_f32_e32 v75, v59, v55
	v_sub_f32_e32 v104, v54, v58
	v_sub_f32_e32 v58, v55, v59
	v_sub_f32_e32 v59, v56, v67
	v_add_f32_e32 v105, v66, v57
	v_add_f32_e32 v67, v56, v67
	v_sub_f32_e32 v66, v57, v66
	v_add_f32_e32 v112, v61, v77
	v_pk_mov_b32 v[54:55], v[60:61], v[68:69] op_sel:[1,0]
	s_waitcnt lgkmcnt(0)
	v_pk_mov_b32 v[56:57], v[76:77], v[106:107] op_sel:[1,0]
	v_mov_b32_e32 v61, v69
	v_mov_b32_e32 v77, v107
	v_add_f32_e32 v113, v68, v106
	v_add_f32_e32 v114, v69, v107
	v_pk_add_f32 v[54:55], v[54:55], v[56:57] neg_lo:[0,1] neg_hi:[0,1]
	v_pk_add_f32 v[56:57], v[60:61], v[76:77] neg_lo:[0,1] neg_hi:[0,1]
	v_mul_f32_e32 v106, 0xbec3ef15, v103
	v_add_f32_e32 v111, v60, v76
	v_add_f32_e32 v61, v112, v114
	v_sub_f32_e32 v69, v112, v114
	v_sub_f32_e32 v76, v56, v57
	v_add_f32_e32 v77, v54, v55
	v_pk_add_f32 v[56:57], v[56:57], v[56:57] op_sel_hi:[0,1]
	v_pk_add_f32 v[54:55], v[54:55], v[54:55] op_sel:[0,1] op_sel_hi:[1,0] neg_lo:[0,1] neg_hi:[0,1]
	v_fmac_f32_e32 v106, 0x3f6c835e, v102
	v_mul_f32_e32 v102, 0x3ec3ef15, v102
	v_mul_f32_e32 v112, 0x3f6c835e, v65
	v_add_f32_e32 v60, v111, v113
	v_sub_f32_e32 v68, v111, v113
	v_fmac_f32_e32 v102, 0x3f6c835e, v103
	v_mul_f32_e32 v103, 0x3f3504f3, v63
	v_mul_f32_e32 v111, 0xbf6c835e, v64
	v_fmac_f32_e32 v112, 0x3ec3ef15, v64
	v_mul_f32_e32 v64, 0xbf6c835e, v77
	v_mov_b32_e32 v55, v57
	v_fma_f32 v107, v62, s72, -v103
	v_fmac_f32_e32 v103, 0x3f3504f3, v62
	v_fmac_f32_e32 v111, 0x3ec3ef15, v65
	v_mul_f32_e32 v62, 0x3f3504f3, v105
	v_mul_f32_e32 v113, 0xbf3504f3, v66
	v_fmac_f32_e32 v64, 0x3ec3ef15, v76
	v_mul_f32_e32 v65, 0x3f6c835e, v76
	v_mul_f32_e32 v76, 0xbf3504f3, v69
	v_pk_mul_f32 v[56:57], v[54:55], s[80:81]
	v_fma_f32 v63, v59, s72, -v62
	v_fmac_f32_e32 v62, 0x3f3504f3, v59
	v_fma_f32 v105, v104, 0, -v58
	v_fmac_f32_e32 v104, 0, v58
	v_fmamk_f32 v114, v67, 0xbf3504f3, v113
	v_fmac_f32_e32 v113, 0x3f3504f3, v67
	v_fmac_f32_e32 v65, 0x3ec3ef15, v77
	v_fmamk_f32 v77, v68, 0xbf3504f3, v76
	v_fmac_f32_e32 v76, 0x3f3504f3, v68
	v_sub_f32_e32 v115, v56, v57
	v_pk_mul_f32 v[54:55], v[54:55], s[78:79]
	v_add_f32_e32 v56, v100, v74
	v_add_f32_e32 v57, v101, v75
	v_sub_f32_e32 v66, v100, v74
	v_sub_f32_e32 v67, v101, v75
	v_add_f32_e32 v58, v72, v60
	v_add_f32_e32 v59, v73, v61
	v_sub_f32_e32 v68, v72, v60
	v_sub_f32_e32 v60, v73, v61
	v_sub_f32_e32 v116, v54, v55
	v_add_f32_e32 v54, v56, v58
	v_add_f32_e32 v55, v57, v59
	v_sub_f32_e32 v56, v56, v58
	v_sub_f32_e32 v57, v57, v59
	v_sub_f32_e32 v58, v66, v60
	v_add_f32_e32 v59, v67, v68
	v_add_f32_e32 v60, v66, v60
	v_sub_f32_e32 v61, v67, v68
	v_add_f32_e32 v66, v99, v63
	v_add_f32_e32 v67, v108, v62
	v_sub_f32_e32 v68, v99, v63
	v_sub_f32_e32 v69, v108, v62
	v_add_f32_e32 v72, v106, v64
	v_add_f32_e32 v73, v102, v65
	v_sub_f32_e32 v74, v106, v64
	v_sub_f32_e32 v75, v102, v65
	v_add_f32_e32 v62, v66, v72
	v_add_f32_e32 v63, v67, v73
	v_sub_f32_e32 v64, v66, v72
	v_sub_f32_e32 v65, v67, v73
	v_sub_f32_e32 v66, v68, v75
	v_add_f32_e32 v67, v69, v74
	v_add_f32_e32 v68, v68, v75
	v_sub_f32_e32 v69, v69, v74
	v_add_f32_e32 v73, v71, v104
	v_sub_f32_e32 v100, v71, v104
	v_add_f32_e32 v74, v107, v77
	v_add_f32_e32 v75, v103, v76
	v_sub_f32_e32 v77, v107, v77
	v_add_f32_e32 v72, v70, v105
	v_sub_f32_e32 v99, v70, v105
	v_sub_f32_e32 v76, v103, v76
	v_add_f32_e32 v71, v73, v75
	v_sub_f32_e32 v73, v73, v75
	v_add_f32_e32 v75, v100, v77
	v_sub_f32_e32 v77, v100, v77
	v_add_f32_e32 v100, v109, v114
	v_add_f32_e32 v103, v110, v113
	v_add_f32_e32 v102, v111, v115
	v_add_f32_e32 v101, v112, v116
	v_add_f32_e32 v70, v72, v74
	v_sub_f32_e32 v72, v72, v74
	v_sub_f32_e32 v74, v99, v76
	v_add_f32_e32 v76, v99, v76
	v_sub_f32_e32 v99, v109, v114
	v_sub_f32_e32 v109, v110, v113
	v_sub_f32_e32 v110, v111, v115
	v_sub_f32_e32 v108, v112, v116
	s_barrier
	ds_write2st64_b64 v88, v[54:55], v[62:63] offset0:68 offset1:72
	v_pk_add_f32 v[54:55], v[102:103], v[100:101]
	v_sub_f32_e32 v104, v100, v102
	v_sub_f32_e32 v105, v103, v101
	v_sub_f32_e32 v106, v99, v108
	v_add_f32_e32 v107, v109, v110
	v_add_f32_e32 v108, v99, v108
	v_sub_f32_e32 v109, v109, v110
	ds_write2st64_b64 v88, v[70:71], v[54:55] offset0:76 offset1:80
	ds_write2st64_b64 v88, v[58:59], v[66:67] offset0:84 offset1:88
	ds_write2st64_b64 v88, v[74:75], v[106:107] offset0:92 offset1:96
	ds_write2st64_b64 v88, v[56:57], v[64:65] offset0:100 offset1:104
	ds_write2st64_b64 v88, v[72:73], v[104:105] offset0:108 offset1:112
	ds_write2st64_b64 v88, v[60:61], v[68:69] offset0:116 offset1:120
	ds_write_b64 v88, v[76:77] offset:63488
	ds_write_b64 v98, v[108:109] offset:30720
	v_mov_b32_e32 v54, v86
	v_mov_b32_e32 v55, v87
	v_mov_b32_e32 v109, v82
	v_mul_f32_e32 v56, v51, v55
	v_mul_f32_e32 v57, v50, v55
	v_mul_f32_e32 v58, 0x3e47c5c2, v55
	v_fma_f32 v56, v50, v54, -v56
	v_fmac_f32_e32 v57, v51, v54
	v_fmac_f32_e32 v58, 0x3f7b14be, v54
	v_mul_f32_e32 v54, 0x3e47c5c2, v54
	v_fma_f32 v54, v55, s76, -v54
	v_mul_f32_e32 v55, v49, v54
	v_fma_f32 v59, v48, v58, -v55
	v_mul_f32_e32 v55, 0x3e47c5c2, v54
	v_mul_f32_e32 v60, v49, v58
	v_fmac_f32_e32 v55, 0x3f7b14be, v58
	v_mul_f32_e32 v58, 0x3e47c5c2, v58
	v_fmac_f32_e32 v60, v48, v54
	v_fma_f32 v54, v54, s76, -v58
	v_mul_f32_e32 v58, v47, v54
	v_mul_f32_e32 v62, 0x3e47c5c2, v54
	v_fma_f32 v58, v46, v55, -v58
	v_mul_f32_e32 v61, v47, v55
	v_fmac_f32_e32 v62, 0x3f7b14be, v55
	v_mul_f32_e32 v55, 0x3e47c5c2, v55
	v_fmac_f32_e32 v61, v46, v54
	v_fma_f32 v54, v54, s76, -v55
	v_mul_f32_e32 v55, v45, v54
	v_fma_f32 v63, v44, v62, -v55
	v_mul_f32_e32 v55, 0x3e47c5c2, v54
	v_mul_f32_e32 v64, v45, v62
	v_fmac_f32_e32 v55, 0x3f7b14be, v62
	v_mul_f32_e32 v62, 0x3e47c5c2, v62
	v_fmac_f32_e32 v64, v44, v54
	v_fma_f32 v54, v54, s76, -v62
	v_mul_f32_e32 v62, v41, v54
	v_mul_f32_e32 v66, 0x3e47c5c2, v54
	v_fma_f32 v62, v40, v55, -v62
	v_mul_f32_e32 v65, v41, v55
	v_fmac_f32_e32 v66, 0x3f7b14be, v55
	v_mul_f32_e32 v55, 0x3e47c5c2, v55
	v_fmac_f32_e32 v65, v40, v54
	v_fma_f32 v54, v54, s76, -v55
	v_mul_f32_e32 v55, v39, v54
	v_fma_f32 v67, v38, v66, -v55
	v_mul_f32_e32 v55, 0x3e47c5c2, v54
	v_mul_f32_e32 v68, v39, v66
	v_fmac_f32_e32 v55, 0x3f7b14be, v66
	v_mul_f32_e32 v66, 0x3e47c5c2, v66
	v_fmac_f32_e32 v68, v38, v54
	v_fma_f32 v54, v54, s76, -v66
	v_mul_f32_e32 v66, v37, v54
	v_mul_f32_e32 v70, 0x3e47c5c2, v54
	v_fma_f32 v66, v36, v55, -v66
	v_mul_f32_e32 v69, v37, v55
	v_fmac_f32_e32 v70, 0x3f7b14be, v55
	v_mul_f32_e32 v55, 0x3e47c5c2, v55
	v_fmac_f32_e32 v69, v36, v54
	v_fma_f32 v54, v54, s76, -v55
	v_mul_f32_e32 v55, v31, v54
	v_fma_f32 v71, v30, v70, -v55
	v_mul_f32_e32 v55, 0x3e47c5c2, v54
	v_mul_f32_e32 v72, v31, v70
	v_fmac_f32_e32 v55, 0x3f7b14be, v70
	v_mul_f32_e32 v70, 0x3e47c5c2, v70
	v_fmac_f32_e32 v72, v30, v54
	v_fma_f32 v54, v54, s76, -v70
	v_mul_f32_e32 v70, v29, v54
	v_mul_f32_e32 v74, 0x3e47c5c2, v54
	v_fma_f32 v70, v28, v55, -v70
	v_mul_f32_e32 v73, v29, v55
	v_fmac_f32_e32 v74, 0x3f7b14be, v55
	v_mul_f32_e32 v55, 0x3e47c5c2, v55
	v_fmac_f32_e32 v73, v28, v54
	v_fma_f32 v54, v54, s76, -v55
	v_mul_f32_e32 v55, v33, v54
	v_fma_f32 v75, v32, v74, -v55
	v_mul_f32_e32 v55, 0x3e47c5c2, v54
	v_mul_f32_e32 v76, v33, v74
	v_fmac_f32_e32 v55, 0x3f7b14be, v74
	v_mul_f32_e32 v74, 0x3e47c5c2, v74
	v_fmac_f32_e32 v76, v32, v54
	v_fma_f32 v54, v54, s76, -v74
	v_mul_f32_e32 v74, v27, v54
	v_mul_f32_e32 v99, 0x3e47c5c2, v54
	v_fma_f32 v74, v26, v55, -v74
	v_mul_f32_e32 v77, v27, v55
	v_fmac_f32_e32 v99, 0x3f7b14be, v55
	v_mul_f32_e32 v55, 0x3e47c5c2, v55
	v_fmac_f32_e32 v77, v26, v54
	v_fma_f32 v54, v54, s76, -v55
	v_mul_f32_e32 v55, v23, v54
	v_fma_f32 v100, v22, v99, -v55
	v_mul_f32_e32 v55, 0x3e47c5c2, v54
	v_mul_f32_e32 v101, v23, v99
	v_fmac_f32_e32 v55, 0x3f7b14be, v99
	v_mul_f32_e32 v99, 0x3e47c5c2, v99
	v_fmac_f32_e32 v101, v22, v54
	v_fma_f32 v54, v54, s76, -v99
	v_mul_f32_e32 v99, v25, v54
	v_mul_f32_e32 v103, 0x3e47c5c2, v54
	v_fma_f32 v99, v24, v55, -v99
	v_mul_f32_e32 v102, v25, v55
	v_fmac_f32_e32 v103, 0x3f7b14be, v55
	v_mul_f32_e32 v55, 0x3e47c5c2, v55
	v_fmac_f32_e32 v102, v24, v54
	v_fma_f32 v54, v54, s76, -v55
	v_mul_f32_e32 v55, v35, v54
	v_fma_f32 v104, v34, v103, -v55
	v_mul_f32_e32 v55, 0x3e47c5c2, v54
	v_mul_f32_e32 v105, v35, v103
	v_fmac_f32_e32 v55, 0x3f7b14be, v103
	v_mul_f32_e32 v103, 0x3e47c5c2, v103
	v_fmac_f32_e32 v105, v34, v54
	v_fma_f32 v54, v54, s76, -v103
	v_mul_f32_e32 v103, v43, v54
	v_mul_f32_e32 v107, 0x3e47c5c2, v54
	v_fma_f32 v103, v42, v55, -v103
	v_mul_f32_e32 v106, v43, v55
	v_fmac_f32_e32 v107, 0x3f7b14be, v55
	v_mul_f32_e32 v55, 0x3e47c5c2, v55
	v_fmac_f32_e32 v106, v42, v54
	v_fma_f32 v54, v54, s76, -v55
	v_mul_f32_e32 v55, v53, v54
	v_add_f32_e32 v111, v56, v70
	v_add_f32_e32 v112, v57, v73
	v_sub_f32_e32 v56, v56, v70
	v_sub_f32_e32 v57, v57, v73
	v_add_f32_e32 v70, v62, v99
	v_add_f32_e32 v73, v65, v102
	v_sub_f32_e32 v62, v62, v99
	v_sub_f32_e32 v65, v65, v102
	v_fma_f32 v108, v52, v107, -v55
	v_mul_f32_e32 v107, v53, v107
	v_add_f32_e32 v99, v111, v70
	v_add_f32_e32 v102, v112, v73
	v_sub_f32_e32 v70, v111, v70
	v_sub_f32_e32 v73, v112, v73
	v_add_f32_e32 v111, v56, v65
	v_sub_f32_e32 v112, v57, v62
	v_sub_f32_e32 v56, v56, v65
	v_add_f32_e32 v62, v57, v62
	v_add_f32_e32 v57, v59, v75
	v_add_f32_e32 v65, v60, v76
	v_sub_f32_e32 v59, v59, v75
	v_sub_f32_e32 v60, v60, v76
	v_add_f32_e32 v75, v67, v104
	v_add_f32_e32 v76, v68, v105
	v_sub_f32_e32 v67, v67, v104
	v_sub_f32_e32 v68, v68, v105
	v_fmac_f32_e32 v107, v52, v54
	v_add_f32_e32 v104, v57, v75
	v_add_f32_e32 v105, v65, v76
	v_sub_f32_e32 v57, v57, v75
	v_sub_f32_e32 v65, v65, v76
	v_add_f32_e32 v75, v59, v68
	v_sub_f32_e32 v76, v60, v67
	v_sub_f32_e32 v59, v59, v68
	v_add_f32_e32 v60, v60, v67
	v_add_f32_e32 v67, v58, v74
	v_add_f32_e32 v68, v61, v77
	v_sub_f32_e32 v58, v58, v74
	v_sub_f32_e32 v61, v61, v77
	v_add_f32_e32 v74, v66, v103
	v_add_f32_e32 v77, v69, v106
	v_sub_f32_e32 v66, v66, v103
	v_sub_f32_e32 v69, v69, v106
	v_add_f32_e32 v103, v67, v74
	v_add_f32_e32 v106, v68, v77
	v_sub_f32_e32 v67, v67, v74
	v_sub_f32_e32 v68, v68, v77
	v_add_f32_e32 v74, v58, v69
	v_sub_f32_e32 v77, v61, v66
	v_sub_f32_e32 v58, v58, v69
	v_add_f32_e32 v61, v61, v66
	v_add_f32_e32 v66, v63, v100
	v_add_f32_e32 v69, v64, v101
	v_sub_f32_e32 v63, v63, v100
	v_sub_f32_e32 v64, v64, v101
	v_add_f32_e32 v100, v71, v108
	v_add_f32_e32 v101, v72, v107
	v_sub_f32_e32 v71, v71, v108
	v_sub_f32_e32 v72, v72, v107
	v_add_f32_e32 v107, v66, v100
	v_add_f32_e32 v108, v69, v101
	v_sub_f32_e32 v66, v66, v100
	v_sub_f32_e32 v69, v69, v101
	v_add_f32_e32 v100, v63, v72
	v_sub_f32_e32 v101, v64, v71
	v_sub_f32_e32 v63, v63, v72
	v_add_f32_e32 v64, v64, v71
	v_mul_f32_e32 v71, 0x3f6c835e, v75
	v_mul_f32_e32 v72, 0xbec3ef15, v75
	v_mul_f32_e32 v74, 0x3f3504f3, v74
	v_fmac_f32_e32 v71, 0x3ec3ef15, v76
	v_fmac_f32_e32 v72, 0x3f6c835e, v76
	v_fmamk_f32 v75, v77, 0x3f3504f3, v74
	v_fma_f32 v74, v77, s72, -v74
	v_mul_f32_e32 v76, 0x3ec3ef15, v100
	v_mul_f32_e32 v77, 0xbf6c835e, v100
	v_mul_f32_e32 v66, 0xbf3504f3, v66
	v_fmac_f32_e32 v76, 0x3f6c835e, v101
	v_fmac_f32_e32 v77, 0x3ec3ef15, v101
	v_fma_f32 v101, 0, v67, v68
	v_fma_f32 v67, v68, 0, -v67
	v_fmamk_f32 v68, v69, 0x3f3504f3, v66
	v_fmac_f32_e32 v66, 0xbf3504f3, v69
	v_mul_f32_e32 v69, 0x3ec3ef15, v59
	v_mul_f32_e32 v59, 0xbf6c835e, v59
	v_mul_f32_e32 v58, 0xbf3504f3, v58
	v_fmac_f32_e32 v69, 0x3f6c835e, v60
	v_fmac_f32_e32 v59, 0x3ec3ef15, v60
	v_fmamk_f32 v60, v61, 0x3f3504f3, v58
	v_fmac_f32_e32 v58, 0xbf3504f3, v61
	v_mul_f32_e32 v61, 0xbf6c835e, v63
	v_fmac_f32_e32 v61, 0xbec3ef15, v64
	v_mul_f32_e32 v64, 0xbf6c835e, v64
	v_mul_f32_e32 v57, 0x3f3504f3, v57
	v_fmac_f32_e32 v64, 0x3ec3ef15, v63
	v_add_f32_e32 v63, v99, v103
	v_add_f32_e32 v113, v102, v106
	v_sub_f32_e32 v99, v99, v103
	v_sub_f32_e32 v102, v102, v106
	v_add_f32_e32 v103, v104, v107
	v_add_f32_e32 v106, v105, v108
	v_sub_f32_e32 v104, v104, v107
	v_sub_f32_e32 v105, v105, v108
	v_fmamk_f32 v100, v65, 0x3f3504f3, v57
	v_fma_f32 v65, v65, s72, -v57
	v_add_f32_e32 v107, v63, v103
	v_add_f32_e32 v57, v113, v106
	v_sub_f32_e32 v63, v63, v103
	v_sub_f32_e32 v103, v113, v106
	v_add_f32_e32 v106, v99, v105
	v_sub_f32_e32 v108, v102, v104
	v_sub_f32_e32 v99, v99, v105
	v_add_f32_e32 v102, v102, v104
	v_add_f32_e32 v104, v111, v75
	v_add_f32_e32 v105, v112, v74
	v_sub_f32_e32 v75, v111, v75
	v_sub_f32_e32 v74, v112, v74
	v_add_f32_e32 v111, v71, v76
	v_add_f32_e32 v112, v72, v77
	v_sub_f32_e32 v71, v71, v76
	v_sub_f32_e32 v72, v72, v77
	v_add_f32_e32 v76, v104, v111
	v_add_f32_e32 v77, v105, v112
	v_sub_f32_e32 v104, v104, v111
	v_sub_f32_e32 v105, v105, v112
	v_add_f32_e32 v111, v75, v72
	v_sub_f32_e32 v112, v74, v71
	v_sub_f32_e32 v72, v75, v72
	v_add_f32_e32 v71, v74, v71
	v_add_f32_e32 v74, v70, v101
	v_add_f32_e32 v75, v73, v67
	v_sub_f32_e32 v70, v70, v101
	v_sub_f32_e32 v67, v73, v67
	v_add_f32_e32 v73, v100, v68
	v_add_f32_e32 v101, v65, v66
	v_sub_f32_e32 v68, v100, v68
	v_sub_f32_e32 v65, v65, v66
	v_mov_b32_e32 v110, v83
	v_mov_b32_e32 v54, v78
	v_mov_b32_e32 v55, v79
	v_add_f32_e32 v66, v74, v73
	v_add_f32_e32 v100, v75, v101
	v_sub_f32_e32 v73, v74, v73
	v_sub_f32_e32 v74, v75, v101
	v_add_f32_e32 v75, v70, v65
	v_sub_f32_e32 v101, v67, v68
	v_sub_f32_e32 v65, v70, v65
	v_add_f32_e32 v67, v67, v68
	v_add_f32_e32 v68, v56, v60
	v_add_f32_e32 v70, v62, v58
	v_sub_f32_e32 v56, v56, v60
	v_sub_f32_e32 v58, v62, v58
	v_add_f32_e32 v60, v69, v61
	v_add_f32_e32 v62, v59, v64
	v_sub_f32_e32 v61, v69, v61
	v_sub_f32_e32 v59, v59, v64
	v_add_f32_e32 v64, v68, v60
	v_add_f32_e32 v69, v70, v62
	v_sub_f32_e32 v60, v68, v60
	v_sub_f32_e32 v62, v70, v62
	v_add_f32_e32 v68, v56, v59
	v_sub_f32_e32 v70, v58, v61
	v_sub_f32_e32 v59, v56, v59
	v_add_f32_e32 v58, v58, v61
	v_fmamk_f32 v56, v57, 0x80000000, v107
	v_fmac_f32_e32 v57, 0, v107
	v_fma_f32 v107, 0, v109, v110
	ds_write_b64 v89, v[56:57]
	v_fmamk_f32 v61, v110, 0x80000000, v109
	v_mul_f32_e32 v56, v107, v77
	v_mul_f32_e32 v57, v107, v76
	v_fma_f32 v56, v61, v76, -v56
	v_fmac_f32_e32 v57, v61, v77
	ds_write_b64 v89, v[56:57] offset:2176
	v_mul_f32_e32 v56, v110, v107
	v_fma_f32 v76, v109, v61, -v56
	v_mul_f32_e32 v61, v110, v61
	v_fmac_f32_e32 v61, v109, v107
	v_mul_f32_e32 v56, v61, v100
	v_mul_f32_e32 v57, v61, v66
	v_fma_f32 v56, v76, v66, -v56
	v_fmac_f32_e32 v57, v76, v100
	ds_write_b64 v89, v[56:57] offset:4352
	v_mul_f32_e32 v56, v110, v61
	v_fma_f32 v66, v109, v76, -v56
	v_mul_f32_e32 v76, v110, v76
	v_fmac_f32_e32 v76, v109, v61
	v_mul_f32_e32 v56, v76, v69
	v_mul_f32_e32 v57, v76, v64
	v_fma_f32 v56, v66, v64, -v56
	v_fmac_f32_e32 v57, v66, v69
	ds_write_b64 v89, v[56:57] offset:6528
	v_mul_f32_e32 v56, v110, v76
	v_mul_f32_e32 v64, v110, v66
	v_fma_f32 v61, v109, v66, -v56
	v_fmac_f32_e32 v64, v109, v76
	v_mul_f32_e32 v56, v64, v108
	v_mul_f32_e32 v57, v61, v108
	v_fma_f32 v56, v61, v106, -v56
	v_fmac_f32_e32 v57, v64, v106
	ds_write_b64 v89, v[56:57] offset:8704
	v_mul_f32_e32 v56, v110, v64
	v_fma_f32 v66, v109, v61, -v56
	v_mul_f32_e32 v61, v110, v61
	v_fmac_f32_e32 v61, v109, v64
	v_mul_f32_e32 v56, v61, v112
	v_mul_f32_e32 v57, v61, v111
	v_fma_f32 v56, v66, v111, -v56
	v_fmac_f32_e32 v57, v66, v112
	ds_write_b64 v89, v[56:57] offset:10880
	v_mul_f32_e32 v56, v110, v61
	v_fma_f32 v64, v109, v66, -v56
	v_mul_f32_e32 v66, v110, v66
	v_fmac_f32_e32 v66, v109, v61
	v_mul_f32_e32 v56, v66, v101
	v_mul_f32_e32 v57, v66, v75
	v_fma_f32 v56, v64, v75, -v56
	v_fmac_f32_e32 v57, v64, v101
	ds_write_b64 v89, v[56:57] offset:13056
	v_mul_f32_e32 v56, v110, v66
	v_fma_f32 v61, v109, v64, -v56
	v_mul_f32_e32 v64, v110, v64
	v_fmac_f32_e32 v64, v109, v66
	v_mul_f32_e32 v56, v64, v70
	v_mul_f32_e32 v57, v64, v68
	v_fma_f32 v56, v61, v68, -v56
	v_fmac_f32_e32 v57, v61, v70
	ds_write_b64 v89, v[56:57] offset:15232
	v_mul_f32_e32 v56, v110, v64
	v_fma_f32 v66, v109, v61, -v56
	v_mul_f32_e32 v61, v110, v61
	v_fmac_f32_e32 v61, v109, v64
	v_mul_f32_e32 v56, v61, v103
	v_mul_f32_e32 v57, v66, v103
	v_fma_f32 v56, v66, v63, -v56
	v_fmac_f32_e32 v57, v61, v63
	v_mul_f32_e32 v64, v110, v66
	ds_write_b64 v89, v[56:57] offset:17408
	v_mul_f32_e32 v56, v110, v61
	v_fmac_f32_e32 v64, v109, v61
	v_fma_f32 v63, v109, v66, -v56
	v_mul_f32_e32 v56, v64, v105
	v_mul_f32_e32 v57, v64, v104
	v_fma_f32 v56, v63, v104, -v56
	v_fmac_f32_e32 v57, v63, v105
	ds_write_b64 v89, v[56:57] offset:19584
	v_mul_f32_e32 v56, v110, v64
	v_fma_f32 v61, v109, v63, -v56
	v_mul_f32_e32 v63, v110, v63
	v_fmac_f32_e32 v63, v109, v64
	v_mul_f32_e32 v56, v63, v74
	v_mul_f32_e32 v57, v63, v73
	v_fma_f32 v56, v61, v73, -v56
	v_fmac_f32_e32 v57, v61, v74
	ds_write_b64 v89, v[56:57] offset:21760
	v_mul_f32_e32 v56, v110, v63
	v_fma_f32 v64, v109, v61, -v56
	v_mul_f32_e32 v61, v110, v61
	v_fmac_f32_e32 v61, v109, v63
	v_mul_f32_e32 v56, v61, v62
	v_mul_f32_e32 v57, v61, v60
	v_fma_f32 v56, v64, v60, -v56
	v_fmac_f32_e32 v57, v64, v62
	ds_write_b64 v89, v[56:57] offset:23936
	v_mul_f32_e32 v56, v110, v61
	v_mul_f32_e32 v62, v110, v64
	v_fma_f32 v60, v109, v64, -v56
	v_fmac_f32_e32 v62, v109, v61
	v_mul_f32_e32 v56, v62, v102
	v_mul_f32_e32 v57, v60, v102
	v_fma_f32 v56, v60, v99, -v56
	v_fmac_f32_e32 v57, v62, v99
	ds_write_b64 v89, v[56:57] offset:26112
	v_mul_f32_e32 v56, v110, v62
	v_fma_f32 v61, v109, v60, -v56
	v_mul_f32_e32 v60, v110, v60
	v_fmac_f32_e32 v60, v109, v62
	v_mul_f32_e32 v56, v60, v71
	v_mul_f32_e32 v57, v60, v72
	v_fma_f32 v56, v61, v72, -v56
	v_fmac_f32_e32 v57, v61, v71
	ds_write_b64 v89, v[56:57] offset:28288
	v_mul_f32_e32 v56, v110, v60
	v_fma_f32 v62, v109, v61, -v56
	v_mul_f32_e32 v61, v110, v61
	v_fmac_f32_e32 v61, v109, v60
	v_mul_f32_e32 v56, v61, v67
	v_mul_f32_e32 v57, v61, v65
	v_fma_f32 v56, v62, v65, -v56
	v_fmac_f32_e32 v57, v62, v67
	ds_write_b64 v89, v[56:57] offset:30464
	v_mul_f32_e32 v57, v110, v62
	v_mul_f32_e32 v56, v110, v61
	v_fmac_f32_e32 v57, v109, v61
	v_fma_f32 v60, v109, v62, -v56
	v_mul_f32_e32 v56, v57, v58
	v_mul_f32_e32 v57, v57, v59
	v_fma_f32 v56, v60, v59, -v56
	v_fmac_f32_e32 v57, v60, v58
	ds_write_b64 v89, v[56:57] offset:32640
	s_waitcnt lgkmcnt(0)
	s_barrier
	ds_read2_b64 v[56:59], v90 offset1:17
	ds_read2_b64 v[60:63], v90 offset0:34 offset1:51
	ds_read2_b64 v[64:67], v90 offset0:68 offset1:85
	ds_read2_b64 v[68:71], v90 offset0:102 offset1:119
	ds_read2_b64 v[72:75], v90 offset0:136 offset1:153
	ds_read2_b64 v[100:103], v90 offset0:170 offset1:187
	ds_read2_b64 v[104:107], v90 offset0:204 offset1:221
	ds_read2_b64 v[108:111], v90 offset0:238 offset1:255
	s_waitcnt lgkmcnt(3)
	v_add_f32_e32 v76, v56, v72
	v_add_f32_e32 v77, v57, v73
	v_sub_f32_e32 v56, v56, v72
	v_sub_f32_e32 v57, v57, v73
	s_waitcnt lgkmcnt(1)
	v_add_f32_e32 v72, v64, v104
	v_add_f32_e32 v73, v65, v105
	v_sub_f32_e32 v64, v64, v104
	v_sub_f32_e32 v65, v65, v105
	v_add_f32_e32 v99, v76, v72
	v_add_f32_e32 v104, v77, v73
	v_sub_f32_e32 v72, v76, v72
	v_sub_f32_e32 v73, v77, v73
	v_add_f32_e32 v76, v56, v65
	v_sub_f32_e32 v77, v57, v64
	v_sub_f32_e32 v56, v56, v65
	v_add_f32_e32 v64, v57, v64
	v_add_f32_e32 v57, v58, v74
	v_add_f32_e32 v65, v59, v75
	v_sub_f32_e32 v58, v58, v74
	v_sub_f32_e32 v59, v59, v75
	v_add_f32_e32 v74, v66, v106
	v_add_f32_e32 v75, v67, v107
	v_sub_f32_e32 v66, v66, v106
	v_sub_f32_e32 v67, v67, v107
	v_add_f32_e32 v105, v57, v74
	v_add_f32_e32 v106, v65, v75
	v_sub_f32_e32 v57, v57, v74
	v_sub_f32_e32 v65, v65, v75
	v_add_f32_e32 v74, v58, v67
	v_sub_f32_e32 v75, v59, v66
	v_sub_f32_e32 v58, v58, v67
	v_add_f32_e32 v59, v59, v66
	v_add_f32_e32 v66, v60, v100
	v_add_f32_e32 v67, v61, v101
	v_sub_f32_e32 v60, v60, v100
	v_sub_f32_e32 v61, v61, v101
	s_waitcnt lgkmcnt(0)
	v_add_f32_e32 v100, v68, v108
	v_add_f32_e32 v101, v69, v109
	v_sub_f32_e32 v68, v68, v108
	v_sub_f32_e32 v69, v69, v109
	v_add_f32_e32 v107, v66, v100
	v_add_f32_e32 v108, v67, v101
	v_sub_f32_e32 v66, v66, v100
	v_sub_f32_e32 v67, v67, v101
	v_add_f32_e32 v100, v60, v69
	v_sub_f32_e32 v101, v61, v68
	v_sub_f32_e32 v60, v60, v69
	v_add_f32_e32 v61, v61, v68
	v_add_f32_e32 v68, v62, v102
	v_add_f32_e32 v69, v63, v103
	v_sub_f32_e32 v62, v62, v102
	v_sub_f32_e32 v63, v63, v103
	v_add_f32_e32 v102, v70, v110
	v_add_f32_e32 v103, v71, v111
	v_sub_f32_e32 v70, v70, v110
	v_sub_f32_e32 v71, v71, v111
	v_add_f32_e32 v109, v68, v102
	v_add_f32_e32 v110, v69, v103
	v_sub_f32_e32 v68, v68, v102
	v_sub_f32_e32 v69, v69, v103
	v_add_f32_e32 v102, v62, v71
	v_sub_f32_e32 v103, v63, v70
	v_sub_f32_e32 v62, v62, v71
	v_add_f32_e32 v63, v63, v70
	v_mul_f32_e32 v70, 0x3f6c835e, v74
	v_mul_f32_e32 v71, 0xbec3ef15, v74
	v_mul_f32_e32 v74, 0x3f3504f3, v100
	v_fmac_f32_e32 v70, 0x3ec3ef15, v75
	v_fmac_f32_e32 v71, 0x3f6c835e, v75
	v_fmamk_f32 v75, v101, 0x3f3504f3, v74
	v_fma_f32 v74, v101, s72, -v74
	v_mul_f32_e32 v100, 0x3ec3ef15, v102
	v_mul_f32_e32 v101, 0xbf6c835e, v102
	v_fmac_f32_e32 v100, 0x3f6c835e, v103
	v_fmac_f32_e32 v101, 0x3ec3ef15, v103
	v_fma_f32 v103, 0, v66, v67
	v_fma_f32 v66, v67, 0, -v66
	v_mul_f32_e32 v67, 0xbf3504f3, v68
	v_fmamk_f32 v68, v69, 0x3f3504f3, v67
	v_fmac_f32_e32 v67, 0xbf3504f3, v69
	v_mul_f32_e32 v69, 0x3ec3ef15, v58
	v_mul_f32_e32 v58, 0xbf6c835e, v58
	v_fmac_f32_e32 v69, 0x3f6c835e, v59
	v_fmac_f32_e32 v58, 0x3ec3ef15, v59
	v_mul_f32_e32 v59, 0xbf3504f3, v60
	v_fmamk_f32 v60, v61, 0x3f3504f3, v59
	v_fmac_f32_e32 v59, 0xbf3504f3, v61
	v_mul_f32_e32 v61, 0xbf6c835e, v62
	v_fmac_f32_e32 v61, 0xbec3ef15, v63
	v_mul_f32_e32 v63, 0xbf6c835e, v63
	v_mul_f32_e32 v57, 0x3f3504f3, v57
	v_fmac_f32_e32 v63, 0x3ec3ef15, v62
	v_add_f32_e32 v62, v99, v107
	v_add_f32_e32 v111, v104, v108
	v_sub_f32_e32 v99, v99, v107
	v_sub_f32_e32 v104, v104, v108
	v_add_f32_e32 v107, v105, v109
	v_add_f32_e32 v108, v106, v110
	v_sub_f32_e32 v105, v105, v109
	v_sub_f32_e32 v106, v106, v110
	v_fmamk_f32 v102, v65, 0x3f3504f3, v57
	v_fma_f32 v65, v65, s72, -v57
	v_add_f32_e32 v109, v62, v107
	v_add_f32_e32 v57, v111, v108
	v_sub_f32_e32 v62, v62, v107
	v_sub_f32_e32 v107, v111, v108
	v_add_f32_e32 v108, v99, v106
	v_sub_f32_e32 v110, v104, v105
	v_sub_f32_e32 v99, v99, v106
	v_add_f32_e32 v104, v104, v105
	v_add_f32_e32 v105, v76, v75
	v_add_f32_e32 v106, v77, v74
	v_sub_f32_e32 v75, v76, v75
	v_sub_f32_e32 v74, v77, v74
	v_add_f32_e32 v76, v70, v100
	v_add_f32_e32 v77, v71, v101
	v_sub_f32_e32 v70, v70, v100
	v_sub_f32_e32 v71, v71, v101
	v_add_f32_e32 v100, v105, v76
	v_add_f32_e32 v101, v106, v77
	v_sub_f32_e32 v76, v105, v76
	v_sub_f32_e32 v77, v106, v77
	v_add_f32_e32 v105, v75, v71
	v_sub_f32_e32 v106, v74, v70
	v_sub_f32_e32 v71, v75, v71
	v_add_f32_e32 v70, v74, v70
	v_add_f32_e32 v74, v72, v103
	v_add_f32_e32 v75, v73, v66
	v_sub_f32_e32 v72, v72, v103
	v_sub_f32_e32 v66, v73, v66
	v_add_f32_e32 v73, v102, v68
	v_add_f32_e32 v103, v65, v67
	v_sub_f32_e32 v68, v102, v68
	v_sub_f32_e32 v65, v65, v67
	v_add_f32_e32 v67, v74, v73
	v_add_f32_e32 v102, v75, v103
	v_sub_f32_e32 v73, v74, v73
	v_sub_f32_e32 v74, v75, v103
	v_add_f32_e32 v75, v72, v65
	v_sub_f32_e32 v103, v66, v68
	v_sub_f32_e32 v65, v72, v65
	v_add_f32_e32 v66, v66, v68
	v_add_f32_e32 v68, v56, v60
	v_add_f32_e32 v72, v64, v59
	v_sub_f32_e32 v56, v56, v60
	v_sub_f32_e32 v59, v64, v59
	v_add_f32_e32 v60, v69, v61
	v_add_f32_e32 v64, v58, v63
	v_sub_f32_e32 v61, v69, v61
	v_sub_f32_e32 v58, v58, v63
	v_add_f32_e32 v63, v68, v60
	v_add_f32_e32 v69, v72, v64
	v_sub_f32_e32 v60, v68, v60
	v_sub_f32_e32 v64, v72, v64
	v_add_f32_e32 v68, v56, v58
	v_sub_f32_e32 v72, v59, v61
	v_sub_f32_e32 v58, v56, v58
	v_add_f32_e32 v59, v59, v61
	v_fmamk_f32 v56, v57, 0x80000000, v109
	v_fmac_f32_e32 v57, 0, v109
	ds_write_b64 v90, v[56:57]
	v_fmamk_f32 v61, v55, 0x80000000, v54
	v_fma_f32 v109, 0, v54, v55
	v_mul_f32_e32 v56, v109, v101
	v_mul_f32_e32 v57, v61, v101
	v_fma_f32 v56, v61, v100, -v56
	v_fmac_f32_e32 v57, v109, v100
	ds_write_b64 v90, v[56:57] offset:136
	v_mul_f32_e32 v56, v55, v109
	v_fma_f32 v100, v54, v61, -v56
	v_mul_f32_e32 v61, v55, v61
	v_fmac_f32_e32 v61, v54, v109
	v_mul_f32_e32 v56, v61, v102
	v_mul_f32_e32 v57, v100, v102
	v_fma_f32 v56, v100, v67, -v56
	v_fmac_f32_e32 v57, v61, v67
	ds_write_b64 v90, v[56:57] offset:272
	v_mul_f32_e32 v56, v55, v61
	v_mul_f32_e32 v61, v54, v61
	v_fma_f32 v67, v54, v100, -v56
	v_fmac_f32_e32 v61, v55, v100
	v_mul_f32_e32 v56, v61, v69
	v_mul_f32_e32 v57, v67, v69
	v_fma_f32 v56, v67, v63, -v56
	v_fmac_f32_e32 v57, v61, v63
	ds_write_b64 v90, v[56:57] offset:408
	v_mul_f32_e32 v56, v55, v61
	v_mul_f32_e32 v61, v54, v61
	v_fma_f32 v63, v54, v67, -v56
	v_fmac_f32_e32 v61, v55, v67
	v_mul_f32_e32 v56, v61, v110
	v_mul_f32_e32 v57, v61, v108
	v_fma_f32 v56, v63, v108, -v56
	v_fmac_f32_e32 v57, v63, v110
	ds_write_b64 v90, v[56:57] offset:544
	v_mul_f32_e32 v56, v55, v61
	v_mul_f32_e32 v61, v54, v61
	v_fma_f32 v67, v54, v63, -v56
	v_fmac_f32_e32 v61, v55, v63
	v_mul_f32_e32 v56, v61, v106
	v_mul_f32_e32 v57, v67, v106
	v_fma_f32 v56, v67, v105, -v56
	v_fmac_f32_e32 v57, v61, v105
	ds_write_b64 v90, v[56:57] offset:680
	v_mul_f32_e32 v56, v55, v61
	v_mul_f32_e32 v61, v54, v61
	v_fma_f32 v63, v54, v67, -v56
	v_fmac_f32_e32 v61, v55, v67
	v_mul_f32_e32 v56, v61, v103
	v_mul_f32_e32 v57, v63, v103
	v_fma_f32 v56, v63, v75, -v56
	v_fmac_f32_e32 v57, v61, v75
	ds_write_b64 v90, v[56:57] offset:816
	v_mul_f32_e32 v56, v55, v61
	v_mul_f32_e32 v61, v54, v61
	v_fma_f32 v67, v54, v63, -v56
	v_fmac_f32_e32 v61, v55, v63
	v_mul_f32_e32 v56, v61, v72
	v_mul_f32_e32 v57, v67, v72
	v_fma_f32 v56, v67, v68, -v56
	v_fmac_f32_e32 v57, v61, v68
	ds_write_b64 v90, v[56:57] offset:952
	v_mul_f32_e32 v56, v55, v61
	v_mul_f32_e32 v61, v54, v61
	v_fma_f32 v63, v54, v67, -v56
	v_fmac_f32_e32 v61, v55, v67
	v_mul_f32_e32 v56, v61, v107
	v_mul_f32_e32 v57, v63, v107
	v_fma_f32 v56, v63, v62, -v56
	v_fmac_f32_e32 v57, v61, v62
	ds_write_b64 v90, v[56:57] offset:1088
	v_mul_f32_e32 v56, v55, v61
	v_mul_f32_e32 v61, v54, v61
	v_fma_f32 v62, v54, v63, -v56
	v_fmac_f32_e32 v61, v55, v63
	v_mul_f32_e32 v56, v61, v77
	v_mul_f32_e32 v57, v62, v77
	v_fma_f32 v56, v62, v76, -v56
	v_fmac_f32_e32 v57, v61, v76
	ds_write_b64 v90, v[56:57] offset:1224
	v_mul_f32_e32 v56, v55, v61
	v_mul_f32_e32 v61, v54, v61
	v_fma_f32 v63, v54, v62, -v56
	v_fmac_f32_e32 v61, v55, v62
	v_mul_f32_e32 v56, v61, v74
	v_mul_f32_e32 v57, v63, v74
	v_fma_f32 v56, v63, v73, -v56
	v_fmac_f32_e32 v57, v61, v73
	ds_write_b64 v90, v[56:57] offset:1360
	v_mul_f32_e32 v56, v55, v61
	v_mul_f32_e32 v61, v54, v61
	v_fma_f32 v62, v54, v63, -v56
	v_fmac_f32_e32 v61, v55, v63
	v_mul_f32_e32 v56, v61, v64
	v_mul_f32_e32 v57, v62, v64
	v_fma_f32 v56, v62, v60, -v56
	v_fmac_f32_e32 v57, v61, v60
	ds_write_b64 v90, v[56:57] offset:1496
	v_mul_f32_e32 v56, v55, v61
	v_mul_f32_e32 v61, v54, v61
	v_fma_f32 v60, v54, v62, -v56
	v_fmac_f32_e32 v61, v55, v62
	v_mul_f32_e32 v56, v61, v104
	v_mul_f32_e32 v57, v61, v99
	v_fma_f32 v56, v60, v99, -v56
	v_fmac_f32_e32 v57, v60, v104
	ds_write_b64 v90, v[56:57] offset:1632
	v_mul_f32_e32 v56, v55, v61
	v_mul_f32_e32 v61, v54, v61
	v_fma_f32 v62, v54, v60, -v56
	v_fmac_f32_e32 v61, v55, v60
	v_mul_f32_e32 v56, v61, v70
	v_mul_f32_e32 v57, v62, v70
	v_fma_f32 v56, v62, v71, -v56
	v_fmac_f32_e32 v57, v61, v71
	ds_write_b64 v90, v[56:57] offset:1768
	v_mul_f32_e32 v56, v55, v61
	v_mul_f32_e32 v61, v54, v61
	v_fma_f32 v60, v54, v62, -v56
	v_fmac_f32_e32 v61, v55, v62
	v_mul_f32_e32 v56, v61, v66
	v_mul_f32_e32 v57, v60, v66
	v_fma_f32 v56, v60, v65, -v56
	v_fmac_f32_e32 v57, v61, v65
	ds_write_b64 v90, v[56:57] offset:1904
	v_mul_f32_e32 v56, v55, v61
	v_mul_f32_e32 v57, v54, v61
	v_fma_f32 v56, v54, v60, -v56
	v_fmac_f32_e32 v57, v55, v60
	v_mul_f32_e32 v54, v57, v59
	v_mul_f32_e32 v55, v56, v59
	v_fma_f32 v54, v56, v58, -v54
	v_fmac_f32_e32 v55, v57, v58
	ds_write_b64 v90, v[54:55] offset:2040
	s_waitcnt lgkmcnt(0)
	s_barrier
	ds_read2_b64 v[54:57], v91 offset1:1
	ds_read2_b64 v[58:61], v91 offset0:2 offset1:3
	ds_read2_b64 v[62:65], v91 offset0:4 offset1:5
	ds_read2_b64 v[66:69], v91 offset0:6 offset1:7
	ds_read2_b64 v[70:73], v91 offset0:8 offset1:9
	ds_read2_b64 v[74:77], v91 offset0:10 offset1:11
	ds_read2_b64 v[100:103], v91 offset0:14 offset1:15
	ds_read2_b64 v[104:107], v91 offset0:12 offset1:13
	s_waitcnt lgkmcnt(0)
	v_add_f32_e32 v99, v54, v70
	v_add_f32_e32 v108, v55, v71
	v_sub_f32_e32 v54, v54, v70
	v_sub_f32_e32 v55, v55, v71
	v_add_f32_e32 v70, v62, v104
	v_add_f32_e32 v71, v63, v105
	v_sub_f32_e32 v62, v62, v104
	v_sub_f32_e32 v63, v63, v105
	v_add_f32_e32 v104, v99, v70
	v_add_f32_e32 v105, v108, v71
	v_sub_f32_e32 v70, v99, v70
	v_sub_f32_e32 v71, v108, v71
	v_add_f32_e32 v99, v54, v63
	v_sub_f32_e32 v108, v55, v62
	v_sub_f32_e32 v54, v54, v63
	v_add_f32_e32 v55, v55, v62
	v_add_f32_e32 v62, v56, v72
	v_add_f32_e32 v63, v57, v73
	v_sub_f32_e32 v56, v56, v72
	v_sub_f32_e32 v57, v57, v73
	v_add_f32_e32 v72, v64, v106
	v_add_f32_e32 v73, v65, v107
	v_sub_f32_e32 v64, v64, v106
	v_sub_f32_e32 v65, v65, v107
	v_add_f32_e32 v106, v62, v72
	v_add_f32_e32 v107, v63, v73
	v_sub_f32_e32 v62, v62, v72
	v_sub_f32_e32 v63, v63, v73
	v_add_f32_e32 v72, v56, v65
	v_sub_f32_e32 v73, v57, v64
	v_sub_f32_e32 v56, v56, v65
	v_add_f32_e32 v57, v57, v64
	v_add_f32_e32 v64, v58, v74
	v_add_f32_e32 v65, v59, v75
	v_sub_f32_e32 v58, v58, v74
	v_sub_f32_e32 v59, v59, v75
	v_add_f32_e32 v74, v66, v100
	v_add_f32_e32 v75, v67, v101
	v_sub_f32_e32 v66, v66, v100
	v_sub_f32_e32 v67, v67, v101
	v_add_f32_e32 v100, v64, v74
	v_add_f32_e32 v101, v65, v75
	v_sub_f32_e32 v64, v64, v74
	v_sub_f32_e32 v65, v65, v75
	v_add_f32_e32 v74, v58, v67
	v_sub_f32_e32 v75, v59, v66
	v_sub_f32_e32 v58, v58, v67
	v_add_f32_e32 v59, v59, v66
	v_add_f32_e32 v66, v60, v76
	v_add_f32_e32 v67, v61, v77
	v_sub_f32_e32 v60, v60, v76
	v_sub_f32_e32 v61, v61, v77
	v_add_f32_e32 v76, v68, v102
	v_add_f32_e32 v77, v69, v103
	v_sub_f32_e32 v68, v68, v102
	v_sub_f32_e32 v69, v69, v103
	v_add_f32_e32 v102, v66, v76
	v_add_f32_e32 v103, v67, v77
	v_sub_f32_e32 v66, v66, v76
	v_sub_f32_e32 v67, v67, v77
	v_add_f32_e32 v76, v60, v69
	v_sub_f32_e32 v77, v61, v68
	v_sub_f32_e32 v60, v60, v69
	v_add_f32_e32 v61, v61, v68
	v_mul_f32_e32 v68, 0x3f6c835e, v72
	v_mul_f32_e32 v69, 0xbec3ef15, v72
	v_mul_f32_e32 v72, 0x3f3504f3, v74
	v_mul_f32_e32 v62, 0x3f3504f3, v62
	v_fmac_f32_e32 v68, 0x3ec3ef15, v73
	v_fmac_f32_e32 v69, 0x3f6c835e, v73
	v_fmamk_f32 v73, v75, 0x3f3504f3, v72
	v_fma_f32 v72, v75, s72, -v72
	v_mul_f32_e32 v74, 0x3ec3ef15, v76
	v_mul_f32_e32 v75, 0xbf6c835e, v76
	v_fmamk_f32 v76, v63, 0x3f3504f3, v62
	v_fma_f32 v62, v63, s72, -v62
	v_fma_f32 v63, 0, v64, v65
	v_fma_f32 v64, v65, 0, -v64
	v_mul_f32_e32 v65, 0xbf3504f3, v66
	v_fmamk_f32 v66, v67, 0x3f3504f3, v65
	v_fmac_f32_e32 v65, 0xbf3504f3, v67
	v_mul_f32_e32 v67, 0x3ec3ef15, v56
	v_mul_f32_e32 v56, 0xbf6c835e, v56
	v_fmac_f32_e32 v67, 0x3f6c835e, v57
	v_fmac_f32_e32 v56, 0x3ec3ef15, v57
	v_mul_f32_e32 v57, 0xbf3504f3, v58
	v_fmamk_f32 v58, v59, 0x3f3504f3, v57
	v_fmac_f32_e32 v57, 0xbf3504f3, v59
	v_mul_f32_e32 v59, 0xbf6c835e, v60
	v_fmac_f32_e32 v59, 0xbec3ef15, v61
	v_mul_f32_e32 v61, 0xbf6c835e, v61
	v_fmac_f32_e32 v74, 0x3f6c835e, v77
	v_fmac_f32_e32 v75, 0x3ec3ef15, v77
	v_fmac_f32_e32 v61, 0x3ec3ef15, v60
	v_add_f32_e32 v60, v104, v100
	v_add_f32_e32 v77, v105, v101
	v_sub_f32_e32 v100, v104, v100
	v_sub_f32_e32 v101, v105, v101
	v_add_f32_e32 v104, v106, v102
	v_sub_f32_e32 v102, v106, v102
	v_add_f32_e32 v105, v107, v103
	v_sub_f32_e32 v103, v107, v103
	v_add_f32_e32 v107, v104, v60
	v_sub_f32_e32 v110, v60, v104
	v_sub_f32_e32 v112, v101, v102
	v_add_f32_e32 v101, v102, v101
	v_add_f32_e32 v60, v99, v73
	v_sub_f32_e32 v73, v99, v73
	v_add_f32_e32 v99, v68, v74
	v_add_f32_e32 v102, v69, v75
	v_sub_f32_e32 v69, v69, v75
	v_add_f32_e32 v111, v100, v103
	v_sub_f32_e32 v113, v100, v103
	v_add_f32_e32 v100, v108, v72
	v_sub_f32_e32 v72, v108, v72
	v_add_f32_e32 v108, v99, v60
	v_sub_f32_e32 v115, v60, v99
	v_add_f32_e32 v116, v69, v73
	v_sub_f32_e32 v118, v73, v69
	v_add_f32_e32 v60, v70, v63
	v_sub_f32_e32 v63, v70, v63
	v_add_f32_e32 v69, v76, v66
	v_add_f32_e32 v70, v62, v65
	v_sub_f32_e32 v62, v62, v65
	v_add_f32_e32 v109, v105, v77
	v_sub_f32_e32 v77, v77, v105
	v_add_f32_e32 v120, v60, v69
	v_sub_f32_e32 v122, v60, v69
	v_add_f32_e32 v124, v63, v62
	v_sub_f32_e32 v105, v63, v62
	v_add_f32_e32 v60, v54, v58
	v_add_f32_e32 v62, v55, v57
	v_sub_f32_e32 v54, v54, v58
	v_sub_f32_e32 v55, v55, v57
	v_add_f32_e32 v57, v67, v59
	v_add_f32_e32 v58, v56, v61
	v_sub_f32_e32 v56, v56, v61
	v_sub_f32_e32 v68, v68, v74
	v_sub_f32_e32 v59, v67, v59
	v_add_f32_e32 v103, v57, v60
	v_sub_f32_e32 v74, v60, v57
	v_add_f32_e32 v99, v56, v54
	v_sub_f32_e32 v57, v54, v56
	v_mov_b32_e32 v54, v0
	v_add_f32_e32 v114, v102, v100
	v_sub_f32_e32 v102, v100, v102
	v_sub_f32_e32 v100, v55, v59
	v_add_f32_e32 v56, v59, v55
	s_barrier
	v_sub_f32_e32 v117, v72, v68
	v_ashrrev_i32_e32 v55, 31, v54
	v_add_f32_e32 v119, v68, v72
	v_add_f32_e32 v68, v71, v64
	v_sub_f32_e32 v64, v71, v64
	v_sub_f32_e32 v66, v76, v66
	v_lshl_add_u64 v[54:55], v[54:55], 3, s[94:95]
	v_add_co_u32_e32 v226, vcc, s18, v54
	v_addc_co_u32_e32 v227, vcc, 0, v55, vcc
	v_add_co_u32_e32 v228, vcc, s19, v54
	v_addc_co_u32_e32 v229, vcc, 0, v55, vcc
	v_add_co_u32_e32 v230, vcc, s67, v54
	v_addc_co_u32_e32 v231, vcc, 0, v55, vcc
	v_add_co_u32_e32 v232, vcc, s50, v54
	v_addc_co_u32_e32 v233, vcc, 0, v55, vcc
	v_add_co_u32_e32 v234, vcc, s5, v54
	v_addc_co_u32_e32 v235, vcc, 0, v55, vcc
	v_add_co_u32_e32 v236, vcc, s51, v54
	v_addc_co_u32_e32 v237, vcc, 0, v55, vcc
	v_add_co_u32_e32 v238, vcc, s56, v54
	v_addc_co_u32_e32 v239, vcc, 0, v55, vcc
	global_load_dwordx2 v[194:195], v[54:55], off
	global_load_dwordx2 v[196:197], v[54:55], off offset:2048
	global_load_dwordx2 v[198:199], v[228:229], off offset:-4096
	global_load_dwordx2 v[200:201], v[228:229], off
	global_load_dwordx2 v[202:203], v[226:227], off offset:2048
	global_load_dwordx2 v[204:205], v[228:229], off offset:2048
	global_load_dwordx2 v[206:207], v[232:233], off offset:-4096
	global_load_dwordx2 v[208:209], v[232:233], off
	global_load_dwordx2 v[210:211], v[230:231], off offset:2048
	global_load_dwordx2 v[212:213], v[232:233], off offset:2048
	global_load_dwordx2 v[214:215], v[234:235], off offset:2048
	global_load_dwordx2 v[216:217], v[236:237], off offset:-4096
	global_load_dwordx2 v[218:219], v[236:237], off
	global_load_dwordx2 v[220:221], v[236:237], off offset:2048
	global_load_dwordx2 v[222:223], v[238:239], off
	global_load_dwordx2 v[224:225], v[238:239], off offset:2048
	v_sub_f32_e32 v125, v64, v66
	v_add_f32_e32 v106, v66, v64
	v_add_co_u32_e32 v64, vcc, s18, v54
	v_add_f32_e32 v121, v70, v68
	s_nop 0
	v_addc_co_u32_e32 v65, vcc, 0, v55, vcc
	v_sub_f32_e32 v123, v68, v70
	s_waitcnt vmcnt(15)
	v_mov_b32_e32 v60, v194
	v_mov_b32_e32 v61, v195
	v_add_co_u32_e32 v68, vcc, s19, v54
	v_add_f32_e32 v104, v58, v62
	v_sub_f32_e32 v75, v62, v58
	s_waitcnt vmcnt(14)
	v_mov_b32_e32 v62, v196
	v_mov_b32_e32 v63, v197
	v_addc_co_u32_e32 v69, vcc, 0, v55, vcc
	s_waitcnt vmcnt(13)
	v_mov_b32_e32 v66, v198
	v_mov_b32_e32 v67, v199
	s_waitcnt vmcnt(12)
	v_mov_b32_e32 v70, v200
	v_mov_b32_e32 v71, v201
	v_add_co_u32_e32 v72, vcc, s67, v54
	v_mul_f32_e32 v58, v109, v61
	v_mul_f32_e32 v59, v107, v61
	v_fma_f32 v58, v107, v60, -v58
	v_fmac_f32_e32 v59, v109, v60
	v_addc_co_u32_e32 v73, vcc, 0, v55, vcc
	v_mul_f32_e32 v60, v112, v63
	v_mul_f32_e32 v61, v111, v63
	v_fma_f32 v60, v111, v62, -v60
	v_fmac_f32_e32 v61, v112, v62
	v_mul_f32_e32 v62, v77, v67
	v_mul_f32_e32 v63, v110, v67
	v_fma_f32 v62, v110, v66, -v62
	v_fmac_f32_e32 v63, v77, v66
	s_waitcnt vmcnt(11)
	v_mov_b32_e32 v66, v202
	v_mov_b32_e32 v67, v203
	v_mul_f32_e32 v64, v101, v67
	v_mul_f32_e32 v65, v113, v67
	v_fma_f32 v64, v113, v66, -v64
	v_fmac_f32_e32 v65, v101, v66
	v_mul_f32_e32 v66, v114, v71
	v_fma_f32 v66, v108, v70, -v66
	v_mul_f32_e32 v67, v108, v71
	v_add_co_u32_e32 v108, vcc, s50, v54
	v_fmac_f32_e32 v67, v114, v70
	s_waitcnt vmcnt(10)
	v_mov_b32_e32 v70, v204
	v_mov_b32_e32 v71, v205
	v_addc_co_u32_e32 v109, vcc, 0, v55, vcc
	s_waitcnt vmcnt(9)
	v_mov_b32_e32 v76, v206
	v_mov_b32_e32 v77, v207
	s_waitcnt vmcnt(8)
	v_mov_b32_e32 v110, v208
	v_mov_b32_e32 v111, v209
	v_mul_f32_e32 v68, v117, v71
	v_mul_f32_e32 v69, v116, v71
	v_fma_f32 v68, v116, v70, -v68
	v_fmac_f32_e32 v69, v117, v70
	v_mul_f32_e32 v70, v102, v77
	v_mul_f32_e32 v71, v115, v77
	v_fma_f32 v70, v115, v76, -v70
	v_fmac_f32_e32 v71, v102, v76
	s_waitcnt vmcnt(7)
	v_mov_b32_e32 v76, v210
	v_mov_b32_e32 v77, v211
	v_mul_f32_e32 v72, v119, v77
	v_mul_f32_e32 v73, v118, v77
	v_fma_f32 v72, v118, v76, -v72
	v_fmac_f32_e32 v73, v119, v76
	v_mul_f32_e32 v76, v121, v111
	v_mul_f32_e32 v77, v120, v111
	v_fma_f32 v76, v120, v110, -v76
	v_fmac_f32_e32 v77, v121, v110
	v_add_co_u32_e32 v110, vcc, s5, v54
	s_waitcnt vmcnt(6)
	v_mov_b32_e32 v108, v212
	v_mov_b32_e32 v109, v213
	s_nop 0
	v_addc_co_u32_e32 v111, vcc, 0, v55, vcc
	v_add_co_u32_e32 v112, vcc, s51, v54
	s_waitcnt vmcnt(5)
	v_mov_b32_e32 v110, v214
	v_mov_b32_e32 v111, v215
	s_nop 0
	v_addc_co_u32_e32 v113, vcc, 0, v55, vcc
	s_waitcnt vmcnt(4)
	v_mov_b32_e32 v114, v216
	v_mov_b32_e32 v115, v217
	v_add_co_u32_e32 v54, vcc, s56, v54
	v_mul_f32_e32 v101, v125, v109
	v_mul_f32_e32 v102, v124, v109
	v_fma_f32 v101, v124, v108, -v101
	v_fmac_f32_e32 v102, v125, v108
	v_addc_co_u32_e32 v55, vcc, 0, v55, vcc
	v_mul_f32_e32 v109, v106, v111
	v_fma_f32 v109, v105, v110, -v109
	v_mul_f32_e32 v107, v123, v115
	v_mul_f32_e32 v108, v122, v115
	v_fma_f32 v107, v122, v114, -v107
	v_fmac_f32_e32 v108, v123, v114
	v_mul_f32_e32 v114, v105, v111
	v_fmac_f32_e32 v114, v106, v110
	s_waitcnt vmcnt(3)
	v_mov_b32_e32 v110, v218
	v_mov_b32_e32 v111, v219
	v_mul_f32_e32 v105, v104, v111
	v_fma_f32 v106, v103, v110, -v105
	v_mul_f32_e32 v103, v103, v111
	v_fmac_f32_e32 v103, v104, v110
	s_waitcnt vmcnt(2)
	v_mov_b32_e32 v104, v220
	v_mov_b32_e32 v105, v221
	v_add_f32_e32 v112, v58, v62
	v_add_f32_e32 v113, v59, v63
	v_sub_f32_e32 v58, v58, v62
	v_sub_f32_e32 v59, v59, v63
	v_add_f32_e32 v62, v60, v64
	v_add_f32_e32 v63, v61, v65
	v_sub_f32_e32 v60, v60, v64
	v_sub_f32_e32 v61, v61, v65
	v_add_f32_e32 v64, v112, v62
	v_add_f32_e32 v65, v113, v63
	v_sub_f32_e32 v62, v112, v62
	v_sub_f32_e32 v63, v113, v63
	v_sub_f32_e32 v112, v58, v61
	v_add_f32_e32 v113, v59, v60
	v_add_f32_e32 v58, v58, v61
	v_sub_f32_e32 v60, v59, v60
	v_add_f32_e32 v59, v66, v70
	v_add_f32_e32 v61, v67, v71
	v_sub_f32_e32 v66, v66, v70
	v_sub_f32_e32 v67, v67, v71
	v_add_f32_e32 v70, v68, v72
	v_add_f32_e32 v71, v69, v73
	v_sub_f32_e32 v68, v68, v72
	v_sub_f32_e32 v69, v69, v73
	v_add_f32_e32 v72, v59, v70
	v_add_f32_e32 v73, v61, v71
	v_sub_f32_e32 v59, v59, v70
	v_sub_f32_e32 v61, v61, v71
	v_sub_f32_e32 v70, v66, v69
	v_add_f32_e32 v71, v67, v68
	v_add_f32_e32 v66, v66, v69
	v_sub_f32_e32 v67, v67, v68
	v_add_f32_e32 v68, v76, v107
	v_add_f32_e32 v69, v77, v108
	v_sub_f32_e32 v76, v76, v107
	v_sub_f32_e32 v77, v77, v108
	v_add_f32_e32 v107, v101, v109
	v_add_f32_e32 v108, v102, v114
	v_sub_f32_e32 v101, v101, v109
	v_sub_f32_e32 v102, v102, v114
	v_add_f32_e32 v109, v68, v107
	v_add_f32_e32 v114, v69, v108
	v_sub_f32_e32 v68, v68, v107
	v_sub_f32_e32 v69, v69, v108
	v_sub_f32_e32 v107, v76, v102
	v_add_f32_e32 v108, v77, v101
	v_add_f32_e32 v76, v76, v102
	v_sub_f32_e32 v77, v77, v101
	v_mul_f32_e32 v61, 0x3f3504f3, v61
	v_add_f32_e32 v115, v65, v114
	v_sub_f32_e32 v65, v65, v114
	v_mov_b32_e32 v111, v79
	v_mul_f32_e32 v110, v100, v105
	v_fma_f32 v110, v99, v104, -v110
	v_mul_f32_e32 v99, v99, v105
	v_fmac_f32_e32 v99, v100, v104
	s_waitcnt vmcnt(1)
	v_mov_b32_e32 v104, v222
	v_mov_b32_e32 v105, v223
	v_mul_f32_e32 v100, v75, v105
	s_waitcnt vmcnt(0)
	v_mov_b32_e32 v54, v224
	v_mov_b32_e32 v55, v225
	v_fma_f32 v100, v74, v104, -v100
	v_mul_f32_e32 v74, v74, v105
	v_fmac_f32_e32 v74, v75, v104
	v_add_f32_e32 v101, v106, v100
	v_add_f32_e32 v102, v103, v74
	v_sub_f32_e32 v100, v106, v100
	v_sub_f32_e32 v74, v103, v74
	v_mov_b32_e32 v105, v78
	v_mul_f32_e32 v75, v56, v55
	v_mul_f32_e32 v104, v57, v55
	v_fma_f32 v75, v57, v54, -v75
	v_fmac_f32_e32 v104, v56, v54
	v_add_f32_e32 v103, v110, v75
	v_add_f32_e32 v106, v99, v104
	v_sub_f32_e32 v99, v99, v104
	v_add_f32_e32 v104, v101, v103
	v_sub_f32_e32 v101, v101, v103
	v_sub_f32_e32 v103, v100, v99
	v_add_f32_e32 v99, v100, v99
	v_mul_f32_e32 v100, 0xbf6c835e, v67
	v_fmac_f32_e32 v100, 0x3ec3ef15, v66
	v_mul_f32_e32 v66, 0x3f6c835e, v66
	v_sub_f32_e32 v75, v110, v75
	v_fmac_f32_e32 v66, 0x3ec3ef15, v67
	v_mul_f32_e32 v67, 0x3f3504f3, v107
	v_add_f32_e32 v110, v102, v106
	v_sub_f32_e32 v102, v102, v106
	v_add_f32_e32 v106, v74, v75
	v_fmamk_f32 v107, v108, 0xbf3504f3, v67
	v_fmac_f32_e32 v67, 0x3f3504f3, v108
	v_fma_f32 v108, v68, 0, -v69
	v_fmac_f32_e32 v68, 0, v69
	v_mul_f32_e32 v69, 0xbf3504f3, v77
	v_fmamk_f32 v77, v76, 0xbf3504f3, v69
	v_fmac_f32_e32 v69, 0x3f3504f3, v76
	v_mul_f32_e32 v76, 0xbf6c835e, v106
	v_sub_f32_e32 v74, v74, v75
	v_mul_f32_e32 v75, 0xbec3ef15, v71
	v_fmac_f32_e32 v76, 0x3ec3ef15, v103
	v_mul_f32_e32 v103, 0x3f6c835e, v103
	v_mul_f32_e32 v102, 0xbf3504f3, v102
	v_fmac_f32_e32 v75, 0x3f6c835e, v70
	v_mul_f32_e32 v70, 0x3ec3ef15, v70
	v_fmac_f32_e32 v103, 0x3ec3ef15, v106
	v_fmamk_f32 v106, v101, 0xbf3504f3, v102
	v_fmac_f32_e32 v102, 0x3f3504f3, v101
	v_mul_f32_e32 v101, 0xbf6c835e, v99
	v_mul_f32_e32 v99, 0xbec3ef15, v99
	v_fmac_f32_e32 v70, 0x3f6c835e, v71
	v_fmac_f32_e32 v101, 0x3ec3ef15, v74
	v_fmac_f32_e32 v99, 0xbf6c835e, v74
	v_add_f32_e32 v74, v64, v109
	v_sub_f32_e32 v64, v64, v109
	v_add_f32_e32 v109, v72, v104
	v_add_f32_e32 v114, v73, v110
	v_sub_f32_e32 v72, v72, v104
	v_sub_f32_e32 v73, v73, v110
	v_fma_f32 v71, v59, s72, -v61
	v_fmac_f32_e32 v61, 0x3f3504f3, v59
	v_add_f32_e32 v104, v74, v109
	v_add_f32_e32 v59, v115, v114
	v_sub_f32_e32 v74, v74, v109
	v_sub_f32_e32 v109, v115, v114
	v_sub_f32_e32 v110, v64, v73
	v_add_f32_e32 v114, v65, v72
	v_add_f32_e32 v64, v64, v73
	v_sub_f32_e32 v65, v65, v72
	v_add_f32_e32 v72, v112, v107
	v_add_f32_e32 v73, v113, v67
	v_sub_f32_e32 v107, v112, v107
	v_sub_f32_e32 v67, v113, v67
	v_add_f32_e32 v112, v75, v76
	v_add_f32_e32 v113, v70, v103
	v_sub_f32_e32 v75, v75, v76
	v_sub_f32_e32 v70, v70, v103
	v_add_f32_e32 v76, v72, v112
	v_add_f32_e32 v103, v73, v113
	v_sub_f32_e32 v72, v72, v112
	v_sub_f32_e32 v73, v73, v113
	v_sub_f32_e32 v112, v107, v70
	v_add_f32_e32 v113, v67, v75
	v_add_f32_e32 v70, v107, v70
	v_sub_f32_e32 v67, v67, v75
	v_add_f32_e32 v75, v62, v108
	v_add_f32_e32 v107, v63, v68
	v_sub_f32_e32 v62, v62, v108
	v_sub_f32_e32 v63, v63, v68
	v_add_f32_e32 v68, v71, v106
	v_add_f32_e32 v108, v61, v102
	v_sub_f32_e32 v71, v71, v106
	v_sub_f32_e32 v61, v61, v102
	v_mov_b32_e32 v56, v80
	v_mov_b32_e32 v57, v81
	v_mov_b32_e32 v54, v84
	v_mov_b32_e32 v55, v85
	v_add_f32_e32 v102, v75, v68
	v_add_f32_e32 v106, v107, v108
	v_sub_f32_e32 v68, v75, v68
	v_sub_f32_e32 v75, v107, v108
	v_sub_f32_e32 v107, v62, v61
	v_add_f32_e32 v108, v63, v71
	v_add_f32_e32 v61, v62, v61
	v_sub_f32_e32 v62, v63, v71
	v_add_f32_e32 v63, v58, v77
	v_add_f32_e32 v71, v60, v69
	v_sub_f32_e32 v58, v58, v77
	v_sub_f32_e32 v60, v60, v69
	v_add_f32_e32 v69, v100, v101
	v_add_f32_e32 v77, v66, v99
	v_sub_f32_e32 v100, v100, v101
	v_sub_f32_e32 v66, v66, v99
	v_add_f32_e32 v99, v63, v69
	v_add_f32_e32 v101, v71, v77
	v_sub_f32_e32 v63, v63, v69
	v_sub_f32_e32 v69, v71, v77
	v_sub_f32_e32 v71, v58, v66
	v_add_f32_e32 v77, v60, v100
	v_add_f32_e32 v66, v58, v66
	v_sub_f32_e32 v60, v60, v100
	v_fma_f32 v58, 0, v59, v104
	v_fmac_f32_e32 v59, 0x80000000, v104
	ds_write_b64 v91, v[58:59]
	v_fmamk_f32 v100, v111, 0x80000000, v105
	v_fma_f32 v104, 0, v105, v111
	v_mul_f32_e32 v58, v104, v103
	v_mul_f32_e32 v59, v104, v76
	v_fmac_f32_e32 v58, v100, v76
	v_fma_f32 v59, v100, v103, -v59
	ds_write_b64 v91, v[58:59] offset:8
	v_mul_f32_e32 v58, v111, v104
	v_fma_f32 v76, v105, v100, -v58
	v_mul_f32_e32 v100, v111, v100
	v_fmac_f32_e32 v100, v105, v104
	v_mul_f32_e32 v58, v100, v106
	v_mul_f32_e32 v59, v100, v102
	v_fmac_f32_e32 v58, v76, v102
	v_fma_f32 v59, v76, v106, -v59
	ds_write_b64 v91, v[58:59] offset:16
	v_mul_f32_e32 v58, v111, v100
	v_fma_f32 v102, v105, v76, -v58
	v_mul_f32_e32 v76, v111, v76
	v_fmac_f32_e32 v76, v105, v100
	v_mul_f32_e32 v58, v76, v101
	v_mul_f32_e32 v59, v76, v99
	v_fmac_f32_e32 v58, v102, v99
	v_fma_f32 v59, v102, v101, -v59
	ds_write_b64 v91, v[58:59] offset:24
	v_mul_f32_e32 v58, v111, v76
	v_mul_f32_e32 v100, v111, v102
	v_fma_f32 v99, v105, v102, -v58
	v_fmac_f32_e32 v100, v105, v76
	v_mul_f32_e32 v58, v114, v100
	v_mul_f32_e32 v59, v110, v100
	v_fmac_f32_e32 v58, v110, v99
	v_fma_f32 v59, v114, v99, -v59
	ds_write_b64 v91, v[58:59] offset:32
	v_mul_f32_e32 v58, v111, v100
	v_fma_f32 v76, v105, v99, -v58
	v_mul_f32_e32 v99, v111, v99
	v_fmac_f32_e32 v99, v105, v100
	v_mul_f32_e32 v58, v113, v99
	v_mul_f32_e32 v59, v112, v99
	v_fmac_f32_e32 v58, v112, v76
	v_fma_f32 v59, v113, v76, -v59
	ds_write_b64 v91, v[58:59] offset:40
	v_mul_f32_e32 v58, v111, v99
	v_fma_f32 v100, v105, v76, -v58
	v_mul_f32_e32 v76, v111, v76
	v_fmac_f32_e32 v76, v105, v99
	v_mul_f32_e32 v58, v108, v76
	v_mul_f32_e32 v59, v107, v76
	v_fmac_f32_e32 v58, v107, v100
	v_fma_f32 v59, v108, v100, -v59
	ds_write_b64 v91, v[58:59] offset:48
	v_mul_f32_e32 v58, v111, v76
	v_fma_f32 v99, v105, v100, -v58
	v_mul_f32_e32 v100, v111, v100
	v_fmac_f32_e32 v100, v105, v76
	v_mul_f32_e32 v58, v77, v100
	v_mul_f32_e32 v59, v71, v100
	v_fmac_f32_e32 v58, v71, v99
	v_fma_f32 v59, v77, v99, -v59
	ds_write_b64 v91, v[58:59] offset:56
	v_mul_f32_e32 v58, v111, v100
	v_mul_f32_e32 v76, v111, v99
	v_fma_f32 v71, v105, v99, -v58
	v_fmac_f32_e32 v76, v105, v100
	v_mul_f32_e32 v58, v109, v76
	v_mul_f32_e32 v59, v74, v76
	v_fmac_f32_e32 v58, v74, v71
	v_fma_f32 v59, v109, v71, -v59
	ds_write_b64 v91, v[58:59] offset:64
	v_mul_f32_e32 v58, v111, v76
	v_fma_f32 v74, v105, v71, -v58
	v_mul_f32_e32 v71, v111, v71
	v_fmac_f32_e32 v71, v105, v76
	v_mul_f32_e32 v58, v73, v71
	v_mul_f32_e32 v59, v72, v71
	v_fmac_f32_e32 v58, v72, v74
	v_fma_f32 v59, v73, v74, -v59
	ds_write_b64 v91, v[58:59] offset:72
	v_mul_f32_e32 v58, v111, v71
	v_mul_f32_e32 v73, v111, v74
	v_fma_f32 v72, v105, v74, -v58
	v_fmac_f32_e32 v73, v105, v71
	v_mul_f32_e32 v58, v75, v73
	v_mul_f32_e32 v59, v68, v73
	v_fmac_f32_e32 v58, v68, v72
	v_fma_f32 v59, v75, v72, -v59
	ds_write_b64 v91, v[58:59] offset:80
	v_mul_f32_e32 v58, v111, v73
	v_mul_f32_e32 v71, v111, v72
	v_fma_f32 v68, v105, v72, -v58
	v_fmac_f32_e32 v71, v105, v73
	v_mul_f32_e32 v58, v69, v71
	v_mul_f32_e32 v59, v63, v71
	v_fmac_f32_e32 v58, v63, v68
	v_fma_f32 v59, v69, v68, -v59
	ds_write_b64 v91, v[58:59] offset:88
	v_mul_f32_e32 v58, v111, v71
	v_fma_f32 v63, v105, v68, -v58
	v_mul_f32_e32 v68, v111, v68
	v_fmac_f32_e32 v68, v105, v71
	v_mul_f32_e32 v58, v65, v68
	v_mul_f32_e32 v59, v64, v68
	v_fmac_f32_e32 v58, v64, v63
	v_fma_f32 v59, v65, v63, -v59
	ds_write_b64 v91, v[58:59] offset:96
	v_mul_f32_e32 v58, v111, v68
	v_fma_f32 v64, v105, v63, -v58
	v_mul_f32_e32 v63, v111, v63
	v_fmac_f32_e32 v63, v105, v68
	v_mul_f32_e32 v58, v67, v63
	v_mul_f32_e32 v59, v70, v63
	v_fmac_f32_e32 v58, v70, v64
	v_fma_f32 v59, v67, v64, -v59
	ds_write_b64 v91, v[58:59] offset:104
	v_mul_f32_e32 v58, v111, v63
	v_fma_f32 v65, v105, v64, -v58
	v_mul_f32_e32 v64, v111, v64
	v_fmac_f32_e32 v64, v105, v63
	v_mul_f32_e32 v58, v62, v64
	v_mul_f32_e32 v59, v61, v64
	v_fmac_f32_e32 v58, v61, v65
	v_fma_f32 v59, v62, v65, -v59
	ds_write_b64 v91, v[58:59] offset:112
	v_mul_f32_e32 v58, v111, v64
	v_mul_f32_e32 v61, v111, v65
	v_fma_f32 v59, v105, v65, -v58
	v_fmac_f32_e32 v61, v105, v64
	v_mul_f32_e32 v58, v60, v61
	v_mul_f32_e32 v61, v66, v61
	v_fmac_f32_e32 v58, v66, v59
	v_fma_f32 v59, v60, v59, -v61
	ds_write_b64 v91, v[58:59] offset:120
	s_waitcnt lgkmcnt(0)
	s_barrier
	ds_read2_b64 v[58:61], v90 offset1:17
	ds_read2_b64 v[62:65], v90 offset0:34 offset1:51
	ds_read2_b64 v[66:69], v90 offset0:68 offset1:85
	ds_read2_b64 v[70:73], v90 offset0:136 offset1:153
	ds_read2_b64 v[74:77], v90 offset0:102 offset1:119
	ds_read2_b64 v[100:103], v90 offset0:170 offset1:187
	ds_read2_b64 v[104:107], v90 offset0:204 offset1:221
	ds_read2_b64 v[108:111], v90 offset0:238 offset1:255
	s_waitcnt lgkmcnt(4)
	v_add_f32_e32 v99, v58, v70
	v_add_f32_e32 v112, v59, v71
	v_sub_f32_e32 v58, v58, v70
	v_sub_f32_e32 v59, v59, v71
	s_waitcnt lgkmcnt(1)
	v_add_f32_e32 v70, v66, v104
	v_add_f32_e32 v71, v67, v105
	v_sub_f32_e32 v66, v66, v104
	v_sub_f32_e32 v67, v67, v105
	v_add_f32_e32 v104, v99, v70
	v_add_f32_e32 v105, v112, v71
	v_sub_f32_e32 v70, v99, v70
	v_sub_f32_e32 v71, v112, v71
	v_sub_f32_e32 v99, v58, v67
	v_add_f32_e32 v112, v59, v66
	v_add_f32_e32 v58, v58, v67
	v_sub_f32_e32 v59, v59, v66
	v_add_f32_e32 v66, v60, v72
	v_add_f32_e32 v67, v61, v73
	v_sub_f32_e32 v60, v60, v72
	v_sub_f32_e32 v61, v61, v73
	v_add_f32_e32 v72, v68, v106
	v_add_f32_e32 v73, v69, v107
	v_sub_f32_e32 v68, v68, v106
	v_sub_f32_e32 v69, v69, v107
	v_add_f32_e32 v106, v66, v72
	v_add_f32_e32 v107, v67, v73
	v_sub_f32_e32 v66, v66, v72
	v_sub_f32_e32 v67, v67, v73
	v_sub_f32_e32 v72, v60, v69
	v_add_f32_e32 v73, v61, v68
	v_add_f32_e32 v60, v60, v69
	v_sub_f32_e32 v61, v61, v68
	v_add_f32_e32 v68, v62, v100
	v_add_f32_e32 v69, v63, v101
	v_sub_f32_e32 v62, v62, v100
	v_sub_f32_e32 v63, v63, v101
	s_waitcnt lgkmcnt(0)
	v_add_f32_e32 v100, v74, v108
	v_add_f32_e32 v101, v75, v109
	v_sub_f32_e32 v74, v74, v108
	v_sub_f32_e32 v75, v75, v109
	v_add_f32_e32 v108, v68, v100
	v_add_f32_e32 v109, v69, v101
	v_sub_f32_e32 v68, v68, v100
	v_sub_f32_e32 v69, v69, v101
	v_sub_f32_e32 v100, v62, v75
	v_add_f32_e32 v101, v63, v74
	v_add_f32_e32 v62, v62, v75
	v_sub_f32_e32 v63, v63, v74
	v_add_f32_e32 v74, v64, v102
	v_add_f32_e32 v75, v65, v103
	v_sub_f32_e32 v64, v64, v102
	v_sub_f32_e32 v65, v65, v103
	v_add_f32_e32 v102, v76, v110
	v_add_f32_e32 v103, v77, v111
	v_sub_f32_e32 v76, v76, v110
	v_sub_f32_e32 v77, v77, v111
	v_add_f32_e32 v111, v75, v103
	v_sub_f32_e32 v75, v75, v103
	v_add_f32_e32 v103, v65, v76
	v_sub_f32_e32 v65, v65, v76
	v_mul_f32_e32 v76, 0xbec3ef15, v73
	v_fmac_f32_e32 v76, 0x3f6c835e, v72
	v_mul_f32_e32 v72, 0x3ec3ef15, v72
	v_add_f32_e32 v110, v74, v102
	v_sub_f32_e32 v74, v74, v102
	v_sub_f32_e32 v102, v64, v77
	v_fmac_f32_e32 v72, 0x3f6c835e, v73
	v_mul_f32_e32 v73, 0x3f3504f3, v100
	v_mul_f32_e32 v100, 0xbf6c835e, v103
	v_mul_f32_e32 v67, 0x3f3504f3, v67
	v_add_f32_e32 v64, v64, v77
	v_fmamk_f32 v77, v101, 0xbf3504f3, v73
	v_fmac_f32_e32 v73, 0x3f3504f3, v101
	v_fmac_f32_e32 v100, 0x3ec3ef15, v102
	v_mul_f32_e32 v101, 0x3f6c835e, v102
	v_fma_f32 v102, v66, s72, -v67
	v_fmac_f32_e32 v67, 0x3f3504f3, v66
	v_fma_f32 v66, v68, 0, -v69
	v_fmac_f32_e32 v68, 0, v69
	v_mul_f32_e32 v69, 0xbf3504f3, v75
	v_fmamk_f32 v75, v74, 0xbf3504f3, v69
	v_fmac_f32_e32 v69, 0x3f3504f3, v74
	v_mul_f32_e32 v74, 0xbf6c835e, v61
	v_fmac_f32_e32 v74, 0x3ec3ef15, v60
	v_mul_f32_e32 v60, 0x3f6c835e, v60
	v_fmac_f32_e32 v60, 0x3ec3ef15, v61
	v_mul_f32_e32 v61, 0xbf3504f3, v63
	v_fmamk_f32 v63, v62, 0xbf3504f3, v61
	v_fmac_f32_e32 v61, 0x3f3504f3, v62
	v_mul_f32_e32 v62, 0xbf6c835e, v64
	v_mul_f32_e32 v64, 0xbec3ef15, v64
	v_fmac_f32_e32 v101, 0x3ec3ef15, v103
	v_fmac_f32_e32 v62, 0x3ec3ef15, v65
	v_fmac_f32_e32 v64, 0xbf6c835e, v65
	v_add_f32_e32 v65, v104, v108
	v_add_f32_e32 v103, v105, v109
	v_sub_f32_e32 v104, v104, v108
	v_sub_f32_e32 v105, v105, v109
	v_add_f32_e32 v108, v106, v110
	v_add_f32_e32 v109, v107, v111
	v_sub_f32_e32 v106, v106, v110
	v_sub_f32_e32 v107, v107, v111
	v_add_f32_e32 v110, v108, v65
	v_add_f32_e32 v111, v109, v103
	v_sub_f32_e32 v65, v65, v108
	v_sub_f32_e32 v103, v103, v109
	v_sub_f32_e32 v108, v104, v107
	v_add_f32_e32 v109, v106, v105
	v_add_f32_e32 v104, v104, v107
	v_sub_f32_e32 v105, v105, v106
	v_add_f32_e32 v106, v99, v77
	v_add_f32_e32 v107, v112, v73
	v_sub_f32_e32 v77, v99, v77
	v_sub_f32_e32 v73, v112, v73
	v_add_f32_e32 v99, v76, v100
	v_add_f32_e32 v112, v72, v101
	v_sub_f32_e32 v76, v76, v100
	v_sub_f32_e32 v72, v72, v101
	v_add_f32_e32 v100, v99, v106
	v_add_f32_e32 v101, v112, v107
	v_sub_f32_e32 v99, v106, v99
	v_sub_f32_e32 v106, v107, v112
	v_sub_f32_e32 v107, v77, v72
	v_add_f32_e32 v112, v76, v73
	v_add_f32_e32 v72, v72, v77
	v_sub_f32_e32 v73, v73, v76
	v_add_f32_e32 v76, v70, v66
	v_add_f32_e32 v77, v71, v68
	v_sub_f32_e32 v66, v70, v66
	v_sub_f32_e32 v68, v71, v68
	v_add_f32_e32 v70, v102, v75
	v_add_f32_e32 v71, v67, v69
	v_sub_f32_e32 v75, v102, v75
	v_sub_f32_e32 v67, v67, v69
	v_add_f32_e32 v69, v76, v70
	v_add_f32_e32 v102, v71, v77
	v_sub_f32_e32 v70, v76, v70
	v_sub_f32_e32 v71, v77, v71
	v_sub_f32_e32 v76, v66, v67
	v_add_f32_e32 v77, v75, v68
	v_add_f32_e32 v66, v66, v67
	v_sub_f32_e32 v67, v68, v75
	v_add_f32_e32 v68, v58, v63
	v_add_f32_e32 v75, v59, v61
	v_sub_f32_e32 v58, v58, v63
	v_sub_f32_e32 v59, v59, v61
	v_add_f32_e32 v61, v74, v62
	v_add_f32_e32 v63, v60, v64
	v_sub_f32_e32 v62, v74, v62
	v_sub_f32_e32 v60, v60, v64
	v_add_f32_e32 v64, v61, v68
	v_add_f32_e32 v74, v63, v75
	v_sub_f32_e32 v61, v68, v61
	v_sub_f32_e32 v63, v75, v63
	v_sub_f32_e32 v68, v58, v60
	v_add_f32_e32 v75, v62, v59
	v_add_f32_e32 v60, v60, v58
	v_sub_f32_e32 v62, v59, v62
	v_mul_f32_e32 v58, v57, v111
	v_mul_f32_e32 v59, v57, v110
	v_fmac_f32_e32 v58, v56, v110
	v_fma_f32 v59, v56, v111, -v59
	v_mul_f32_e32 v110, v57, v55
	v_mul_f32_e32 v111, v56, v55
	v_fma_f32 v110, v56, v54, -v110
	v_fmac_f32_e32 v111, v57, v54
	v_mul_f32_e32 v56, v110, v100
	v_mul_f32_e32 v57, v111, v100
	v_fmac_f32_e32 v56, v111, v101
	v_fma_f32 v57, v110, v101, -v57
	ds_write2_b64 v90, v[58:59], v[56:57] offset1:17
	v_mul_f32_e32 v59, v55, v110
	v_mul_f32_e32 v56, v55, v111
	v_fmac_f32_e32 v59, v54, v111
	v_fma_f32 v58, v54, v110, -v56
	v_mul_f32_e32 v56, v59, v102
	v_fmac_f32_e32 v56, v58, v69
	v_mul_f32_e32 v57, v59, v69
	v_mul_f32_e32 v69, v55, v59
	v_mul_f32_e32 v100, v55, v58
	v_fma_f32 v69, v54, v58, -v69
	v_fmac_f32_e32 v100, v54, v59
	v_fma_f32 v57, v58, v102, -v57
	v_mul_f32_e32 v58, v69, v64
	v_mul_f32_e32 v59, v100, v64
	v_fmac_f32_e32 v58, v100, v74
	v_fma_f32 v59, v69, v74, -v59
	ds_write2_b64 v90, v[56:57], v[58:59] offset0:34 offset1:51
	v_mul_f32_e32 v56, v55, v100
	v_mul_f32_e32 v59, v55, v69
	v_fma_f32 v58, v54, v69, -v56
	v_fmac_f32_e32 v59, v54, v100
	v_mul_f32_e32 v64, v55, v59
	v_mul_f32_e32 v69, v55, v58
	v_mul_f32_e32 v56, v59, v109
	v_mul_f32_e32 v57, v59, v108
	v_fma_f32 v64, v54, v58, -v64
	v_fmac_f32_e32 v69, v54, v59
	v_fmac_f32_e32 v56, v58, v108
	v_fma_f32 v57, v58, v109, -v57
	v_mul_f32_e32 v58, v64, v107
	v_mul_f32_e32 v59, v69, v107
	v_fmac_f32_e32 v58, v69, v112
	v_fma_f32 v59, v64, v112, -v59
	ds_write2_b64 v90, v[56:57], v[58:59] offset0:68 offset1:85
	v_mul_f32_e32 v56, v55, v69
	v_mul_f32_e32 v59, v55, v64
	v_fma_f32 v58, v54, v64, -v56
	v_fmac_f32_e32 v59, v54, v69
	v_mul_f32_e32 v64, v55, v59
	v_mul_f32_e32 v69, v55, v58
	v_mul_f32_e32 v56, v59, v77
	v_mul_f32_e32 v57, v59, v76
	v_fma_f32 v64, v54, v58, -v64
	v_fmac_f32_e32 v69, v54, v59
	v_fmac_f32_e32 v56, v58, v76
	v_fma_f32 v57, v58, v77, -v57
	v_mul_f32_e32 v58, v64, v68
	v_mul_f32_e32 v59, v69, v68
	v_fmac_f32_e32 v58, v69, v75
	v_fma_f32 v59, v64, v75, -v59
	ds_write2_b64 v90, v[56:57], v[58:59] offset0:102 offset1:119
	v_mul_f32_e32 v56, v55, v69
	v_mul_f32_e32 v59, v55, v64
	v_fma_f32 v58, v54, v64, -v56
	v_fmac_f32_e32 v59, v54, v69
	v_mul_f32_e32 v56, v59, v103
	v_fmac_f32_e32 v56, v58, v65
	v_mul_f32_e32 v57, v59, v65
	v_mul_f32_e32 v64, v55, v59
	v_mul_f32_e32 v65, v55, v58
	v_fma_f32 v64, v54, v58, -v64
	v_fmac_f32_e32 v65, v54, v59
	v_fma_f32 v57, v58, v103, -v57
	v_mul_f32_e32 v58, v64, v99
	v_mul_f32_e32 v59, v65, v99
	v_fmac_f32_e32 v58, v65, v106
	v_fma_f32 v59, v64, v106, -v59
	ds_write2_b64 v90, v[56:57], v[58:59] offset0:136 offset1:153
	v_mul_f32_e32 v56, v55, v65
	v_mul_f32_e32 v59, v55, v64
	v_fma_f32 v58, v54, v64, -v56
	v_fmac_f32_e32 v59, v54, v65
	v_mul_f32_e32 v64, v55, v59
	v_mul_f32_e32 v65, v55, v58
	v_mul_f32_e32 v56, v59, v71
	v_mul_f32_e32 v57, v59, v70
	v_fma_f32 v64, v54, v58, -v64
	v_fmac_f32_e32 v65, v54, v59
	v_fmac_f32_e32 v56, v58, v70
	v_fma_f32 v57, v58, v71, -v57
	v_mul_f32_e32 v58, v64, v61
	v_mul_f32_e32 v59, v65, v61
	v_fmac_f32_e32 v58, v65, v63
	v_fma_f32 v59, v64, v63, -v59
	ds_write2_b64 v90, v[56:57], v[58:59] offset0:170 offset1:187
	v_mul_f32_e32 v56, v55, v65
	v_mul_f32_e32 v59, v55, v64
	v_fma_f32 v58, v54, v64, -v56
	v_fmac_f32_e32 v59, v54, v65
	v_mul_f32_e32 v61, v55, v59
	v_mul_f32_e32 v63, v55, v58
	v_mul_f32_e32 v56, v59, v105
	v_mul_f32_e32 v57, v59, v104
	v_fma_f32 v61, v54, v58, -v61
	v_fmac_f32_e32 v63, v54, v59
	v_fmac_f32_e32 v56, v58, v104
	v_fma_f32 v57, v58, v105, -v57
	v_mul_f32_e32 v58, v61, v72
	v_mul_f32_e32 v59, v63, v72
	v_fmac_f32_e32 v58, v63, v73
	v_fma_f32 v59, v61, v73, -v59
	ds_write2_b64 v90, v[56:57], v[58:59] offset0:204 offset1:221
	v_mul_f32_e32 v59, v55, v61
	v_mul_f32_e32 v56, v55, v63
	v_fmac_f32_e32 v59, v54, v63
	v_fma_f32 v58, v54, v61, -v56
	v_mul_f32_e32 v61, v55, v59
	v_fma_f32 v61, v54, v58, -v61
	v_mul_f32_e32 v55, v55, v58
	v_fmac_f32_e32 v55, v54, v59
	v_mul_f32_e32 v54, v61, v60
	v_mul_f32_e32 v56, v59, v67
	v_mul_f32_e32 v57, v59, v66
	v_fmac_f32_e32 v54, v55, v62
	v_mul_f32_e32 v55, v55, v60
	v_fmac_f32_e32 v56, v58, v66
	v_fma_f32 v57, v58, v67, -v57
	v_fma_f32 v55, v61, v62, -v55
	ds_write2_b64 v90, v[56:57], v[54:55] offset0:238 offset1:255
	s_waitcnt lgkmcnt(0)
	s_barrier
	ds_read_b64 v[54:55], v89
	ds_read_b64 v[56:57], v89 offset:2176
	ds_read_b64 v[58:59], v89 offset:4352
	ds_read_b64 v[60:61], v89 offset:6528
	ds_read_b64 v[62:63], v89 offset:8704
	ds_read_b64 v[64:65], v89 offset:10880
	ds_read_b64 v[66:67], v89 offset:13056
	ds_read_b64 v[68:69], v89 offset:15232
	ds_read_b64 v[70:71], v89 offset:17408
	ds_read_b64 v[72:73], v89 offset:19584
	ds_read_b64 v[74:75], v89 offset:21760
	ds_read_b64 v[76:77], v89 offset:23936
	ds_read_b64 v[100:101], v89 offset:26112
	ds_read_b64 v[102:103], v89 offset:28288
	ds_read_b64 v[104:105], v89 offset:30464
	ds_read_b64 v[106:107], v89 offset:32640
	s_waitcnt lgkmcnt(7)
	v_pk_add_f32 v[108:109], v[70:71], v[54:55]
	v_pk_add_f32 v[54:55], v[54:55], v[70:71] neg_lo:[0,1] neg_hi:[0,1]
	s_waitcnt lgkmcnt(3)
	v_pk_add_f32 v[70:71], v[100:101], v[62:63]
	v_pk_add_f32 v[62:63], v[62:63], v[100:101] neg_lo:[0,1] neg_hi:[0,1]
	v_pk_add_f32 v[110:111], v[108:109], v[70:71]
	v_pk_mov_b32 v[100:101], v[62:63], v[62:63] op_sel:[1,0]
	v_pk_add_f32 v[108:109], v[108:109], v[70:71] neg_lo:[0,1] neg_hi:[0,1]
	v_pk_add_f32 v[70:71], v[54:55], v[62:63] op_sel:[0,1] op_sel_hi:[1,0] neg_lo:[0,1] neg_hi:[0,1]
	v_pk_add_f32 v[112:113], v[54:55], v[62:63] op_sel:[0,1] op_sel_hi:[1,0]
	v_pk_add_f32 v[62:63], v[56:57], v[72:73]
	v_mov_b32_e32 v118, v58
	v_mov_b32_e32 v119, v56
	v_mov_b32_e32 v120, v74
	v_mov_b32_e32 v121, v72
	v_mov_b32_e32 v56, v59
	v_mov_b32_e32 v72, v75
	s_waitcnt lgkmcnt(2)
	v_pk_add_f32 v[114:115], v[102:103], v[64:65]
	v_pk_add_f32 v[118:119], v[118:119], v[120:121] neg_lo:[0,1] neg_hi:[0,1]
	v_mov_b32_e32 v121, v65
	v_pk_add_f32 v[56:57], v[56:57], v[72:73] neg_lo:[0,1] neg_hi:[0,1]
	v_mov_b32_e32 v72, v66
	v_mov_b32_e32 v73, v64
	s_waitcnt lgkmcnt(1)
	v_mov_b32_e32 v64, v104
	v_mov_b32_e32 v65, v102
	v_mov_b32_e32 v120, v67
	v_mov_b32_e32 v122, v105
	v_mov_b32_e32 v123, v103
	v_pk_add_f32 v[64:65], v[72:73], v[64:65] neg_lo:[0,1] neg_hi:[0,1]
	v_pk_add_f32 v[72:73], v[58:59], v[74:75]
	v_pk_add_f32 v[102:103], v[66:67], v[104:105]
	v_pk_add_f32 v[120:121], v[120:121], v[122:123] neg_lo:[0,1] neg_hi:[0,1]
	v_pk_add_f32 v[122:123], v[102:103], v[72:73]
	v_pk_add_f32 v[72:73], v[72:73], v[102:103] neg_lo:[0,1] neg_hi:[0,1]
	v_pk_mov_b32 v[102:103], v[60:61], v[58:59] op_sel:[1,0]
	v_pk_mov_b32 v[124:125], v[76:77], v[74:75] op_sel:[1,0]
	s_waitcnt lgkmcnt(0)
	v_mov_b32_e32 v126, v106
	v_pk_add_f32 v[102:103], v[102:103], v[124:125] neg_lo:[0,1] neg_hi:[0,1]
	v_mov_b32_e32 v124, v68
	v_mov_b32_e32 v125, v67
	v_mov_b32_e32 v127, v105
	v_mov_b32_e32 v58, v60
	v_mov_b32_e32 v74, v76
	v_pk_add_f32 v[128:129], v[56:57], v[64:65] neg_lo:[0,1] neg_hi:[0,1]
	v_add_f32_e32 v56, v57, v65
	v_pk_add_f32 v[124:125], v[124:125], v[126:127] neg_lo:[0,1] neg_hi:[0,1]
	v_pk_add_f32 v[58:59], v[58:59], v[74:75] neg_lo:[0,1] neg_hi:[0,1]
	v_pk_mov_b32 v[66:67], v[68:69], v[66:67] op_sel:[1,0]
	v_pk_mov_b32 v[74:75], v[106:107], v[104:105] op_sel:[1,0]
	v_pk_add_f32 v[104:105], v[118:119], v[120:121]
	v_pk_add_f32 v[60:61], v[60:61], v[76:77]
	v_pk_add_f32 v[68:69], v[68:69], v[106:107]
	v_sub_f32_e32 v54, v119, v121
	v_pk_mul_f32 v[56:57], v[56:57], s[80:81] op_sel_hi:[0,1]
	v_pk_add_f32 v[116:117], v[62:63], v[114:115]
	v_pk_add_f32 v[66:67], v[66:67], v[74:75] neg_lo:[0,1] neg_hi:[0,1]
	v_pk_add_f32 v[76:77], v[60:61], v[68:69]
	v_mov_b32_e32 v106, v62
	v_mov_b32_e32 v107, v60
	v_mov_b32_e32 v131, v68
	v_mov_b32_e32 v60, v63
	v_mov_b32_e32 v68, v115
	v_pk_add_f32 v[62:63], v[102:103], v[124:125]
	v_pk_fma_f32 v[64:65], v[54:55], s[70:71], v[56:57] op_sel_hi:[0,1,1] neg_lo:[0,0,1] neg_hi:[0,0,1]
	v_pk_fma_f32 v[56:57], v[54:55], s[70:71], v[56:57] op_sel_hi:[0,1,1]
	v_mul_f32_e32 v54, 0x3ec3ef15, v105
	v_mul_f32_e32 v100, 0x3f6c835e, v129
	v_pk_add_f32 v[74:75], v[66:67], v[58:59]
	v_pk_add_f32 v[60:61], v[60:61], v[68:69] neg_lo:[0,1] neg_hi:[0,1]
	v_pk_add_f32 v[58:59], v[58:59], v[66:67] neg_lo:[0,1] neg_hi:[0,1]
	v_mov_b32_e32 v69, v63
	v_pk_add_f32 v[54:55], v[54:55], v[100:101] neg_lo:[0,1] neg_hi:[0,1]
	v_pk_fma_f32 v[100:101], v[72:73], 0, v[72:73] op_sel:[0,0,1] op_sel_hi:[1,0,0] neg_lo:[0,0,1] neg_hi:[0,0,1]
	v_pk_fma_f32 v[72:73], v[72:73], 0, v[72:73] op_sel:[0,0,1] op_sel_hi:[1,0,0]
	s_mov_b32 s73, s71
	v_pk_mul_f32 v[62:63], v[62:63], s[70:71] op_sel_hi:[0,1]
	v_mov_b32_e32 v130, v114
	v_mov_b32_e32 v67, v59
	v_mov_b32_e32 v101, v73
	v_pk_mul_f32 v[72:73], v[128:129], s[72:73]
	v_readlane_b32 s10, v254, 9
	v_pk_fma_f32 v[114:115], v[58:59], s[80:81], v[62:63] neg_lo:[0,0,1] neg_hi:[0,0,1]
	v_pk_fma_f32 v[58:59], v[58:59], s[80:81], v[62:63] op_sel_hi:[0,1,1]
	s_mov_b32 s73, s74
	v_pk_add_f32 v[126:127], v[102:103], v[124:125] neg_lo:[0,1] neg_hi:[0,1]
	v_pk_add_f32 v[106:107], v[106:107], v[130:131] neg_lo:[0,1] neg_hi:[0,1]
	v_mov_b32_e32 v66, v74
	v_readlane_b32 s11, v254, 10
	v_mov_b32_e32 v115, v59
	v_pk_mul_f32 v[58:59], v[60:61], s[72:73] op_sel_hi:[1,0]
	v_mov_b32_e32 v68, v126
	v_mov_b32_e32 v65, v57
	v_mul_f32_e32 v56, 0x3f3504f3, v127
	v_mul_f32_e32 v57, 0x3f3504f3, v75
	s_mov_b32 s75, s70
	v_pk_mul_f32 v[66:67], v[66:67], s[10:11]
	v_pk_fma_f32 v[60:61], v[106:107], s[72:73], v[58:59] neg_lo:[0,0,1] neg_hi:[0,0,1]
	v_pk_fma_f32 v[62:63], v[106:107], s[72:73], v[58:59]
	v_mov_b32_e32 v71, v113
	v_sub_f32_e32 v56, v56, v57
	v_fmac_f32_e32 v57, 0x3f3504f3, v127
	v_pk_fma_f32 v[102:103], v[104:105], s[74:75], v[72:73] neg_lo:[0,0,1] neg_hi:[0,0,1]
	v_pk_fma_f32 v[104:105], v[104:105], s[74:75], v[72:73]
	v_pk_mov_b32 v[118:119], v[60:61], v[62:63] op_sel:[1,0]
	v_pk_fma_f32 v[58:59], v[106:107], s[72:73], v[58:59] op_sel_hi:[1,0,1] neg_lo:[0,0,1] neg_hi:[0,0,1]
	v_pk_fma_f32 v[106:107], v[68:69], s[82:83], v[66:67]
	v_mov_b32_e32 v127, v74
	v_mul_f32_e32 v60, 0x3ec3ef15, v74
	v_pk_add_f32 v[66:67], v[110:111], v[122:123]
	v_pk_add_f32 v[68:69], v[110:111], v[122:123] neg_lo:[0,1] neg_hi:[0,1]
	v_pk_add_f32 v[72:73], v[116:117], v[76:77]
	v_pk_add_f32 v[74:75], v[116:117], v[76:77] neg_lo:[0,1] neg_hi:[0,1]
	v_pk_add_f32 v[110:111], v[66:67], v[72:73]
	v_pk_add_f32 v[116:117], v[66:67], v[72:73] neg_lo:[0,1] neg_hi:[0,1]
	v_pk_add_f32 v[76:77], v[68:69], v[74:75] op_sel:[0,1] op_sel_hi:[1,0] neg_lo:[0,1] neg_hi:[0,1]
	v_pk_add_f32 v[72:73], v[68:69], v[74:75] op_sel:[0,1] op_sel_hi:[1,0]
	v_pk_add_f32 v[66:67], v[70:71], v[56:57]
	v_pk_add_f32 v[56:57], v[70:71], v[56:57] neg_lo:[0,1] neg_hi:[0,1]
	v_pk_add_f32 v[68:69], v[64:65], v[114:115]
	v_pk_add_f32 v[64:65], v[64:65], v[114:115] neg_lo:[0,1] neg_hi:[0,1]
	v_pk_add_f32 v[114:115], v[66:67], v[68:69]
	v_pk_add_f32 v[122:123], v[66:67], v[68:69] neg_lo:[0,1] neg_hi:[0,1]
	v_pk_add_f32 v[70:71], v[56:57], v[64:65] op_sel:[0,1] op_sel_hi:[1,0] neg_lo:[0,1] neg_hi:[0,1]
	v_pk_add_f32 v[66:67], v[56:57], v[64:65] op_sel:[0,1] op_sel_hi:[1,0]
	v_pk_add_f32 v[56:57], v[108:109], v[100:101]
	v_pk_add_f32 v[64:65], v[58:59], v[118:119]
	v_pk_fma_f32 v[120:121], v[126:127], s[78:79], v[60:61] op_sel_hi:[1,1,0] neg_lo:[0,0,1] neg_hi:[0,0,1]
	v_pk_add_f32 v[100:101], v[108:109], v[100:101] neg_lo:[0,1] neg_hi:[0,1]
	v_mov_b32_e32 v63, v58
	v_mov_b32_e32 v60, v59
	v_pk_add_f32 v[108:109], v[56:57], v[64:65]
	v_pk_add_f32 v[118:119], v[56:57], v[64:65] neg_lo:[0,1] neg_hi:[0,1]
	v_mov_b32_e32 v113, v55
	v_mov_b32_e32 v56, v102
	v_mov_b32_e32 v57, v107
	v_mov_b32_e32 v103, v105
	v_pk_add_f32 v[58:59], v[62:63], v[60:61] neg_lo:[0,1] neg_hi:[0,1]
	v_pk_add_f32 v[56:57], v[112:113], v[56:57] neg_lo:[0,1] neg_hi:[0,1]
	v_mov_b32_e32 v113, v120
	v_pk_add_f32 v[64:65], v[100:101], v[58:59] neg_lo:[0,1] neg_hi:[0,1]
	v_pk_add_f32 v[60:61], v[100:101], v[58:59]
	v_pk_add_f32 v[58:59], v[54:55], v[106:107]
	v_pk_add_f32 v[100:101], v[102:103], v[112:113]
	v_pk_mov_b32 v[54:55], v[104:105], v[54:55] op_sel:[1,0]
	v_mov_b32_e32 v121, v106
	v_pk_add_f32 v[54:55], v[54:55], v[120:121] neg_lo:[0,1] neg_hi:[0,1]
	v_pk_add_f32 v[104:105], v[58:59], v[100:101]
	v_mov_b32_e32 v102, v100
	v_mov_b32_e32 v103, v59
	v_mov_b32_e32 v59, v101
	v_mov_b32_e32 v112, v86
	v_mov_b32_e32 v120, v87
	v_pk_add_f32 v[106:107], v[102:103], v[58:59] neg_lo:[0,1] neg_hi:[0,1]
	s_barrier
	ds_read2st64_b64 v[100:103], v88 offset0:68 offset1:72
	v_pk_mul_f32 v[124:125], v[110:111], v[120:121] op_sel:[1,0] op_sel_hi:[0,0]
	v_pk_fma_f32 v[126:127], v[110:111], v[112:113], v[124:125]
	v_pk_fma_f32 v[110:111], v[110:111], v[112:113], v[124:125] op_sel_hi:[1,0,1] neg_lo:[0,0,1] neg_hi:[0,0,1]
	v_mov_b32_e32 v121, v112
	v_mov_b32_e32 v127, v111
	s_waitcnt lgkmcnt(0)
	v_pk_add_f32 v[100:101], v[100:101], v[126:127]
	v_mul_f32_e32 v110, 0x3e47c5c2, v112
	v_pk_mul_f32 v[100:101], v[100:101], s[68:69] op_sel_hi:[1,0]
	v_mov_b32_e32 v113, v120
	v_pk_fma_f32 v[50:51], v[14:15], v[50:51], v[100:101]
	v_mul_f32_e32 v100, 0x3e47c5c2, v120
	v_pk_fma_f32 v[110:111], v[120:121], s[76:77], v[110:111] op_sel_hi:[1,1,0] neg_lo:[0,0,1] neg_hi:[0,0,1]
	v_pk_fma_f32 v[100:101], v[112:113], s[76:77], v[100:101] op_sel_hi:[1,1,0]
	v_pk_mul_f32 v[112:113], v[114:115], v[110:111] op_sel:[1,0] op_sel_hi:[0,0]
	v_pk_fma_f32 v[120:121], v[114:115], v[100:101], v[112:113]
	v_pk_fma_f32 v[112:113], v[114:115], v[100:101], v[112:113] op_sel_hi:[1,0,1] neg_lo:[0,0,1] neg_hi:[0,0,1]
	v_mov_b32_e32 v101, v110
	v_mov_b32_e32 v121, v113
	v_pk_add_f32 v[102:103], v[120:121], v[102:103]
	v_mov_b32_e32 v111, v100
	v_pk_mul_f32 v[102:103], v[102:103], s[68:69] op_sel_hi:[1,0]
	v_pk_add_f32 v[58:59], v[56:57], v[54:55] neg_lo:[0,1] neg_hi:[0,1]
	v_pk_fma_f32 v[48:49], v[14:15], v[48:49], v[102:103]
	ds_write2st64_b64 v88, v[50:51], v[48:49] offset0:68 offset1:72
	v_mul_f32_e32 v48, 0x3e47c5c2, v110
	v_pk_fma_f32 v[102:103], v[100:101], s[76:77], v[48:49] op_sel_hi:[1,1,0]
	v_mul_f32_e32 v48, 0x3e47c5c2, v100
	v_pk_fma_f32 v[100:101], v[110:111], s[76:77], v[48:49] op_sel_hi:[1,1,0] neg_lo:[0,0,1] neg_hi:[0,0,1]
	ds_read2st64_b64 v[48:51], v88 offset0:76 offset1:80
	v_pk_mul_f32 v[110:111], v[108:109], v[100:101] op_sel:[1,0] op_sel_hi:[0,0]
	v_pk_fma_f32 v[112:113], v[108:109], v[102:103], v[110:111]
	v_pk_fma_f32 v[108:109], v[108:109], v[102:103], v[110:111] op_sel_hi:[1,0,1] neg_lo:[0,0,1] neg_hi:[0,0,1]
	v_mov_b32_e32 v101, v102
	v_mov_b32_e32 v113, v109
	s_waitcnt lgkmcnt(0)
	v_pk_add_f32 v[48:49], v[112:113], v[48:49]
	v_mov_b32_e32 v103, v100
	v_pk_mul_f32 v[48:49], v[48:49], s[68:69] op_sel_hi:[1,0]
	v_pk_mul_f32 v[100:101], v[100:101], s[76:77]
	v_pk_fma_f32 v[46:47], v[14:15], v[46:47], v[48:49]
	v_pk_mul_f32 v[48:49], v[102:103], s[76:77]
	v_pk_add_f32 v[100:101], v[100:101], v[100:101] op_sel:[0,1] op_sel_hi:[0,1] neg_lo:[0,1] neg_hi:[0,1]
	v_pk_add_f32 v[48:49], v[48:49], v[48:49] op_sel:[0,1] op_sel_hi:[0,1]
	v_pk_mul_f32 v[102:103], v[104:105], v[100:101]
	v_pk_add_f32 v[54:55], v[56:57], v[54:55]
	v_pk_fma_f32 v[108:109], v[104:105], v[48:49], v[102:103] op_sel:[0,0,1] op_sel_hi:[1,1,0]
	v_pk_fma_f32 v[102:103], v[104:105], v[48:49], v[102:103] op_sel:[0,0,1] op_sel_hi:[1,1,0] neg_lo:[0,0,1] neg_hi:[0,0,1]
	v_mov_b32_e32 v74, v72
	v_mov_b32_e32 v109, v103
	v_pk_add_f32 v[50:51], v[108:109], v[50:51]
	v_mov_b32_e32 v75, v77
	v_pk_mul_f32 v[50:51], v[50:51], s[68:69] op_sel_hi:[1,0]
	v_mov_b32_e32 v68, v66
	v_pk_fma_f32 v[44:45], v[14:15], v[44:45], v[50:51]
	ds_write2st64_b64 v88, v[46:47], v[44:45] offset0:76 offset1:80
	v_pk_mul_f32 v[44:45], v[48:49], s[86:87]
	v_mov_b32_e32 v69, v71
	v_pk_fma_f32 v[48:49], v[100:101], s[76:77], v[44:45] neg_lo:[0,0,1] neg_hi:[0,0,1]
	v_pk_fma_f32 v[44:45], v[100:101], s[76:77], v[44:45]
	v_mov_b32_e32 v50, v48
	v_mov_b32_e32 v51, v45
	v_pk_mov_b32 v[100:101], v[44:45], v[48:49] op_sel:[1,0]
	ds_read2st64_b64 v[44:47], v88 offset0:84 offset1:88
	v_pk_mul_f32 v[100:101], v[76:77], v[100:101] op_sel_hi:[0,1]
	v_pk_fma_f32 v[48:49], v[72:73], v[48:49], v[100:101] op_sel:[1,0,0]
	v_pk_fma_f32 v[100:101], v[72:73], v[50:51], v[100:101] op_sel:[1,0,0] neg_lo:[0,0,1] neg_hi:[0,0,1]
	v_mov_b32_e32 v62, v60
	v_mov_b32_e32 v49, v101
	s_waitcnt lgkmcnt(0)
	v_pk_add_f32 v[44:45], v[48:49], v[44:45]
	v_mov_b32_e32 v63, v65
	v_pk_mul_f32 v[44:45], v[44:45], s[68:69] op_sel_hi:[1,0]
	v_mov_b32_e32 v56, v54
	v_pk_fma_f32 v[40:41], v[14:15], v[40:41], v[44:45]
	v_pk_mul_f32 v[44:45], v[50:51], s[4:5] op_sel_hi:[1,0]
	v_mov_b32_e32 v57, v59
	v_pk_fma_f32 v[48:49], v[50:51], s[76:77], v[44:45] op_sel:[0,0,1] op_sel_hi:[1,0,0] neg_lo:[0,0,1] neg_hi:[0,0,1]
	v_pk_fma_f32 v[44:45], v[50:51], s[76:77], v[44:45] op_sel:[0,0,1] op_sel_hi:[1,0,0]
	v_mov_b32_e32 v50, v48
	v_mov_b32_e32 v51, v45
	v_pk_mov_b32 v[44:45], v[44:45], v[48:49] op_sel:[1,0]
	s_add_u32 s10, s3, s88
	v_pk_mul_f32 v[44:45], v[70:71], v[44:45] op_sel_hi:[0,1]
	v_pk_fma_f32 v[48:49], v[66:67], v[48:49], v[44:45] op_sel:[1,0,0]
	v_pk_fma_f32 v[44:45], v[66:67], v[50:51], v[44:45] op_sel:[1,0,0] neg_lo:[0,0,1] neg_hi:[0,0,1]
	s_addc_u32 s11, 0, s0
	v_mov_b32_e32 v49, v45
	v_pk_add_f32 v[44:45], v[48:49], v[46:47]
	s_lshl_b64 s[10:11], s[10:11], 13
	v_pk_mul_f32 v[44:45], v[44:45], s[68:69] op_sel_hi:[1,0]
	s_add_u32 s10, s24, s10
	v_pk_fma_f32 v[38:39], v[14:15], v[38:39], v[44:45]
	ds_write2st64_b64 v88, v[40:41], v[38:39] offset0:84 offset1:88
	v_pk_mul_f32 v[38:39], v[50:51], s[4:5] op_sel_hi:[1,0]
	s_addc_u32 s11, s25, s11
	v_pk_fma_f32 v[44:45], v[50:51], s[76:77], v[38:39] op_sel:[0,0,1] op_sel_hi:[1,0,0] neg_lo:[0,0,1] neg_hi:[0,0,1]
	v_pk_fma_f32 v[38:39], v[50:51], s[76:77], v[38:39] op_sel:[0,0,1] op_sel_hi:[1,0,0]
	v_mov_b32_e32 v46, v44
	v_mov_b32_e32 v47, v39
	v_pk_mov_b32 v[48:49], v[38:39], v[44:45] op_sel:[1,0]
	ds_read2st64_b64 v[38:41], v88 offset0:92 offset1:96
	v_pk_mul_f32 v[48:49], v[64:65], v[48:49] op_sel_hi:[0,1]
	v_pk_fma_f32 v[44:45], v[60:61], v[44:45], v[48:49] op_sel:[1,0,0]
	v_pk_fma_f32 v[48:49], v[60:61], v[46:47], v[48:49] op_sel:[1,0,0] neg_lo:[0,0,1] neg_hi:[0,0,1]
	s_mov_b32 s73, 1
	v_mov_b32_e32 v45, v49
	s_waitcnt lgkmcnt(0)
	v_pk_add_f32 v[38:39], v[44:45], v[38:39]
	s_mov_b32 s75, 16
	v_pk_mul_f32 v[38:39], v[38:39], s[68:69] op_sel_hi:[1,0]
	s_nop 0
	v_pk_fma_f32 v[36:37], v[14:15], v[36:37], v[38:39]
	v_pk_mul_f32 v[38:39], v[46:47], s[4:5] op_sel_hi:[1,0]
	s_nop 0
	v_pk_fma_f32 v[44:45], v[46:47], s[76:77], v[38:39] op_sel:[0,0,1] op_sel_hi:[1,0,0] neg_lo:[0,0,1] neg_hi:[0,0,1]
	v_pk_fma_f32 v[38:39], v[46:47], s[76:77], v[38:39] op_sel:[0,0,1] op_sel_hi:[1,0,0]
	v_mov_b32_e32 v46, v44
	v_pk_mov_b32 v[48:49], v[38:39], v[44:45] op_sel:[1,0]
	v_mov_b32_e32 v47, v39
	v_pk_mul_f32 v[48:49], v[58:59], v[48:49] op_sel_hi:[0,1]
	v_pk_fma_f32 v[44:45], v[54:55], v[44:45], v[48:49] op_sel:[1,0,0]
	v_pk_fma_f32 v[48:49], v[54:55], v[46:47], v[48:49] op_sel:[1,0,0] neg_lo:[0,0,1] neg_hi:[0,0,1]
	s_nop 0
	v_mov_b32_e32 v45, v49
	v_pk_add_f32 v[40:41], v[44:45], v[40:41]
	s_nop 0
	v_pk_mul_f32 v[40:41], v[40:41], s[68:69] op_sel_hi:[1,0]
	s_nop 0
	v_pk_fma_f32 v[30:31], v[14:15], v[30:31], v[40:41]
	ds_write2st64_b64 v88, v[36:37], v[30:31] offset0:92 offset1:96
	v_mul_f32_e32 v36, 0x3e47c5c2, v39
	v_mul_f32_e32 v30, 0x3f7b14be, v39
	v_pk_fma_f32 v[40:41], v[46:47], s[76:77], v[36:37] op_sel_hi:[1,1,0] neg_lo:[0,0,1] neg_hi:[0,0,1]
	ds_read2st64_b64 v[36:39], v88 offset0:100 offset1:104
	v_pk_fma_f32 v[30:31], v[46:47], s[86:87], v[30:31] op_sel_hi:[1,1,0]
	v_pk_mul_f32 v[44:45], v[116:117], v[40:41] op_sel:[1,0] op_sel_hi:[0,0]
	v_pk_fma_f32 v[46:47], v[116:117], v[30:31], v[44:45]
	v_pk_fma_f32 v[44:45], v[116:117], v[30:31], v[44:45] op_sel_hi:[1,0,1] neg_lo:[0,0,1] neg_hi:[0,0,1]
	v_mov_b32_e32 v31, v40
	v_mov_b32_e32 v47, v45
	s_waitcnt lgkmcnt(0)
	v_pk_add_f32 v[36:37], v[46:47], v[36:37]
	v_mov_b32_e32 v41, v30
	v_pk_mul_f32 v[36:37], v[36:37], s[68:69] op_sel_hi:[1,0]
	s_nop 0
	v_pk_fma_f32 v[28:29], v[14:15], v[28:29], v[36:37]
	v_mul_f32_e32 v36, 0x3e47c5c2, v40
	v_pk_fma_f32 v[36:37], v[30:31], s[76:77], v[36:37] op_sel_hi:[1,1,0]
	v_mul_f32_e32 v30, 0x3e47c5c2, v30
	v_pk_fma_f32 v[30:31], v[40:41], s[76:77], v[30:31] op_sel_hi:[1,1,0] neg_lo:[0,0,1] neg_hi:[0,0,1]
	s_nop 0
	v_pk_mul_f32 v[40:41], v[122:123], v[30:31] op_sel:[1,0] op_sel_hi:[0,0]
	v_pk_fma_f32 v[44:45], v[122:123], v[36:37], v[40:41]
	v_pk_fma_f32 v[40:41], v[122:123], v[36:37], v[40:41] op_sel_hi:[1,0,1] neg_lo:[0,0,1] neg_hi:[0,0,1]
	v_mov_b32_e32 v37, v30
	v_mov_b32_e32 v45, v41
	v_pk_add_f32 v[38:39], v[44:45], v[38:39]
	v_mov_b32_e32 v31, v36
	v_pk_mul_f32 v[38:39], v[38:39], s[68:69] op_sel_hi:[1,0]
	s_nop 0
	v_pk_fma_f32 v[32:33], v[14:15], v[32:33], v[38:39]
	ds_write2st64_b64 v88, v[28:29], v[32:33] offset0:100 offset1:104
	v_mul_f32_e32 v28, 0x3e47c5c2, v30
	v_pk_fma_f32 v[32:33], v[36:37], s[76:77], v[28:29] op_sel_hi:[1,1,0]
	v_mul_f32_e32 v28, 0x3e47c5c2, v36
	v_pk_fma_f32 v[36:37], v[30:31], s[76:77], v[28:29] op_sel_hi:[1,1,0] neg_lo:[0,0,1] neg_hi:[0,0,1]
	ds_read2st64_b64 v[28:31], v88 offset0:108 offset1:112
	v_pk_mul_f32 v[38:39], v[118:119], v[36:37] op_sel:[1,0] op_sel_hi:[0,0]
	v_pk_fma_f32 v[40:41], v[118:119], v[32:33], v[38:39]
	v_pk_fma_f32 v[38:39], v[118:119], v[32:33], v[38:39] op_sel_hi:[1,0,1] neg_lo:[0,0,1] neg_hi:[0,0,1]
	v_mov_b32_e32 v33, v36
	v_mov_b32_e32 v41, v39
	s_waitcnt lgkmcnt(0)
	v_pk_add_f32 v[28:29], v[40:41], v[28:29]
	v_mov_b32_e32 v37, v32
	v_pk_mul_f32 v[28:29], v[28:29], s[68:69] op_sel_hi:[1,0]
	s_nop 0
	v_pk_fma_f32 v[26:27], v[14:15], v[26:27], v[28:29]
	v_mul_f32_e32 v28, 0x3e47c5c2, v36
	v_pk_fma_f32 v[28:29], v[32:33], s[76:77], v[28:29] op_sel_hi:[1,1,0]
	v_mul_f32_e32 v32, 0x3e47c5c2, v32
	v_pk_fma_f32 v[32:33], v[36:37], s[76:77], v[32:33] op_sel_hi:[1,1,0] neg_lo:[0,0,1] neg_hi:[0,0,1]
	s_nop 0
	v_pk_mul_f32 v[36:37], v[106:107], v[32:33] op_sel:[1,0] op_sel_hi:[0,0]
	v_pk_fma_f32 v[38:39], v[106:107], v[28:29], v[36:37]
	v_pk_fma_f32 v[36:37], v[106:107], v[28:29], v[36:37] op_sel_hi:[1,0,1] neg_lo:[0,0,1] neg_hi:[0,0,1]
	v_mov_b32_e32 v29, v32
	v_mov_b32_e32 v39, v37
	v_pk_add_f32 v[30:31], v[38:39], v[30:31]
	v_mov_b32_e32 v33, v28
	v_pk_mul_f32 v[30:31], v[30:31], s[68:69] op_sel_hi:[1,0]
	v_mov_b32_e32 v38, v0
	v_pk_fma_f32 v[22:23], v[14:15], v[22:23], v[30:31]
	ds_write2st64_b64 v88, v[26:27], v[22:23] offset0:108 offset1:112
	v_mul_f32_e32 v22, 0x3e47c5c2, v32
	v_mul_f32_e32 v26, 0x3e47c5c2, v28
	v_pk_fma_f32 v[22:23], v[28:29], s[76:77], v[22:23] op_sel_hi:[1,1,0]
	v_pk_fma_f32 v[30:31], v[32:33], s[76:77], v[26:27] op_sel_hi:[1,1,0] neg_lo:[0,0,1] neg_hi:[0,0,1]
	ds_read2st64_b64 v[26:29], v88 offset0:116 offset1:120
	v_pk_mov_b32 v[32:33], v[76:77], v[72:73] op_sel:[1,0]
	s_nop 0
	v_pk_mul_f32 v[32:33], v[32:33], v[30:31] op_sel_hi:[1,0]
	v_mov_b32_e32 v31, v22
	v_pk_fma_f32 v[36:37], v[72:73], v[22:23], v[32:33]
	v_pk_fma_f32 v[32:33], v[74:75], v[22:23], v[32:33] op_sel_hi:[1,0,1] neg_lo:[0,0,1] neg_hi:[0,0,1]
	v_mov_b32_e32 v23, v30
	v_mov_b32_e32 v37, v33
	s_waitcnt lgkmcnt(0)
	v_pk_add_f32 v[26:27], v[36:37], v[26:27]
	s_nop 0
	v_pk_mul_f32 v[26:27], v[26:27], s[68:69] op_sel_hi:[1,0]
	s_nop 0
	v_pk_fma_f32 v[24:25], v[14:15], v[24:25], v[26:27]
	v_mul_f32_e32 v26, 0x3e47c5c2, v30
	v_pk_fma_f32 v[26:27], v[22:23], s[76:77], v[26:27] op_sel_hi:[1,1,0]
	v_mul_f32_e32 v22, 0x3e47c5c2, v22
	v_pk_fma_f32 v[22:23], v[30:31], s[76:77], v[22:23] op_sel_hi:[1,1,0] neg_lo:[0,0,1] neg_hi:[0,0,1]
	v_pk_mov_b32 v[30:31], v[70:71], v[66:67] op_sel:[1,0]
	s_nop 0
	v_pk_mul_f32 v[30:31], v[30:31], v[22:23] op_sel_hi:[1,0]
	v_mov_b32_e32 v23, v26
	v_pk_fma_f32 v[32:33], v[66:67], v[26:27], v[30:31]
	v_pk_fma_f32 v[30:31], v[68:69], v[26:27], v[30:31] op_sel_hi:[1,0,1] neg_lo:[0,0,1] neg_hi:[0,0,1]
	v_mov_b32_e32 v27, v22
	v_mov_b32_e32 v33, v31
	v_pk_add_f32 v[28:29], v[32:33], v[28:29]
	s_nop 0
	v_pk_mul_f32 v[28:29], v[28:29], s[68:69] op_sel_hi:[1,0]
	s_nop 0
	v_pk_fma_f32 v[28:29], v[14:15], v[34:35], v[28:29]
	ds_write2st64_b64 v88, v[24:25], v[28:29] offset0:116 offset1:120
	v_mul_f32_e32 v24, 0x3e47c5c2, v22
	v_pk_fma_f32 v[24:25], v[26:27], s[76:77], v[24:25] op_sel_hi:[1,1,0]
	v_mul_f32_e32 v26, 0x3e47c5c2, v26
	ds_read_b64 v[28:29], v88 offset:63488
	v_pk_fma_f32 v[22:23], v[22:23], s[76:77], v[26:27] op_sel_hi:[1,1,0] neg_lo:[0,0,1] neg_hi:[0,0,1]
	v_pk_mov_b32 v[26:27], v[64:65], v[60:61] op_sel:[1,0]
	s_nop 0
	v_pk_mul_f32 v[26:27], v[26:27], v[22:23] op_sel_hi:[1,0]
	v_mov_b32_e32 v23, v24
	v_pk_fma_f32 v[30:31], v[60:61], v[24:25], v[26:27]
	v_pk_fma_f32 v[26:27], v[62:63], v[24:25], v[26:27] op_sel_hi:[1,0,1] neg_lo:[0,0,1] neg_hi:[0,0,1]
	v_mov_b32_e32 v25, v22
	v_mov_b32_e32 v31, v27
	ds_read_b64 v[26:27], v98 offset:30720
	s_waitcnt lgkmcnt(1)
	v_pk_add_f32 v[28:29], v[30:31], v[28:29]
	v_pk_mul_f32 v[22:23], v[22:23], s[76:77]
	v_pk_mul_f32 v[28:29], v[28:29], s[68:69] op_sel_hi:[1,0]
	v_pk_add_f32 v[22:23], v[22:23], v[22:23] op_sel:[0,1] op_sel_hi:[0,1] neg_lo:[0,1] neg_hi:[0,1]
	v_pk_fma_f32 v[28:29], v[14:15], v[42:43], v[28:29]
	ds_write_b64 v88, v[28:29] offset:63488
	v_pk_mul_f32 v[28:29], v[24:25], s[76:77]
	s_nop 0
	v_pk_add_f32 v[24:25], v[28:29], v[28:29] op_sel:[0,1] op_sel_hi:[0,1]
	v_pk_mov_b32 v[28:29], v[58:59], v[54:55] op_sel:[1,0]
	s_nop 0
	v_pk_mul_f32 v[22:23], v[28:29], v[22:23]
	s_nop 0
	v_pk_fma_f32 v[28:29], v[54:55], v[24:25], v[22:23]
	v_pk_fma_f32 v[22:23], v[56:57], v[24:25], v[22:23] neg_lo:[0,0,1] neg_hi:[0,0,1]
	s_nop 0
	v_mov_b32_e32 v29, v23
	s_waitcnt lgkmcnt(1)
	v_pk_add_f32 v[22:23], v[28:29], v[26:27]
	s_nop 0
	v_pk_mul_f32 v[22:23], v[22:23], s[68:69] op_sel_hi:[1,0]
	s_nop 0
	v_pk_fma_f32 v[22:23], v[14:15], v[52:53], v[22:23]
	ds_write_b64 v98, v[22:23] offset:30720
	s_nop 0
	v_lshlrev_b32_e32 v22, 3, v38
	v_ashrrev_i32_e32 v23, 31, v22
	v_lshlrev_b64 v[30:31], 1, v[22:23]
	v_add_u32_e32 v22, 0x800, v22
	v_ashrrev_i32_e32 v23, 31, v22
	v_lshlrev_b64 v[32:33], 1, v[22:23]
	v_lshl_add_u64 v[24:25], s[10:11], 0, v[30:31]
	v_lshl_add_u64 v[26:27], s[10:11], 0, v[32:33]
	s_add_u32 s10, s43, s88
	s_addc_u32 s11, 0, s0
	s_lshl_b64 s[10:11], s[10:11], 13
	s_add_u32 s10, s24, s10
	s_addc_u32 s11, s25, s11
	v_lshl_add_u64 v[30:31], s[10:11], 0, v[30:31]
	v_lshl_add_u64 v[34:35], s[10:11], 0, v[32:33]
	global_load_dwordx4 v[22:25], v[24:25], off
	s_nop 0
	global_load_dwordx4 v[26:29], v[26:27], off
	s_nop 0
	global_load_dwordx4 v[30:33], v[30:31], off
	s_nop 0
	global_load_dwordx4 v[34:37], v[34:35], off
	s_lshl_b32 s3, s42, 11
	s_add_u32 s10, s3, s88
	s_addc_u32 s11, 0, s0
	s_lshl_b64 s[10:11], s[10:11], 13
	s_add_u32 s42, s46, s10
	s_addc_u32 s43, s47, s11
	s_lshl_b32 s2, s2, 10
	s_add_u32 s2, s2, s88
	s_addc_u32 s3, 0, s0
	s_lshl_b64 s[2:3], s[2:3], 13
	s_add_u32 s2, s46, s2
	v_lshl_add_u32 v38, v38, 4, s33
	s_addc_u32 s3, s47, s3
	s_waitcnt vmcnt(3)
	ds_write_b128 v38, v[22:25]
	s_waitcnt vmcnt(2)
	ds_write_b128 v38, v[26:29] offset:4096
	s_waitcnt vmcnt(1)
	ds_write_b128 v38, v[30:33] offset:8192
	s_waitcnt vmcnt(0)
	ds_write_b128 v38, v[34:37] offset:12288
	s_waitcnt lgkmcnt(0)
	s_barrier
